# indexer key tiles staged by LDS-DMA into per-wave 4-slot LDS ring, 3 tiles lookahead, fragments read from LDS directly into MFMA B regs (no bn copies)
# speedup vs baseline: 1.0190x; 1.0133x over previous
.LBB0_399:
	v_cndmask_b32_e64 v2, v159, v92, s[82:83]
	v_readlane_b32 s74, v252, 26
	v_lshlrev_b32_e32 v88, 1, v2
	v_readlane_b32 s75, v252, 27
	v_or_b32_e32 v2, v88, v95
	s_movk_i32 s80, 0x3400
	v_mov_b64_e32 v[42:43], s[74:75]
	v_readfirstlane_b32 s100, v198
	s_nop 0
	s_lshr_b32 s100, s100, 6
	s_lshl_b32 s100, s100, 14
	v_lshrrev_b32_e32 v75, 1, v93
	v_and_b32_e32 v75, 7, v75
	v_xor_b32_e32 v75, v75, v94
	v_lshlrev_b32_e32 v75, 4, v75
	v_lshl_add_u32 v75, v93, 7, v75
	v_add_u32_e32 v74, s100, v75
	v_xor_b32_e32 v75, 32, v74
	v_xor_b32_e32 v76, 64, v74
	v_xor_b32_e32 v77, 0x60, v74
	v_lshl_or_b32 v73, v94, 5, v93
	v_lshrrev_b32_e32 v72, 3, v73
	v_mul_u32_u24_e32 v72, 0x3400, v72
	v_lshrrev_b32_e32 v78, 4, v73
	v_and_b32_e32 v73, 7, v73
	v_xor_b32_e32 v73, v73, v78
	v_lshl_add_u32 v72, v73, 4, v72
	v_xor_b32_e32 v73, 64, v72
	s_add_u32 m0, s100, 0x2000
	v_readfirstlane_b32 s100, v88
	s_nop 0
	s_and_b32 s100, s100, 0xf800
	s_mul_i32 s100, s100, 0x3400
	s_add_u32 s100, s100, 0xd3200
	s_add_u32 s100, s74, s100
	s_addc_u32 s101, s75, 0
	s_nop 0
	global_load_lds_dwordx4 v72, s[100:101]
	s_add_u32 m0, m0, 0x400
	s_add_u32 s100, s100, 0x1a000
	s_addc_u32 s101, s101, 0
	s_nop 0
	global_load_lds_dwordx4 v73, s[100:101]
	s_add_u32 m0, m0, 0x400
	s_add_u32 s100, s100, 0x1a000
	s_addc_u32 s101, s101, 0
	s_nop 0
	global_load_lds_dwordx4 v72, s[100:101]
	s_add_u32 m0, m0, 0x400
	s_add_u32 s100, s100, 0x1a000
	s_addc_u32 s101, s101, 0
	s_nop 0
	global_load_lds_dwordx4 v73, s[100:101]
	s_add_u32 m0, m0, 0x400
	s_add_u32 s100, s100, 0x1a000
	s_addc_u32 s101, s101, 0
	s_nop 0
	global_load_lds_dwordx4 v72, s[100:101]
	s_add_u32 m0, m0, 0x400
	s_add_u32 s100, s100, 0x1a000
	s_addc_u32 s101, s101, 0
	s_nop 0
	global_load_lds_dwordx4 v73, s[100:101]
	s_add_u32 m0, m0, 0x400
	s_add_u32 s100, s100, 0x1a000
	s_addc_u32 s101, s101, 0
	s_nop 0
	global_load_lds_dwordx4 v72, s[100:101]
	s_add_u32 m0, m0, 0x400
	s_add_u32 s100, s100, 0x1a000
	s_addc_u32 s101, s101, 0
	s_nop 0
	global_load_lds_dwordx4 v73, s[100:101]
	s_sub_u32 m0, m0, 0x3c00
	s_add_u32 s100, s100, 0x1a000
	s_addc_u32 s101, s101, 0
	s_nop 0
	global_load_lds_dwordx4 v72, s[100:101]
	s_add_u32 m0, m0, 0x400
	s_add_u32 s100, s100, 0x1a000
	s_addc_u32 s101, s101, 0
	s_nop 0
	global_load_lds_dwordx4 v73, s[100:101]
	s_add_u32 m0, m0, 0x400
	s_add_u32 s100, s100, 0x1a000
	s_addc_u32 s101, s101, 0
	s_nop 0
	global_load_lds_dwordx4 v72, s[100:101]
	s_add_u32 m0, m0, 0x400
	s_add_u32 s100, s100, 0x1a000
	s_addc_u32 s101, s101, 0
	s_nop 0
	global_load_lds_dwordx4 v73, s[100:101]
	s_add_u32 m0, m0, 0x400
	s_add_u32 s100, s100, 0x1a000
	s_addc_u32 s101, s101, 0
	v_mad_i64_i32 v[4:5], s[74:75], v2, s80, v[42:43]
	v_lshl_add_u64 v[4:5], v[4:5], 0, v[0:1]
	v_mov_b32_e32 v87, v1
	v_lshl_add_u64 v[4:5], v[4:5], 0, v[86:87]
	s_mov_b64 s[74:75], 0x1200
	v_lshl_add_u64 v[34:35], v[4:5], 0, s[74:75]
	v_add_co_u32_e32 v4, vcc, 0x1000, v4
	global_load_dwordx4 v[10:13], v[34:35], off offset:64
	s_nop 0
	v_addc_co_u32_e32 v5, vcc, 0, v5, vcc
	global_load_dwordx4 v[14:17], v[4:5], off offset:512
	v_ashrrev_i32_e32 v3, 31, v2
	v_lshlrev_b64 v[2:3], 8, v[2:3]
	v_lshl_add_u64 v[44:45], v[82:83], 0, v[2:3]
	global_load_dwordx4 v[18:21], v[44:45], off
	global_load_dwordx4 v[22:25], v[44:45], off offset:16
	global_load_dwordx4 v[26:29], v[44:45], off offset:32
	global_load_dwordx4 v[30:33], v[44:45], off offset:48
	global_load_dwordx4 v[6:9], v[34:35], off offset:32
	global_load_dwordx4 v[2:5], v[34:35], off offset:96
	s_movk_i32 s2, 0xf800
	v_and_b32_e32 v177, 0x7fe, v88
	s_waitcnt vmcnt(7)
	v_lshlrev_b32_e32 v34, 16, v10
	v_and_b32_e32 v10, 0xffff0000, v10
	v_lshlrev_b32_e32 v36, 16, v11
	v_and_b32_e32 v38, 0xffff0000, v11
	v_lshlrev_b32_e32 v40, 16, v12
	v_and_b32_e32 v12, 0xffff0000, v12
	v_lshlrev_b32_e32 v46, 16, v13
	v_and_b32_e32 v48, 0xffff0000, v13
	s_waitcnt vmcnt(6)
	v_lshlrev_b32_e32 v35, 16, v14
	v_and_b32_e32 v11, 0xffff0000, v14
	v_lshlrev_b32_e32 v37, 16, v15
	v_and_b32_e32 v39, 0xffff0000, v15
	v_lshlrev_b32_e32 v41, 16, v16
	v_and_b32_e32 v13, 0xffff0000, v16
	v_lshlrev_b32_e32 v47, 16, v17
	v_and_b32_e32 v49, 0xffff0000, v17
	s_waitcnt vmcnt(5)
	v_pk_mul_f32 v[14:15], v[18:19], v[34:35] op_sel:[0,1] op_sel_hi:[1,0]
	v_pk_mul_f32 v[16:17], v[18:19], v[34:35]
	v_pk_mul_f32 v[18:19], v[20:21], v[10:11] op_sel:[0,1] op_sel_hi:[1,0]
	v_pk_mul_f32 v[10:11], v[20:21], v[10:11]
	s_waitcnt vmcnt(4)
	v_pk_mul_f32 v[20:21], v[22:23], v[36:37] op_sel:[0,1] op_sel_hi:[1,0]
	v_pk_mul_f32 v[22:23], v[22:23], v[36:37]
	v_pk_mul_f32 v[34:35], v[24:25], v[38:39] op_sel:[0,1] op_sel_hi:[1,0]
	v_pk_mul_f32 v[24:25], v[24:25], v[38:39]
	s_waitcnt vmcnt(3)
	v_pk_mul_f32 v[36:37], v[26:27], v[40:41] op_sel:[0,1] op_sel_hi:[1,0]
	v_pk_mul_f32 v[26:27], v[26:27], v[40:41]
	v_pk_mul_f32 v[38:39], v[28:29], v[12:13] op_sel:[0,1] op_sel_hi:[1,0]
	v_pk_mul_f32 v[12:13], v[28:29], v[12:13]
	s_waitcnt vmcnt(2)
	v_pk_mul_f32 v[28:29], v[30:31], v[46:47] op_sel:[0,1] op_sel_hi:[1,0]
	v_pk_mul_f32 v[30:31], v[30:31], v[46:47]
	v_pk_mul_f32 v[40:41], v[32:33], v[48:49] op_sel:[0,1] op_sel_hi:[1,0]
	v_pk_mul_f32 v[32:33], v[32:33], v[48:49]
	v_sub_f32_e32 v14, v14, v15
	v_add_f32_e32 v15, v17, v16
	v_sub_f32_e32 v16, v18, v19
	v_add_f32_e32 v10, v10, v11
	v_sub_f32_e32 v11, v20, v21
	v_add_f32_e32 v17, v22, v23
	v_sub_f32_e32 v18, v34, v35
	v_add_f32_e32 v19, v24, v25
	v_sub_f32_e32 v20, v36, v37
	v_add_f32_e32 v21, v26, v27
	v_sub_f32_e32 v22, v38, v39
	v_add_f32_e32 v12, v12, v13
	v_sub_f32_e32 v13, v28, v29
	v_add_f32_e32 v23, v30, v31
	v_sub_f32_e32 v24, v40, v41
	v_add_f32_e32 v25, v32, v33
	v_cvt_pk_bf16_f32 v38, v14, v16
	v_cvt_pk_bf16_f32 v39, v11, v18
	v_cvt_pk_bf16_f32 v40, v20, v22
	v_cvt_pk_bf16_f32 v41, v13, v24
	v_cvt_pk_bf16_f32 v34, v15, v10
	v_cvt_pk_bf16_f32 v35, v17, v19
	v_cvt_pk_bf16_f32 v36, v21, v12
	v_cvt_pk_bf16_f32 v37, v23, v25
	global_load_dwordx4 v[10:13], v[44:45], off offset:128
	global_load_dwordx4 v[14:17], v[44:45], off offset:144
	global_load_dwordx4 v[18:21], v[44:45], off offset:160
	global_load_dwordx4 v[22:25], v[44:45], off offset:176
	v_or_b32_e32 v26, v88, v94
	v_and_or_b32 v28, v88, s2, v93
	v_mad_i64_i32 v[26:27], s[74:75], v26, s80, v[42:43]
	s_movk_i32 s2, 0x3000
	v_mad_i64_i32 v[28:29], s[74:75], v28, s80, v[42:43]
	v_add_co_u32_e32 v32, vcc, s2, v26
	v_lshl_add_u64 v[30:31], v[28:29], 0, v[86:87]
	s_nop 0
	v_addc_co_u32_e32 v33, vcc, 0, v27, vcc
	s_waitcnt vmcnt(5)
	v_lshlrev_b32_e32 v27, 16, v6
	v_and_b32_e32 v29, 0xffff0000, v6
	v_lshlrev_b32_e32 v43, 16, v7
	v_and_b32_e32 v7, 0xffff0000, v7
	v_lshlrev_b32_e32 v45, 16, v8
	v_and_b32_e32 v47, 0xffff0000, v8
	v_lshlrev_b32_e32 v49, 16, v9
	v_and_b32_e32 v9, 0xffff0000, v9
	s_waitcnt vmcnt(4)
	v_lshlrev_b32_e32 v26, 16, v2
	v_and_b32_e32 v28, 0xffff0000, v2
	v_lshlrev_b32_e32 v42, 16, v3
	v_and_b32_e32 v6, 0xffff0000, v3
	v_lshlrev_b32_e32 v44, 16, v4
	v_and_b32_e32 v46, 0xffff0000, v4
	v_and_b32_e32 v8, 0xffff0000, v5
	s_mov_b64 s[74:75], 0x3200
	v_lshlrev_b32_e32 v48, 16, v5
	v_lshl_add_u64 v[90:91], v[30:31], 0, s[74:75]
	v_add_co_u32_e32 v30, vcc, 0x3000, v30
	v_cmp_lt_u32_e64 s[74:75], 31, v177
	s_nop 0
	v_addc_co_u32_e32 v31, vcc, 0, v31, vcc
	s_waitcnt vmcnt(3)
	v_pk_mul_f32 v[2:3], v[10:11], v[26:27] op_sel:[0,1] op_sel_hi:[1,0]
	v_pk_mul_f32 v[4:5], v[10:11], v[26:27]
	v_pk_mul_f32 v[10:11], v[12:13], v[28:29] op_sel:[0,1] op_sel_hi:[1,0]
	v_pk_mul_f32 v[12:13], v[12:13], v[28:29]
	s_waitcnt vmcnt(2)
	v_pk_mul_f32 v[26:27], v[14:15], v[42:43] op_sel:[0,1] op_sel_hi:[1,0]
	v_pk_mul_f32 v[14:15], v[14:15], v[42:43]
	v_pk_mul_f32 v[28:29], v[16:17], v[6:7] op_sel:[0,1] op_sel_hi:[1,0]
	v_pk_mul_f32 v[6:7], v[16:17], v[6:7]
	s_waitcnt vmcnt(1)
	v_pk_mul_f32 v[16:17], v[18:19], v[44:45] op_sel:[0,1] op_sel_hi:[1,0]
	v_pk_mul_f32 v[18:19], v[18:19], v[44:45]
	v_pk_mul_f32 v[42:43], v[20:21], v[46:47] op_sel:[0,1] op_sel_hi:[1,0]
	v_pk_mul_f32 v[20:21], v[20:21], v[46:47]
	s_waitcnt vmcnt(0)
	v_pk_mul_f32 v[46:47], v[24:25], v[8:9] op_sel:[0,1] op_sel_hi:[1,0]
	v_pk_mul_f32 v[44:45], v[22:23], v[48:49] op_sel:[0,1] op_sel_hi:[1,0]
	v_pk_mul_f32 v[22:23], v[22:23], v[48:49]
	v_pk_mul_f32 v[8:9], v[24:25], v[8:9]
	v_sub_f32_e32 v2, v2, v3
	v_add_f32_e32 v3, v4, v5
	v_sub_f32_e32 v4, v10, v11
	v_add_f32_e32 v5, v12, v13
	v_add_f32_e32 v13, v18, v19
	v_sub_f32_e32 v18, v46, v47
	v_sub_f32_e32 v10, v26, v27
	v_add_f32_e32 v11, v14, v15
	v_sub_f32_e32 v12, v28, v29
	v_add_f32_e32 v6, v6, v7
	v_sub_f32_e32 v7, v16, v17
	v_sub_f32_e32 v14, v42, v43
	v_add_f32_e32 v15, v20, v21
	v_sub_f32_e32 v16, v44, v45
	v_add_f32_e32 v17, v22, v23
	v_add_f32_e32 v8, v8, v9
	v_cvt_pk_bf16_f32 v46, v2, v4
	v_cvt_pk_bf16_f32 v47, v10, v12
	v_cvt_pk_bf16_f32 v48, v7, v14
	v_cvt_pk_bf16_f32 v49, v16, v18
	v_cvt_pk_bf16_f32 v42, v3, v5
	v_cvt_pk_bf16_f32 v43, v11, v6
	v_cvt_pk_bf16_f32 v44, v13, v15
	v_cvt_pk_bf16_f32 v45, v17, v8
	global_load_dwordx4 v[26:29], v[90:91], off offset:32
	global_load_dwordx4 v[18:21], v[90:91], off offset:64
	global_load_dwordx4 v[2:5], v[32:33], off offset:768
	global_load_dwordx4 v[22:25], v[90:91], off offset:96
	global_load_dwordx4 v[6:9], v[30:31], off offset:512
	global_load_dwordx4 v[10:13], v[32:33], off offset:784
	s_waitcnt vmcnt(5)
	v_mov_b64_e32 v[56:57], v[28:29]
	s_waitcnt vmcnt(4)
	v_mov_b64_e32 v[52:53], v[20:21]
	v_mov_b64_e32 v[50:51], v[18:19]
	s_waitcnt vmcnt(2)
	v_mov_b64_e32 v[64:65], v[24:25]
	s_waitcnt vmcnt(1)
	v_mov_b64_e32 v[60:61], v[8:9]
	v_mov_b64_e32 v[62:63], v[22:23]
	v_mov_b64_e32 v[54:55], v[26:27]
	v_mov_b64_e32 v[58:59], v[6:7]
	s_and_saveexec_b64 s[80:81], s[74:75]
	s_cbranch_execz .LBB0_401
	v_add_co_u32_e32 v14, vcc, 0x68000, v90
	s_nop 1
	v_addc_co_u32_e32 v15, vcc, 0, v91, vcc
	global_load_dwordx4 v[58:61], v[14:15], off
	global_load_dwordx4 v[54:57], v[14:15], off offset:32
	global_load_dwordx4 v[50:53], v[14:15], off offset:64
	global_load_dwordx4 v[62:65], v[14:15], off offset:96
.LBB0_401:
	s_or_b64 exec, exec, s[80:81]
	v_lshlrev_b32_e32 v174, 16, v2
	s_waitcnt vmcnt(0)
	v_lshlrev_b32_e32 v166, 16, v10
	v_and_b32_e32 v173, 0xffff0000, v2
	v_and_b32_e32 v165, 0xffff0000, v10
	v_lshlrev_b32_e32 v172, 16, v3
	v_lshlrev_b32_e32 v164, 16, v11
	v_and_b32_e32 v171, 0xffff0000, v3
	v_and_b32_e32 v163, 0xffff0000, v11
	v_lshlrev_b32_e32 v170, 16, v4
	v_lshlrev_b32_e32 v162, 16, v12
	v_and_b32_e32 v169, 0xffff0000, v4
	v_and_b32_e32 v161, 0xffff0000, v12
	v_lshlrev_b32_e32 v168, 16, v5
	v_lshlrev_b32_e32 v160, 16, v13
	v_and_b32_e32 v167, 0xffff0000, v5
	v_and_b32_e32 v89, 0xffff0000, v13
	v_mfma_f32_32x32x16_bf16 v[2:17], v[38:41], v[6:9], 0
	v_or_b32_e32 v87, v177, v94
	v_mov_b32_e32 v175, 0
	v_mfma_f32_32x32x16_bf16 v[2:17], v[46:49], v[26:29], v[2:17]
	v_mfma_f32_32x32x16_bf16 v[2:17], v[34:37], v[18:21], v[2:17]
	v_mfma_f32_32x32x16_bf16 v[2:17], v[42:45], v[22:25], v[2:17]
	s_and_saveexec_b64 s[80:81], s[74:75]
	s_cbranch_execz .LBB0_405
	s_waitcnt lgkmcnt(0)
	v_cmp_lt_u32_e32 vcc, 63, v177
	s_and_saveexec_b64 s[74:75], vcc
	s_cbranch_execz .LBB0_404
	s_nop 0
	global_load_lds_dwordx4 v72, s[100:101]
	s_add_u32 m0, m0, 0x400
	s_add_u32 s100, s100, 0x1a000
	s_addc_u32 s101, s101, 0
	s_nop 0
	global_load_lds_dwordx4 v73, s[100:101]
	s_add_u32 m0, m0, 0x400
	s_add_u32 s100, s100, 0x1a000
	s_addc_u32 s101, s101, 0
	s_nop 0
	global_load_lds_dwordx4 v72, s[100:101]
	s_add_u32 m0, m0, 0x400
	s_add_u32 s100, s100, 0x1a000
	s_addc_u32 s101, s101, 0
	s_nop 0
	global_load_lds_dwordx4 v73, s[100:101]
	s_add_u32 m0, m0, 0x400
	s_add_u32 s100, s100, 0x1a000
	s_addc_u32 s101, s101, 0
.LBB0_404:
	s_or_b64 exec, exec, s[74:75]
	v_mfma_f32_32x32x16_bf16 v[18:33], v[38:41], v[58:61], 0
	v_mfma_f32_32x32x16_bf16 v[18:33], v[46:49], v[54:57], v[18:33]
	v_mfma_f32_32x32x16_bf16 v[18:33], v[34:37], v[50:53], v[18:33]
	v_mfma_f32_32x32x16_bf16 v[18:33], v[42:45], v[62:65], v[18:33]
	s_waitcnt vmcnt(12)
	ds_read_b128 v[58:61], v74 offset:8192
	ds_read_b128 v[54:57], v75 offset:8192
	ds_read_b128 v[50:53], v76 offset:8192
	ds_read_b128 v[62:65], v77 offset:8192
	s_nop 8
	v_max_f32_e32 v18, v18, v18
	v_max_f32_e32 v19, v19, v19
	v_max_f32_e32 v18, 0, v18
	v_max_f32_e32 v20, v20, v20
	v_max_f32_e32 v19, 0, v19
	v_fma_f32 v18, v174, v18, 0
	v_max_f32_e32 v21, v21, v21
	v_max_f32_e32 v20, 0, v20
	v_fmac_f32_e32 v18, v173, v19
	v_max_f32_e32 v22, v22, v22
	v_max_f32_e32 v21, 0, v21
	v_fmac_f32_e32 v18, v172, v20
	v_max_f32_e32 v23, v23, v23
	v_max_f32_e32 v22, 0, v22
	v_fmac_f32_e32 v18, v171, v21
	v_max_f32_e32 v24, v24, v24
	v_max_f32_e32 v23, 0, v23
	v_fmac_f32_e32 v18, v170, v22
	v_max_f32_e32 v25, v25, v25
	v_max_f32_e32 v24, 0, v24
	v_fmac_f32_e32 v18, v169, v23
	v_max_f32_e32 v26, v26, v26
	v_max_f32_e32 v25, 0, v25
	v_fmac_f32_e32 v18, v168, v24
	v_max_f32_e32 v27, v27, v27
	v_max_f32_e32 v26, 0, v26
	v_fmac_f32_e32 v18, v167, v25
	v_max_f32_e32 v28, v28, v28
	v_max_f32_e32 v27, 0, v27
	v_fmac_f32_e32 v18, v166, v26
	v_max_f32_e32 v29, v29, v29
	v_max_f32_e32 v28, 0, v28
	v_fmac_f32_e32 v18, v165, v27
	v_max_f32_e32 v30, v30, v30
	v_max_f32_e32 v29, 0, v29
	v_fmac_f32_e32 v18, v164, v28
	v_max_f32_e32 v31, v31, v31
	v_max_f32_e32 v30, 0, v30
	v_fmac_f32_e32 v18, v163, v29
	v_fmac_f32_e32 v18, v162, v30
	v_max_f32_e32 v19, 0, v31
	v_fmac_f32_e32 v18, v161, v19
	v_max_f32_e32 v19, v32, v32
	v_max_f32_e32 v19, 0, v19
	v_fmac_f32_e32 v18, v160, v19
	v_max_f32_e32 v19, v33, v33
	v_max_f32_e32 v19, 0, v19
	v_fmac_f32_e32 v18, v89, v19
	v_not_b32_e32 v19, v18
	v_or_b32_e32 v20, 0x80000000, v18
	v_cmp_gt_i32_e32 vcc, 0, v18
	s_nop 1
	v_cndmask_b32_e32 v18, v20, v19, vcc
	v_cmp_le_u32_e32 vcc, v96, v87
	s_nop 1
	v_cndmask_b32_e32 v175, 0, v18, vcc
.LBB0_405:
	s_or_b64 exec, exec, s[80:81]
	s_xor_b64 s[80:81], s[82:83], -1
	v_cmp_lt_u32_e32 vcc, 63, v177
	v_mov_b32_e32 v176, 0
	s_and_saveexec_b64 s[74:75], vcc
	s_cbranch_execz .LBB0_409
	s_movk_i32 s2, 0x5f
	s_waitcnt lgkmcnt(0)
	v_cmp_lt_u32_e32 vcc, s2, v177
	s_and_saveexec_b64 s[82:83], vcc
	s_cbranch_execz .LBB0_408
	s_nop 0
	global_load_lds_dwordx4 v72, s[100:101]
	s_add_u32 m0, m0, 0x400
	s_add_u32 s100, s100, 0x1a000
	s_addc_u32 s101, s101, 0
	s_nop 0
	global_load_lds_dwordx4 v73, s[100:101]
	s_add_u32 m0, m0, 0x400
	s_add_u32 s100, s100, 0x1a000
	s_addc_u32 s101, s101, 0
	s_nop 0
	global_load_lds_dwordx4 v72, s[100:101]
	s_add_u32 m0, m0, 0x400
	s_add_u32 s100, s100, 0x1a000
	s_addc_u32 s101, s101, 0
	s_nop 0
	global_load_lds_dwordx4 v73, s[100:101]
	s_add_u32 m0, m0, 0x400
	s_add_u32 s100, s100, 0x1a000
	s_addc_u32 s101, s101, 0
.LBB0_408:
	s_or_b64 exec, exec, s[82:83]
	v_mfma_f32_32x32x16_bf16 v[18:33], v[38:41], v[58:61], 0
	v_mfma_f32_32x32x16_bf16 v[18:33], v[46:49], v[54:57], v[18:33]
	v_mfma_f32_32x32x16_bf16 v[18:33], v[34:37], v[50:53], v[18:33]
	v_mfma_f32_32x32x16_bf16 v[18:33], v[42:45], v[62:65], v[18:33]
	s_waitcnt vmcnt(12)
	ds_read_b128 v[58:61], v74 offset:12288
	ds_read_b128 v[54:57], v75 offset:12288
	ds_read_b128 v[50:53], v76 offset:12288
	ds_read_b128 v[62:65], v77 offset:12288
	s_nop 8
	v_max_f32_e32 v18, v18, v18
	v_max_f32_e32 v19, v19, v19
	v_max_f32_e32 v18, 0, v18
	v_max_f32_e32 v20, v20, v20
	v_max_f32_e32 v19, 0, v19
	v_fma_f32 v18, v174, v18, 0
	v_max_f32_e32 v21, v21, v21
	v_max_f32_e32 v20, 0, v20
	v_fmac_f32_e32 v18, v173, v19
	v_max_f32_e32 v22, v22, v22
	v_max_f32_e32 v21, 0, v21
	v_fmac_f32_e32 v18, v172, v20
	v_max_f32_e32 v23, v23, v23
	v_max_f32_e32 v22, 0, v22
	v_fmac_f32_e32 v18, v171, v21
	v_max_f32_e32 v24, v24, v24
	v_max_f32_e32 v23, 0, v23
	v_fmac_f32_e32 v18, v170, v22
	v_max_f32_e32 v25, v25, v25
	v_max_f32_e32 v24, 0, v24
	v_fmac_f32_e32 v18, v169, v23
	v_max_f32_e32 v26, v26, v26
	v_max_f32_e32 v25, 0, v25
	v_fmac_f32_e32 v18, v168, v24
	v_max_f32_e32 v27, v27, v27
	v_max_f32_e32 v26, 0, v26
	v_fmac_f32_e32 v18, v167, v25
	v_max_f32_e32 v28, v28, v28
	v_max_f32_e32 v27, 0, v27
	v_fmac_f32_e32 v18, v166, v26
	v_max_f32_e32 v29, v29, v29
	v_max_f32_e32 v28, 0, v28
	v_fmac_f32_e32 v18, v165, v27
	v_max_f32_e32 v30, v30, v30
	v_max_f32_e32 v29, 0, v29
	v_fmac_f32_e32 v18, v164, v28
	v_max_f32_e32 v31, v31, v31
	v_max_f32_e32 v30, 0, v30
	v_fmac_f32_e32 v18, v163, v29
	v_fmac_f32_e32 v18, v162, v30
	v_max_f32_e32 v19, 0, v31
	v_fmac_f32_e32 v18, v161, v19
	v_max_f32_e32 v19, v32, v32
	v_max_f32_e32 v19, 0, v19
	v_fmac_f32_e32 v18, v160, v19
	v_max_f32_e32 v19, v33, v33
	v_max_f32_e32 v19, 0, v19
	v_fmac_f32_e32 v18, v89, v19
	v_not_b32_e32 v19, v18
	v_or_b32_e32 v20, 0x80000000, v18
	v_cmp_gt_i32_e32 vcc, 0, v18
	s_nop 1
	v_cndmask_b32_e32 v18, v20, v19, vcc
	v_cmp_le_u32_e32 vcc, v97, v87
	s_nop 1
	v_cndmask_b32_e32 v176, 0, v18, vcc
.LBB0_409:
	s_or_b64 exec, exec, s[74:75]
	s_movk_i32 s2, 0x5f
	v_cmp_lt_u32_e32 vcc, s2, v177
	v_mov_b32_e32 v179, 0
	s_and_saveexec_b64 s[74:75], vcc
	s_cbranch_execz .LBB0_413
	s_movk_i32 s2, 0x7f
	s_waitcnt lgkmcnt(0)
	v_cmp_lt_u32_e32 vcc, s2, v177
	s_and_saveexec_b64 s[82:83], vcc
	s_cbranch_execz .LBB0_412
	s_nop 0
	global_load_lds_dwordx4 v72, s[100:101]
	s_add_u32 m0, m0, 0x400
	s_add_u32 s100, s100, 0x1a000
	s_addc_u32 s101, s101, 0
	s_nop 0
	global_load_lds_dwordx4 v73, s[100:101]
	s_add_u32 m0, m0, 0x400
	s_add_u32 s100, s100, 0x1a000
	s_addc_u32 s101, s101, 0
	s_nop 0
	global_load_lds_dwordx4 v72, s[100:101]
	s_add_u32 m0, m0, 0x400
	s_add_u32 s100, s100, 0x1a000
	s_addc_u32 s101, s101, 0
	s_nop 0
	global_load_lds_dwordx4 v73, s[100:101]
	s_sub_u32 m0, m0, 0x3c00
	s_add_u32 s100, s100, 0x1a000
	s_addc_u32 s101, s101, 0
.LBB0_412:
	s_or_b64 exec, exec, s[82:83]
	v_mfma_f32_32x32x16_bf16 v[18:33], v[38:41], v[58:61], 0
	v_mfma_f32_32x32x16_bf16 v[18:33], v[46:49], v[54:57], v[18:33]
	v_mfma_f32_32x32x16_bf16 v[18:33], v[34:37], v[50:53], v[18:33]
	v_mfma_f32_32x32x16_bf16 v[18:33], v[42:45], v[62:65], v[18:33]
	s_waitcnt vmcnt(12)
	ds_read_b128 v[58:61], v74 offset:0
	ds_read_b128 v[54:57], v75 offset:0
	ds_read_b128 v[50:53], v76 offset:0
	ds_read_b128 v[62:65], v77 offset:0
	s_nop 8
	v_max_f32_e32 v18, v18, v18
	v_max_f32_e32 v19, v19, v19
	v_max_f32_e32 v18, 0, v18
	v_max_f32_e32 v20, v20, v20
	v_max_f32_e32 v19, 0, v19
	v_fma_f32 v18, v174, v18, 0
	v_max_f32_e32 v21, v21, v21
	v_max_f32_e32 v20, 0, v20
	v_fmac_f32_e32 v18, v173, v19
	v_max_f32_e32 v22, v22, v22
	v_max_f32_e32 v21, 0, v21
	v_fmac_f32_e32 v18, v172, v20
	v_max_f32_e32 v23, v23, v23
	v_max_f32_e32 v22, 0, v22
	v_fmac_f32_e32 v18, v171, v21
	v_max_f32_e32 v24, v24, v24
	v_max_f32_e32 v23, 0, v23
	v_fmac_f32_e32 v18, v170, v22
	v_max_f32_e32 v25, v25, v25
	v_max_f32_e32 v24, 0, v24
	v_fmac_f32_e32 v18, v169, v23
	v_max_f32_e32 v26, v26, v26
	v_max_f32_e32 v25, 0, v25
	v_fmac_f32_e32 v18, v168, v24
	v_max_f32_e32 v27, v27, v27
	v_max_f32_e32 v26, 0, v26
	v_fmac_f32_e32 v18, v167, v25
	v_max_f32_e32 v28, v28, v28
	v_max_f32_e32 v27, 0, v27
	v_fmac_f32_e32 v18, v166, v26
	v_max_f32_e32 v29, v29, v29
	v_max_f32_e32 v28, 0, v28
	v_fmac_f32_e32 v18, v165, v27
	v_max_f32_e32 v30, v30, v30
	v_max_f32_e32 v29, 0, v29
	v_fmac_f32_e32 v18, v164, v28
	v_max_f32_e32 v31, v31, v31
	v_max_f32_e32 v30, 0, v30
	v_fmac_f32_e32 v18, v163, v29
	v_fmac_f32_e32 v18, v162, v30
	v_max_f32_e32 v19, 0, v31
	v_fmac_f32_e32 v18, v161, v19
	v_max_f32_e32 v19, v32, v32
	v_max_f32_e32 v19, 0, v19
	v_fmac_f32_e32 v18, v160, v19
	v_max_f32_e32 v19, v33, v33
	v_max_f32_e32 v19, 0, v19
	v_fmac_f32_e32 v18, v89, v19
	v_not_b32_e32 v19, v18
	v_or_b32_e32 v20, 0x80000000, v18
	v_cmp_gt_i32_e32 vcc, 0, v18
	s_nop 1
	v_cndmask_b32_e32 v18, v20, v19, vcc
	v_cmp_le_u32_e32 vcc, v98, v87
	s_nop 1
	v_cndmask_b32_e32 v179, 0, v18, vcc
.LBB0_413:
	s_or_b64 exec, exec, s[74:75]
	s_movk_i32 s2, 0x7f
	v_cmp_lt_u32_e32 vcc, s2, v177
	v_mov_b32_e32 v180, 0
	s_and_saveexec_b64 s[74:75], vcc
	s_cbranch_execz .LBB0_417
	s_movk_i32 s2, 0x9f
	s_waitcnt lgkmcnt(0)
	v_cmp_lt_u32_e32 vcc, s2, v177
	s_and_saveexec_b64 s[82:83], vcc
	s_cbranch_execz .LBB0_416
	s_nop 0
	global_load_lds_dwordx4 v72, s[100:101]
	s_add_u32 m0, m0, 0x400
	s_add_u32 s100, s100, 0x1a000
	s_addc_u32 s101, s101, 0
	s_nop 0
	global_load_lds_dwordx4 v73, s[100:101]
	s_add_u32 m0, m0, 0x400
	s_add_u32 s100, s100, 0x1a000
	s_addc_u32 s101, s101, 0
	s_nop 0
	global_load_lds_dwordx4 v72, s[100:101]
	s_add_u32 m0, m0, 0x400
	s_add_u32 s100, s100, 0x1a000
	s_addc_u32 s101, s101, 0
	s_nop 0
	global_load_lds_dwordx4 v73, s[100:101]
	s_add_u32 m0, m0, 0x400
	s_add_u32 s100, s100, 0x1a000
	s_addc_u32 s101, s101, 0
.LBB0_416:
	s_or_b64 exec, exec, s[82:83]
	v_mfma_f32_32x32x16_bf16 v[18:33], v[38:41], v[58:61], 0
	v_mfma_f32_32x32x16_bf16 v[18:33], v[46:49], v[54:57], v[18:33]
	v_mfma_f32_32x32x16_bf16 v[18:33], v[34:37], v[50:53], v[18:33]
	v_mfma_f32_32x32x16_bf16 v[18:33], v[42:45], v[62:65], v[18:33]
	s_waitcnt vmcnt(12)
	ds_read_b128 v[58:61], v74 offset:4096
	ds_read_b128 v[54:57], v75 offset:4096
	ds_read_b128 v[50:53], v76 offset:4096
	ds_read_b128 v[62:65], v77 offset:4096
	s_nop 8
	v_max_f32_e32 v18, v18, v18
	v_max_f32_e32 v19, v19, v19
	v_max_f32_e32 v18, 0, v18
	v_max_f32_e32 v20, v20, v20
	v_max_f32_e32 v19, 0, v19
	v_fma_f32 v18, v174, v18, 0
	v_max_f32_e32 v21, v21, v21
	v_max_f32_e32 v20, 0, v20
	v_fmac_f32_e32 v18, v173, v19
	v_max_f32_e32 v22, v22, v22
	v_max_f32_e32 v21, 0, v21
	v_fmac_f32_e32 v18, v172, v20
	v_max_f32_e32 v23, v23, v23
	v_max_f32_e32 v22, 0, v22
	v_fmac_f32_e32 v18, v171, v21
	v_max_f32_e32 v24, v24, v24
	v_max_f32_e32 v23, 0, v23
	v_fmac_f32_e32 v18, v170, v22
	v_max_f32_e32 v25, v25, v25
	v_max_f32_e32 v24, 0, v24
	v_fmac_f32_e32 v18, v169, v23
	v_max_f32_e32 v26, v26, v26
	v_max_f32_e32 v25, 0, v25
	v_fmac_f32_e32 v18, v168, v24
	v_max_f32_e32 v27, v27, v27
	v_max_f32_e32 v26, 0, v26
	v_fmac_f32_e32 v18, v167, v25
	v_max_f32_e32 v28, v28, v28
	v_max_f32_e32 v27, 0, v27
	v_fmac_f32_e32 v18, v166, v26
	v_max_f32_e32 v29, v29, v29
	v_max_f32_e32 v28, 0, v28
	v_fmac_f32_e32 v18, v165, v27
	v_max_f32_e32 v30, v30, v30
	v_max_f32_e32 v29, 0, v29
	v_fmac_f32_e32 v18, v164, v28
	v_max_f32_e32 v31, v31, v31
	v_max_f32_e32 v30, 0, v30
	v_fmac_f32_e32 v18, v163, v29
	v_fmac_f32_e32 v18, v162, v30
	v_max_f32_e32 v19, 0, v31
	v_fmac_f32_e32 v18, v161, v19
	v_max_f32_e32 v19, v32, v32
	v_max_f32_e32 v19, 0, v19
	v_fmac_f32_e32 v18, v160, v19
	v_max_f32_e32 v19, v33, v33
	v_max_f32_e32 v19, 0, v19
	v_fmac_f32_e32 v18, v89, v19
	v_not_b32_e32 v19, v18
	v_or_b32_e32 v20, 0x80000000, v18
	v_cmp_gt_i32_e32 vcc, 0, v18
	s_nop 1
	v_cndmask_b32_e32 v18, v20, v19, vcc
	v_cmp_le_u32_e32 vcc, v99, v87
	s_nop 1
	v_cndmask_b32_e32 v180, 0, v18, vcc
.LBB0_417:
	s_or_b64 exec, exec, s[74:75]
	s_movk_i32 s2, 0x9f
	v_cmp_lt_u32_e32 vcc, s2, v177
	v_mov_b32_e32 v181, 0
	s_and_saveexec_b64 s[74:75], vcc
	s_cbranch_execz .LBB0_421
	s_movk_i32 s2, 0xbf
	s_waitcnt lgkmcnt(0)
	v_cmp_lt_u32_e32 vcc, s2, v177
	s_and_saveexec_b64 s[82:83], vcc
	s_cbranch_execz .LBB0_420
	s_nop 0
	global_load_lds_dwordx4 v72, s[100:101]
	s_add_u32 m0, m0, 0x400
	s_add_u32 s100, s100, 0x1a000
	s_addc_u32 s101, s101, 0
	s_nop 0
	global_load_lds_dwordx4 v73, s[100:101]
	s_add_u32 m0, m0, 0x400
	s_add_u32 s100, s100, 0x1a000
	s_addc_u32 s101, s101, 0
	s_nop 0
	global_load_lds_dwordx4 v72, s[100:101]
	s_add_u32 m0, m0, 0x400
	s_add_u32 s100, s100, 0x1a000
	s_addc_u32 s101, s101, 0
	s_nop 0
	global_load_lds_dwordx4 v73, s[100:101]
	s_add_u32 m0, m0, 0x400
	s_add_u32 s100, s100, 0x1a000
	s_addc_u32 s101, s101, 0
.LBB0_420:
	s_or_b64 exec, exec, s[82:83]
	v_mfma_f32_32x32x16_bf16 v[18:33], v[38:41], v[58:61], 0
	v_mfma_f32_32x32x16_bf16 v[18:33], v[46:49], v[54:57], v[18:33]
	v_mfma_f32_32x32x16_bf16 v[18:33], v[34:37], v[50:53], v[18:33]
	v_mfma_f32_32x32x16_bf16 v[18:33], v[42:45], v[62:65], v[18:33]
	s_waitcnt vmcnt(12)
	ds_read_b128 v[58:61], v74 offset:8192
	ds_read_b128 v[54:57], v75 offset:8192
	ds_read_b128 v[50:53], v76 offset:8192
	ds_read_b128 v[62:65], v77 offset:8192
	s_nop 8
	v_max_f32_e32 v18, v18, v18
	v_max_f32_e32 v19, v19, v19
	v_max_f32_e32 v18, 0, v18
	v_max_f32_e32 v20, v20, v20
	v_max_f32_e32 v19, 0, v19
	v_fma_f32 v18, v174, v18, 0
	v_max_f32_e32 v21, v21, v21
	v_max_f32_e32 v20, 0, v20
	v_fmac_f32_e32 v18, v173, v19
	v_max_f32_e32 v22, v22, v22
	v_max_f32_e32 v21, 0, v21
	v_fmac_f32_e32 v18, v172, v20
	v_max_f32_e32 v23, v23, v23
	v_max_f32_e32 v22, 0, v22
	v_fmac_f32_e32 v18, v171, v21
	v_max_f32_e32 v24, v24, v24
	v_max_f32_e32 v23, 0, v23
	v_fmac_f32_e32 v18, v170, v22
	v_max_f32_e32 v25, v25, v25
	v_max_f32_e32 v24, 0, v24
	v_fmac_f32_e32 v18, v169, v23
	v_max_f32_e32 v26, v26, v26
	v_max_f32_e32 v25, 0, v25
	v_fmac_f32_e32 v18, v168, v24
	v_max_f32_e32 v27, v27, v27
	v_max_f32_e32 v26, 0, v26
	v_fmac_f32_e32 v18, v167, v25
	v_max_f32_e32 v28, v28, v28
	v_max_f32_e32 v27, 0, v27
	v_fmac_f32_e32 v18, v166, v26
	v_max_f32_e32 v29, v29, v29
	v_max_f32_e32 v28, 0, v28
	v_fmac_f32_e32 v18, v165, v27
	v_max_f32_e32 v30, v30, v30
	v_max_f32_e32 v29, 0, v29
	v_fmac_f32_e32 v18, v164, v28
	v_max_f32_e32 v31, v31, v31
	v_max_f32_e32 v30, 0, v30
	v_fmac_f32_e32 v18, v163, v29
	v_fmac_f32_e32 v18, v162, v30
	v_max_f32_e32 v19, 0, v31
	v_fmac_f32_e32 v18, v161, v19
	v_max_f32_e32 v19, v32, v32
	v_max_f32_e32 v19, 0, v19
	v_fmac_f32_e32 v18, v160, v19
	v_max_f32_e32 v19, v33, v33
	v_max_f32_e32 v19, 0, v19
	v_fmac_f32_e32 v18, v89, v19
	v_not_b32_e32 v19, v18
	v_or_b32_e32 v20, 0x80000000, v18
	v_cmp_gt_i32_e32 vcc, 0, v18
	s_nop 1
	v_cndmask_b32_e32 v18, v20, v19, vcc
	v_cmp_le_u32_e32 vcc, v100, v87
	s_nop 1
	v_cndmask_b32_e32 v181, 0, v18, vcc
.LBB0_421:
	s_or_b64 exec, exec, s[74:75]
	s_movk_i32 s2, 0xbf
	v_cmp_lt_u32_e32 vcc, s2, v177
	v_mov_b32_e32 v182, 0
	s_and_saveexec_b64 s[74:75], vcc
	s_cbranch_execz .LBB0_425
	s_movk_i32 s2, 0xdf
	s_waitcnt lgkmcnt(0)
	v_cmp_lt_u32_e32 vcc, s2, v177
	s_and_saveexec_b64 s[82:83], vcc
	s_cbranch_execz .LBB0_424
	s_nop 0
	global_load_lds_dwordx4 v72, s[100:101]
	s_add_u32 m0, m0, 0x400
	s_add_u32 s100, s100, 0x1a000
	s_addc_u32 s101, s101, 0
	s_nop 0
	global_load_lds_dwordx4 v73, s[100:101]
	s_add_u32 m0, m0, 0x400
	s_add_u32 s100, s100, 0x1a000
	s_addc_u32 s101, s101, 0
	s_nop 0
	global_load_lds_dwordx4 v72, s[100:101]
	s_add_u32 m0, m0, 0x400
	s_add_u32 s100, s100, 0x1a000
	s_addc_u32 s101, s101, 0
	s_nop 0
	global_load_lds_dwordx4 v73, s[100:101]
	s_add_u32 m0, m0, 0x400
	s_add_u32 s100, s100, 0x1a000
	s_addc_u32 s101, s101, 0
.LBB0_424:
	s_or_b64 exec, exec, s[82:83]
	v_mfma_f32_32x32x16_bf16 v[18:33], v[38:41], v[58:61], 0
	v_mfma_f32_32x32x16_bf16 v[18:33], v[46:49], v[54:57], v[18:33]
	v_mfma_f32_32x32x16_bf16 v[18:33], v[34:37], v[50:53], v[18:33]
	v_mfma_f32_32x32x16_bf16 v[18:33], v[42:45], v[62:65], v[18:33]
	s_waitcnt vmcnt(12)
	ds_read_b128 v[58:61], v74 offset:12288
	ds_read_b128 v[54:57], v75 offset:12288
	ds_read_b128 v[50:53], v76 offset:12288
	ds_read_b128 v[62:65], v77 offset:12288
	s_nop 8
	v_max_f32_e32 v18, v18, v18
	v_max_f32_e32 v19, v19, v19
	v_max_f32_e32 v18, 0, v18
	v_max_f32_e32 v20, v20, v20
	v_max_f32_e32 v19, 0, v19
	v_fma_f32 v18, v174, v18, 0
	v_max_f32_e32 v21, v21, v21
	v_max_f32_e32 v20, 0, v20
	v_fmac_f32_e32 v18, v173, v19
	v_max_f32_e32 v22, v22, v22
	v_max_f32_e32 v21, 0, v21
	v_fmac_f32_e32 v18, v172, v20
	v_max_f32_e32 v23, v23, v23
	v_max_f32_e32 v22, 0, v22
	v_fmac_f32_e32 v18, v171, v21
	v_max_f32_e32 v24, v24, v24
	v_max_f32_e32 v23, 0, v23
	v_fmac_f32_e32 v18, v170, v22
	v_max_f32_e32 v25, v25, v25
	v_max_f32_e32 v24, 0, v24
	v_fmac_f32_e32 v18, v169, v23
	v_max_f32_e32 v26, v26, v26
	v_max_f32_e32 v25, 0, v25
	v_fmac_f32_e32 v18, v168, v24
	v_max_f32_e32 v27, v27, v27
	v_max_f32_e32 v26, 0, v26
	v_fmac_f32_e32 v18, v167, v25
	v_max_f32_e32 v28, v28, v28
	v_max_f32_e32 v27, 0, v27
	v_fmac_f32_e32 v18, v166, v26
	v_max_f32_e32 v29, v29, v29
	v_max_f32_e32 v28, 0, v28
	v_fmac_f32_e32 v18, v165, v27
	v_max_f32_e32 v30, v30, v30
	v_max_f32_e32 v29, 0, v29
	v_fmac_f32_e32 v18, v164, v28
	v_max_f32_e32 v31, v31, v31
	v_max_f32_e32 v30, 0, v30
	v_fmac_f32_e32 v18, v163, v29
	v_fmac_f32_e32 v18, v162, v30
	v_max_f32_e32 v19, 0, v31
	v_fmac_f32_e32 v18, v161, v19
	v_max_f32_e32 v19, v32, v32
	v_max_f32_e32 v19, 0, v19
	v_fmac_f32_e32 v18, v160, v19
	v_max_f32_e32 v19, v33, v33
	v_max_f32_e32 v19, 0, v19
	v_fmac_f32_e32 v18, v89, v19
	v_not_b32_e32 v19, v18
	v_or_b32_e32 v20, 0x80000000, v18
	v_cmp_gt_i32_e32 vcc, 0, v18
	s_nop 1
	v_cndmask_b32_e32 v18, v20, v19, vcc
	v_cmp_le_u32_e32 vcc, v101, v87
	s_nop 1
	v_cndmask_b32_e32 v182, 0, v18, vcc
.LBB0_425:
	s_or_b64 exec, exec, s[74:75]
	s_movk_i32 s2, 0xdf
	v_cmp_lt_u32_e32 vcc, s2, v177
	v_mov_b32_e32 v183, 0
	s_and_saveexec_b64 s[74:75], vcc
	s_cbranch_execz .LBB0_429
	s_movk_i32 s2, 0xff
	s_waitcnt lgkmcnt(0)
	v_cmp_lt_u32_e32 vcc, s2, v177
	s_and_saveexec_b64 s[82:83], vcc
	s_cbranch_execz .LBB0_428
	s_nop 0
	global_load_lds_dwordx4 v72, s[100:101]
	s_add_u32 m0, m0, 0x400
	s_add_u32 s100, s100, 0x1a000
	s_addc_u32 s101, s101, 0
	s_nop 0
	global_load_lds_dwordx4 v73, s[100:101]
	s_add_u32 m0, m0, 0x400
	s_add_u32 s100, s100, 0x1a000
	s_addc_u32 s101, s101, 0
	s_nop 0
	global_load_lds_dwordx4 v72, s[100:101]
	s_add_u32 m0, m0, 0x400
	s_add_u32 s100, s100, 0x1a000
	s_addc_u32 s101, s101, 0
	s_nop 0
	global_load_lds_dwordx4 v73, s[100:101]
	s_sub_u32 m0, m0, 0x3c00
	s_add_u32 s100, s100, 0x1a000
	s_addc_u32 s101, s101, 0
.LBB0_428:
	s_or_b64 exec, exec, s[82:83]
	v_mfma_f32_32x32x16_bf16 v[18:33], v[38:41], v[58:61], 0
	v_mfma_f32_32x32x16_bf16 v[18:33], v[46:49], v[54:57], v[18:33]
	v_mfma_f32_32x32x16_bf16 v[18:33], v[34:37], v[50:53], v[18:33]
	v_mfma_f32_32x32x16_bf16 v[18:33], v[42:45], v[62:65], v[18:33]
	s_waitcnt vmcnt(12)
	ds_read_b128 v[58:61], v74 offset:0
	ds_read_b128 v[54:57], v75 offset:0
	ds_read_b128 v[50:53], v76 offset:0
	ds_read_b128 v[62:65], v77 offset:0
	s_nop 8
	v_max_f32_e32 v18, v18, v18
	v_max_f32_e32 v19, v19, v19
	v_max_f32_e32 v18, 0, v18
	v_max_f32_e32 v20, v20, v20
	v_max_f32_e32 v19, 0, v19
	v_fma_f32 v18, v174, v18, 0
	v_max_f32_e32 v21, v21, v21
	v_max_f32_e32 v20, 0, v20
	v_fmac_f32_e32 v18, v173, v19
	v_max_f32_e32 v22, v22, v22
	v_max_f32_e32 v21, 0, v21
	v_fmac_f32_e32 v18, v172, v20
	v_max_f32_e32 v23, v23, v23
	v_max_f32_e32 v22, 0, v22
	v_fmac_f32_e32 v18, v171, v21
	v_max_f32_e32 v24, v24, v24
	v_max_f32_e32 v23, 0, v23
	v_fmac_f32_e32 v18, v170, v22
	v_max_f32_e32 v25, v25, v25
	v_max_f32_e32 v24, 0, v24
	v_fmac_f32_e32 v18, v169, v23
	v_max_f32_e32 v26, v26, v26
	v_max_f32_e32 v25, 0, v25
	v_fmac_f32_e32 v18, v168, v24
	v_max_f32_e32 v27, v27, v27
	v_max_f32_e32 v26, 0, v26
	v_fmac_f32_e32 v18, v167, v25
	v_max_f32_e32 v28, v28, v28
	v_max_f32_e32 v27, 0, v27
	v_fmac_f32_e32 v18, v166, v26
	v_max_f32_e32 v29, v29, v29
	v_max_f32_e32 v28, 0, v28
	v_fmac_f32_e32 v18, v165, v27
	v_max_f32_e32 v30, v30, v30
	v_max_f32_e32 v29, 0, v29
	v_fmac_f32_e32 v18, v164, v28
	v_max_f32_e32 v31, v31, v31
	v_max_f32_e32 v30, 0, v30
	v_fmac_f32_e32 v18, v163, v29
	v_fmac_f32_e32 v18, v162, v30
	v_max_f32_e32 v19, 0, v31
	v_fmac_f32_e32 v18, v161, v19
	v_max_f32_e32 v19, v32, v32
	v_max_f32_e32 v19, 0, v19
	v_fmac_f32_e32 v18, v160, v19
	v_max_f32_e32 v19, v33, v33
	v_max_f32_e32 v19, 0, v19
	v_fmac_f32_e32 v18, v89, v19
	v_not_b32_e32 v19, v18
	v_or_b32_e32 v20, 0x80000000, v18
	v_cmp_gt_i32_e32 vcc, 0, v18
	s_nop 1
	v_cndmask_b32_e32 v18, v20, v19, vcc
	v_cmp_le_u32_e32 vcc, v102, v87
	s_nop 1
	v_cndmask_b32_e32 v183, 0, v18, vcc
.LBB0_429:
	s_or_b64 exec, exec, s[74:75]
	s_movk_i32 s2, 0xff
	v_cmp_gt_u32_e64 s[74:75], s33, v177
	v_cmp_lt_u32_e32 vcc, s2, v177
	v_mov_b32_e32 v184, 0
	s_and_saveexec_b64 s[82:83], vcc
	s_cbranch_execz .LBB0_433
	s_movk_i32 s2, 0x11f
	s_waitcnt lgkmcnt(0)
	v_cmp_lt_u32_e32 vcc, s2, v177
	s_and_saveexec_b64 s[84:85], vcc
	s_cbranch_execz .LBB0_432
	s_nop 0
	global_load_lds_dwordx4 v72, s[100:101]
	s_add_u32 m0, m0, 0x400
	s_add_u32 s100, s100, 0x1a000
	s_addc_u32 s101, s101, 0
	s_nop 0
	global_load_lds_dwordx4 v73, s[100:101]
	s_add_u32 m0, m0, 0x400
	s_add_u32 s100, s100, 0x1a000
	s_addc_u32 s101, s101, 0
	s_nop 0
	global_load_lds_dwordx4 v72, s[100:101]
	s_add_u32 m0, m0, 0x400
	s_add_u32 s100, s100, 0x1a000
	s_addc_u32 s101, s101, 0
	s_nop 0
	global_load_lds_dwordx4 v73, s[100:101]
	s_add_u32 m0, m0, 0x400
	s_add_u32 s100, s100, 0x1a000
	s_addc_u32 s101, s101, 0
.LBB0_432:
	s_or_b64 exec, exec, s[84:85]
	v_mfma_f32_32x32x16_bf16 v[18:33], v[38:41], v[58:61], 0
	v_mfma_f32_32x32x16_bf16 v[18:33], v[46:49], v[54:57], v[18:33]
	v_mfma_f32_32x32x16_bf16 v[18:33], v[34:37], v[50:53], v[18:33]
	v_mfma_f32_32x32x16_bf16 v[18:33], v[42:45], v[62:65], v[18:33]
	s_waitcnt vmcnt(12)
	ds_read_b128 v[58:61], v74 offset:4096
	ds_read_b128 v[54:57], v75 offset:4096
	ds_read_b128 v[50:53], v76 offset:4096
	ds_read_b128 v[62:65], v77 offset:4096
	s_nop 8
	v_max_f32_e32 v18, v18, v18
	v_max_f32_e32 v19, v19, v19
	v_max_f32_e32 v18, 0, v18
	v_max_f32_e32 v20, v20, v20
	v_max_f32_e32 v19, 0, v19
	v_fma_f32 v18, v174, v18, 0
	v_max_f32_e32 v21, v21, v21
	v_max_f32_e32 v20, 0, v20
	v_fmac_f32_e32 v18, v173, v19
	v_max_f32_e32 v22, v22, v22
	v_max_f32_e32 v21, 0, v21
	v_fmac_f32_e32 v18, v172, v20
	v_max_f32_e32 v23, v23, v23
	v_max_f32_e32 v22, 0, v22
	v_fmac_f32_e32 v18, v171, v21
	v_max_f32_e32 v24, v24, v24
	v_max_f32_e32 v23, 0, v23
	v_fmac_f32_e32 v18, v170, v22
	v_max_f32_e32 v25, v25, v25
	v_max_f32_e32 v24, 0, v24
	v_fmac_f32_e32 v18, v169, v23
	v_max_f32_e32 v26, v26, v26
	v_max_f32_e32 v25, 0, v25
	v_fmac_f32_e32 v18, v168, v24
	v_max_f32_e32 v27, v27, v27
	v_max_f32_e32 v26, 0, v26
	v_fmac_f32_e32 v18, v167, v25
	v_max_f32_e32 v28, v28, v28
	v_max_f32_e32 v27, 0, v27
	v_fmac_f32_e32 v18, v166, v26
	v_max_f32_e32 v29, v29, v29
	v_max_f32_e32 v28, 0, v28
	v_fmac_f32_e32 v18, v165, v27
	v_max_f32_e32 v30, v30, v30
	v_max_f32_e32 v29, 0, v29
	v_fmac_f32_e32 v18, v164, v28
	v_max_f32_e32 v31, v31, v31
	v_max_f32_e32 v30, 0, v30
	v_fmac_f32_e32 v18, v163, v29
	v_fmac_f32_e32 v18, v162, v30
	v_max_f32_e32 v19, 0, v31
	v_fmac_f32_e32 v18, v161, v19
	v_max_f32_e32 v19, v32, v32
	v_max_f32_e32 v19, 0, v19
	v_fmac_f32_e32 v18, v160, v19
	v_max_f32_e32 v19, v33, v33
	v_max_f32_e32 v19, 0, v19
	v_fmac_f32_e32 v18, v89, v19
	v_not_b32_e32 v19, v18
	v_or_b32_e32 v20, 0x80000000, v18
	v_cmp_gt_i32_e32 vcc, 0, v18
	s_nop 1
	v_cndmask_b32_e32 v18, v20, v19, vcc
	v_cmp_le_u32_e32 vcc, v103, v87
	s_nop 1
	v_cndmask_b32_e32 v184, 0, v18, vcc
.LBB0_433:
	s_or_b64 exec, exec, s[82:83]
	s_movk_i32 s2, 0x11f
	v_cmp_lt_u32_e32 vcc, s2, v177
	v_mov_b32_e32 v185, 0
	s_and_saveexec_b64 s[82:83], vcc
	s_cbranch_execz .LBB0_437
	s_movk_i32 s2, 0x13f
	s_waitcnt lgkmcnt(0)
	v_cmp_lt_u32_e32 vcc, s2, v177
	s_and_saveexec_b64 s[84:85], vcc
	s_cbranch_execz .LBB0_436
	s_nop 0
	global_load_lds_dwordx4 v72, s[100:101]
	s_add_u32 m0, m0, 0x400
	s_add_u32 s100, s100, 0x1a000
	s_addc_u32 s101, s101, 0
	s_nop 0
	global_load_lds_dwordx4 v73, s[100:101]
	s_add_u32 m0, m0, 0x400
	s_add_u32 s100, s100, 0x1a000
	s_addc_u32 s101, s101, 0
	s_nop 0
	global_load_lds_dwordx4 v72, s[100:101]
	s_add_u32 m0, m0, 0x400
	s_add_u32 s100, s100, 0x1a000
	s_addc_u32 s101, s101, 0
	s_nop 0
	global_load_lds_dwordx4 v73, s[100:101]
	s_add_u32 m0, m0, 0x400
	s_add_u32 s100, s100, 0x1a000
	s_addc_u32 s101, s101, 0
.LBB0_436:
	s_or_b64 exec, exec, s[84:85]
	v_mfma_f32_32x32x16_bf16 v[18:33], v[38:41], v[58:61], 0
	v_mfma_f32_32x32x16_bf16 v[18:33], v[46:49], v[54:57], v[18:33]
	v_mfma_f32_32x32x16_bf16 v[18:33], v[34:37], v[50:53], v[18:33]
	v_mfma_f32_32x32x16_bf16 v[18:33], v[42:45], v[62:65], v[18:33]
	s_waitcnt vmcnt(12)
	ds_read_b128 v[58:61], v74 offset:8192
	ds_read_b128 v[54:57], v75 offset:8192
	ds_read_b128 v[50:53], v76 offset:8192
	ds_read_b128 v[62:65], v77 offset:8192
	s_nop 8
	v_max_f32_e32 v18, v18, v18
	v_max_f32_e32 v19, v19, v19
	v_max_f32_e32 v18, 0, v18
	v_max_f32_e32 v20, v20, v20
	v_max_f32_e32 v19, 0, v19
	v_fma_f32 v18, v174, v18, 0
	v_max_f32_e32 v21, v21, v21
	v_max_f32_e32 v20, 0, v20
	v_fmac_f32_e32 v18, v173, v19
	v_max_f32_e32 v22, v22, v22
	v_max_f32_e32 v21, 0, v21
	v_fmac_f32_e32 v18, v172, v20
	v_max_f32_e32 v23, v23, v23
	v_max_f32_e32 v22, 0, v22
	v_fmac_f32_e32 v18, v171, v21
	v_max_f32_e32 v24, v24, v24
	v_max_f32_e32 v23, 0, v23
	v_fmac_f32_e32 v18, v170, v22
	v_max_f32_e32 v25, v25, v25
	v_max_f32_e32 v24, 0, v24
	v_fmac_f32_e32 v18, v169, v23
	v_max_f32_e32 v26, v26, v26
	v_max_f32_e32 v25, 0, v25
	v_fmac_f32_e32 v18, v168, v24
	v_max_f32_e32 v27, v27, v27
	v_max_f32_e32 v26, 0, v26
	v_fmac_f32_e32 v18, v167, v25
	v_max_f32_e32 v28, v28, v28
	v_max_f32_e32 v27, 0, v27
	v_fmac_f32_e32 v18, v166, v26
	v_max_f32_e32 v29, v29, v29
	v_max_f32_e32 v28, 0, v28
	v_fmac_f32_e32 v18, v165, v27
	v_max_f32_e32 v30, v30, v30
	v_max_f32_e32 v29, 0, v29
	v_fmac_f32_e32 v18, v164, v28
	v_max_f32_e32 v31, v31, v31
	v_max_f32_e32 v30, 0, v30
	v_fmac_f32_e32 v18, v163, v29
	v_fmac_f32_e32 v18, v162, v30
	v_max_f32_e32 v19, 0, v31
	v_fmac_f32_e32 v18, v161, v19
	v_max_f32_e32 v19, v32, v32
	v_max_f32_e32 v19, 0, v19
	v_fmac_f32_e32 v18, v160, v19
	v_max_f32_e32 v19, v33, v33
	v_max_f32_e32 v19, 0, v19
	v_fmac_f32_e32 v18, v89, v19
	v_not_b32_e32 v19, v18
	v_or_b32_e32 v20, 0x80000000, v18
	v_cmp_gt_i32_e32 vcc, 0, v18
	s_nop 1
	v_cndmask_b32_e32 v18, v20, v19, vcc
	v_cmp_le_u32_e32 vcc, v104, v87
	s_nop 1
	v_cndmask_b32_e32 v185, 0, v18, vcc
.LBB0_437:
	s_or_b64 exec, exec, s[82:83]
	s_movk_i32 s2, 0x13f
	v_cmp_lt_u32_e32 vcc, s2, v177
	v_mov_b32_e32 v186, 0
	s_and_saveexec_b64 s[82:83], vcc
	s_cbranch_execz .LBB0_441
	s_movk_i32 s2, 0x15f
	s_waitcnt lgkmcnt(0)
	v_cmp_lt_u32_e32 vcc, s2, v177
	s_and_saveexec_b64 s[84:85], vcc
	s_cbranch_execz .LBB0_440
	s_nop 0
	global_load_lds_dwordx4 v72, s[100:101]
	s_add_u32 m0, m0, 0x400
	s_add_u32 s100, s100, 0x1a000
	s_addc_u32 s101, s101, 0
	s_nop 0
	global_load_lds_dwordx4 v73, s[100:101]
	s_add_u32 m0, m0, 0x400
	s_add_u32 s100, s100, 0x1a000
	s_addc_u32 s101, s101, 0
	s_nop 0
	global_load_lds_dwordx4 v72, s[100:101]
	s_add_u32 m0, m0, 0x400
	s_add_u32 s100, s100, 0x1a000
	s_addc_u32 s101, s101, 0
	s_nop 0
	global_load_lds_dwordx4 v73, s[100:101]
	s_add_u32 m0, m0, 0x400
	s_add_u32 s100, s100, 0x1a000
	s_addc_u32 s101, s101, 0
.LBB0_440:
	s_or_b64 exec, exec, s[84:85]
	v_mfma_f32_32x32x16_bf16 v[18:33], v[38:41], v[58:61], 0
	v_mfma_f32_32x32x16_bf16 v[18:33], v[46:49], v[54:57], v[18:33]
	v_mfma_f32_32x32x16_bf16 v[18:33], v[34:37], v[50:53], v[18:33]
	v_mfma_f32_32x32x16_bf16 v[18:33], v[42:45], v[62:65], v[18:33]
	s_waitcnt vmcnt(12)
	ds_read_b128 v[58:61], v74 offset:12288
	ds_read_b128 v[54:57], v75 offset:12288
	ds_read_b128 v[50:53], v76 offset:12288
	ds_read_b128 v[62:65], v77 offset:12288
	s_nop 8
	v_max_f32_e32 v18, v18, v18
	v_max_f32_e32 v19, v19, v19
	v_max_f32_e32 v18, 0, v18
	v_max_f32_e32 v20, v20, v20
	v_max_f32_e32 v19, 0, v19
	v_fma_f32 v18, v174, v18, 0
	v_max_f32_e32 v21, v21, v21
	v_max_f32_e32 v20, 0, v20
	v_fmac_f32_e32 v18, v173, v19
	v_max_f32_e32 v22, v22, v22
	v_max_f32_e32 v21, 0, v21
	v_fmac_f32_e32 v18, v172, v20
	v_max_f32_e32 v23, v23, v23
	v_max_f32_e32 v22, 0, v22
	v_fmac_f32_e32 v18, v171, v21
	v_max_f32_e32 v24, v24, v24
	v_max_f32_e32 v23, 0, v23
	v_fmac_f32_e32 v18, v170, v22
	v_max_f32_e32 v25, v25, v25
	v_max_f32_e32 v24, 0, v24
	v_fmac_f32_e32 v18, v169, v23
	v_max_f32_e32 v26, v26, v26
	v_max_f32_e32 v25, 0, v25
	v_fmac_f32_e32 v18, v168, v24
	v_max_f32_e32 v27, v27, v27
	v_max_f32_e32 v26, 0, v26
	v_fmac_f32_e32 v18, v167, v25
	v_max_f32_e32 v28, v28, v28
	v_max_f32_e32 v27, 0, v27
	v_fmac_f32_e32 v18, v166, v26
	v_max_f32_e32 v29, v29, v29
	v_max_f32_e32 v28, 0, v28
	v_fmac_f32_e32 v18, v165, v27
	v_max_f32_e32 v30, v30, v30
	v_max_f32_e32 v29, 0, v29
	v_fmac_f32_e32 v18, v164, v28
	v_max_f32_e32 v31, v31, v31
	v_max_f32_e32 v30, 0, v30
	v_fmac_f32_e32 v18, v163, v29
	v_fmac_f32_e32 v18, v162, v30
	v_max_f32_e32 v19, 0, v31
	v_fmac_f32_e32 v18, v161, v19
	v_max_f32_e32 v19, v32, v32
	v_max_f32_e32 v19, 0, v19
	v_fmac_f32_e32 v18, v160, v19
	v_max_f32_e32 v19, v33, v33
	v_max_f32_e32 v19, 0, v19
	v_fmac_f32_e32 v18, v89, v19
	v_not_b32_e32 v19, v18
	v_or_b32_e32 v20, 0x80000000, v18
	v_cmp_gt_i32_e32 vcc, 0, v18
	s_nop 1
	v_cndmask_b32_e32 v18, v20, v19, vcc
	v_cmp_le_u32_e32 vcc, v105, v87
	s_nop 1
	v_cndmask_b32_e32 v186, 0, v18, vcc
.LBB0_441:
	s_or_b64 exec, exec, s[82:83]
	s_movk_i32 s2, 0x15f
	v_cmp_lt_u32_e32 vcc, s2, v177
	v_mov_b32_e32 v187, 0
	s_and_saveexec_b64 s[82:83], vcc
	s_cbranch_execz .LBB0_445
	s_movk_i32 s2, 0x17f
	s_waitcnt lgkmcnt(0)
	v_cmp_lt_u32_e32 vcc, s2, v177
	s_and_saveexec_b64 s[84:85], vcc
	s_cbranch_execz .LBB0_444
	s_nop 0
	global_load_lds_dwordx4 v72, s[100:101]
	s_add_u32 m0, m0, 0x400
	s_add_u32 s100, s100, 0x1a000
	s_addc_u32 s101, s101, 0
	s_nop 0
	global_load_lds_dwordx4 v73, s[100:101]
	s_add_u32 m0, m0, 0x400
	s_add_u32 s100, s100, 0x1a000
	s_addc_u32 s101, s101, 0
	s_nop 0
	global_load_lds_dwordx4 v72, s[100:101]
	s_add_u32 m0, m0, 0x400
	s_add_u32 s100, s100, 0x1a000
	s_addc_u32 s101, s101, 0
	s_nop 0
	global_load_lds_dwordx4 v73, s[100:101]
	s_sub_u32 m0, m0, 0x3c00
	s_add_u32 s100, s100, 0x1a000
	s_addc_u32 s101, s101, 0
.LBB0_444:
	s_or_b64 exec, exec, s[84:85]
	v_mfma_f32_32x32x16_bf16 v[18:33], v[38:41], v[58:61], 0
	v_mfma_f32_32x32x16_bf16 v[18:33], v[46:49], v[54:57], v[18:33]
	v_mfma_f32_32x32x16_bf16 v[18:33], v[34:37], v[50:53], v[18:33]
	v_mfma_f32_32x32x16_bf16 v[18:33], v[42:45], v[62:65], v[18:33]
	s_waitcnt vmcnt(12)
	ds_read_b128 v[58:61], v74 offset:0
	ds_read_b128 v[54:57], v75 offset:0
	ds_read_b128 v[50:53], v76 offset:0
	ds_read_b128 v[62:65], v77 offset:0
	s_nop 8
	v_max_f32_e32 v18, v18, v18
	v_max_f32_e32 v19, v19, v19
	v_max_f32_e32 v18, 0, v18
	v_max_f32_e32 v20, v20, v20
	v_max_f32_e32 v19, 0, v19
	v_fma_f32 v18, v174, v18, 0
	v_max_f32_e32 v21, v21, v21
	v_max_f32_e32 v20, 0, v20
	v_fmac_f32_e32 v18, v173, v19
	v_max_f32_e32 v22, v22, v22
	v_max_f32_e32 v21, 0, v21
	v_fmac_f32_e32 v18, v172, v20
	v_max_f32_e32 v23, v23, v23
	v_max_f32_e32 v22, 0, v22
	v_fmac_f32_e32 v18, v171, v21
	v_max_f32_e32 v24, v24, v24
	v_max_f32_e32 v23, 0, v23
	v_fmac_f32_e32 v18, v170, v22
	v_max_f32_e32 v25, v25, v25
	v_max_f32_e32 v24, 0, v24
	v_fmac_f32_e32 v18, v169, v23
	v_max_f32_e32 v26, v26, v26
	v_max_f32_e32 v25, 0, v25
	v_fmac_f32_e32 v18, v168, v24
	v_max_f32_e32 v27, v27, v27
	v_max_f32_e32 v26, 0, v26
	v_fmac_f32_e32 v18, v167, v25
	v_max_f32_e32 v28, v28, v28
	v_max_f32_e32 v27, 0, v27
	v_fmac_f32_e32 v18, v166, v26
	v_max_f32_e32 v29, v29, v29
	v_max_f32_e32 v28, 0, v28
	v_fmac_f32_e32 v18, v165, v27
	v_max_f32_e32 v30, v30, v30
	v_max_f32_e32 v29, 0, v29
	v_fmac_f32_e32 v18, v164, v28
	v_max_f32_e32 v31, v31, v31
	v_max_f32_e32 v30, 0, v30
	v_fmac_f32_e32 v18, v163, v29
	v_fmac_f32_e32 v18, v162, v30
	v_max_f32_e32 v19, 0, v31
	v_fmac_f32_e32 v18, v161, v19
	v_max_f32_e32 v19, v32, v32
	v_max_f32_e32 v19, 0, v19
	v_fmac_f32_e32 v18, v160, v19
	v_max_f32_e32 v19, v33, v33
	v_max_f32_e32 v19, 0, v19
	v_fmac_f32_e32 v18, v89, v19
	v_not_b32_e32 v19, v18
	v_or_b32_e32 v20, 0x80000000, v18
	v_cmp_gt_i32_e32 vcc, 0, v18
	s_nop 1
	v_cndmask_b32_e32 v18, v20, v19, vcc
	v_cmp_le_u32_e32 vcc, v106, v87
	s_nop 1
	v_cndmask_b32_e32 v187, 0, v18, vcc
.LBB0_445:
	s_or_b64 exec, exec, s[82:83]
	s_movk_i32 s2, 0x17f
	v_cmp_lt_u32_e32 vcc, s2, v177
	v_mov_b32_e32 v188, 0
	s_and_saveexec_b64 s[82:83], vcc
	s_cbranch_execz .LBB0_449
	s_movk_i32 s2, 0x19f
	s_waitcnt lgkmcnt(0)
	v_cmp_lt_u32_e32 vcc, s2, v177
	s_and_saveexec_b64 s[84:85], vcc
	s_cbranch_execz .LBB0_448
	s_nop 0
	global_load_lds_dwordx4 v72, s[100:101]
	s_add_u32 m0, m0, 0x400
	s_add_u32 s100, s100, 0x1a000
	s_addc_u32 s101, s101, 0
	s_nop 0
	global_load_lds_dwordx4 v73, s[100:101]
	s_add_u32 m0, m0, 0x400
	s_add_u32 s100, s100, 0x1a000
	s_addc_u32 s101, s101, 0
	s_nop 0
	global_load_lds_dwordx4 v72, s[100:101]
	s_add_u32 m0, m0, 0x400
	s_add_u32 s100, s100, 0x1a000
	s_addc_u32 s101, s101, 0
	s_nop 0
	global_load_lds_dwordx4 v73, s[100:101]
	s_add_u32 m0, m0, 0x400
	s_add_u32 s100, s100, 0x1a000
	s_addc_u32 s101, s101, 0
.LBB0_448:
	s_or_b64 exec, exec, s[84:85]
	v_mfma_f32_32x32x16_bf16 v[18:33], v[38:41], v[58:61], 0
	v_mfma_f32_32x32x16_bf16 v[18:33], v[46:49], v[54:57], v[18:33]
	v_mfma_f32_32x32x16_bf16 v[18:33], v[34:37], v[50:53], v[18:33]
	v_mfma_f32_32x32x16_bf16 v[18:33], v[42:45], v[62:65], v[18:33]
	s_waitcnt vmcnt(12)
	ds_read_b128 v[58:61], v74 offset:4096
	ds_read_b128 v[54:57], v75 offset:4096
	ds_read_b128 v[50:53], v76 offset:4096
	ds_read_b128 v[62:65], v77 offset:4096
	s_nop 8
	v_max_f32_e32 v18, v18, v18
	v_max_f32_e32 v19, v19, v19
	v_max_f32_e32 v18, 0, v18
	v_max_f32_e32 v20, v20, v20
	v_max_f32_e32 v19, 0, v19
	v_fma_f32 v18, v174, v18, 0
	v_max_f32_e32 v21, v21, v21
	v_max_f32_e32 v20, 0, v20
	v_fmac_f32_e32 v18, v173, v19
	v_max_f32_e32 v22, v22, v22
	v_max_f32_e32 v21, 0, v21
	v_fmac_f32_e32 v18, v172, v20
	v_max_f32_e32 v23, v23, v23
	v_max_f32_e32 v22, 0, v22
	v_fmac_f32_e32 v18, v171, v21
	v_max_f32_e32 v24, v24, v24
	v_max_f32_e32 v23, 0, v23
	v_fmac_f32_e32 v18, v170, v22
	v_max_f32_e32 v25, v25, v25
	v_max_f32_e32 v24, 0, v24
	v_fmac_f32_e32 v18, v169, v23
	v_max_f32_e32 v26, v26, v26
	v_max_f32_e32 v25, 0, v25
	v_fmac_f32_e32 v18, v168, v24
	v_max_f32_e32 v27, v27, v27
	v_max_f32_e32 v26, 0, v26
	v_fmac_f32_e32 v18, v167, v25
	v_max_f32_e32 v28, v28, v28
	v_max_f32_e32 v27, 0, v27
	v_fmac_f32_e32 v18, v166, v26
	v_max_f32_e32 v29, v29, v29
	v_max_f32_e32 v28, 0, v28
	v_fmac_f32_e32 v18, v165, v27
	v_max_f32_e32 v30, v30, v30
	v_max_f32_e32 v29, 0, v29
	v_fmac_f32_e32 v18, v164, v28
	v_max_f32_e32 v31, v31, v31
	v_max_f32_e32 v30, 0, v30
	v_fmac_f32_e32 v18, v163, v29
	v_fmac_f32_e32 v18, v162, v30
	v_max_f32_e32 v19, 0, v31
	v_fmac_f32_e32 v18, v161, v19
	v_max_f32_e32 v19, v32, v32
	v_max_f32_e32 v19, 0, v19
	v_fmac_f32_e32 v18, v160, v19
	v_max_f32_e32 v19, v33, v33
	v_max_f32_e32 v19, 0, v19
	v_fmac_f32_e32 v18, v89, v19
	v_not_b32_e32 v19, v18
	v_or_b32_e32 v20, 0x80000000, v18
	v_cmp_gt_i32_e32 vcc, 0, v18
	s_nop 1
	v_cndmask_b32_e32 v18, v20, v19, vcc
	v_cmp_le_u32_e32 vcc, v107, v87
	s_nop 1
	v_cndmask_b32_e32 v188, 0, v18, vcc
.LBB0_449:
	s_or_b64 exec, exec, s[82:83]
	s_movk_i32 s2, 0x19f
	v_cmp_lt_u32_e32 vcc, s2, v177
	v_mov_b32_e32 v189, 0
	s_and_saveexec_b64 s[82:83], vcc
	s_cbranch_execz .LBB0_453
	s_movk_i32 s2, 0x1bf
	s_waitcnt lgkmcnt(0)
	v_cmp_lt_u32_e32 vcc, s2, v177
	s_and_saveexec_b64 s[84:85], vcc
	s_cbranch_execz .LBB0_452
	s_nop 0
	global_load_lds_dwordx4 v72, s[100:101]
	s_add_u32 m0, m0, 0x400
	s_add_u32 s100, s100, 0x1a000
	s_addc_u32 s101, s101, 0
	s_nop 0
	global_load_lds_dwordx4 v73, s[100:101]
	s_add_u32 m0, m0, 0x400
	s_add_u32 s100, s100, 0x1a000
	s_addc_u32 s101, s101, 0
	s_nop 0
	global_load_lds_dwordx4 v72, s[100:101]
	s_add_u32 m0, m0, 0x400
	s_add_u32 s100, s100, 0x1a000
	s_addc_u32 s101, s101, 0
	s_nop 0
	global_load_lds_dwordx4 v73, s[100:101]
	s_add_u32 m0, m0, 0x400
	s_add_u32 s100, s100, 0x1a000
	s_addc_u32 s101, s101, 0
.LBB0_452:
	s_or_b64 exec, exec, s[84:85]
	v_mfma_f32_32x32x16_bf16 v[18:33], v[38:41], v[58:61], 0
	v_mfma_f32_32x32x16_bf16 v[18:33], v[46:49], v[54:57], v[18:33]
	v_mfma_f32_32x32x16_bf16 v[18:33], v[34:37], v[50:53], v[18:33]
	v_mfma_f32_32x32x16_bf16 v[18:33], v[42:45], v[62:65], v[18:33]
	s_waitcnt vmcnt(12)
	ds_read_b128 v[58:61], v74 offset:8192
	ds_read_b128 v[54:57], v75 offset:8192
	ds_read_b128 v[50:53], v76 offset:8192
	ds_read_b128 v[62:65], v77 offset:8192
	s_nop 8
	v_max_f32_e32 v18, v18, v18
	v_max_f32_e32 v19, v19, v19
	v_max_f32_e32 v18, 0, v18
	v_max_f32_e32 v20, v20, v20
	v_max_f32_e32 v19, 0, v19
	v_fma_f32 v18, v174, v18, 0
	v_max_f32_e32 v21, v21, v21
	v_max_f32_e32 v20, 0, v20
	v_fmac_f32_e32 v18, v173, v19
	v_max_f32_e32 v22, v22, v22
	v_max_f32_e32 v21, 0, v21
	v_fmac_f32_e32 v18, v172, v20
	v_max_f32_e32 v23, v23, v23
	v_max_f32_e32 v22, 0, v22
	v_fmac_f32_e32 v18, v171, v21
	v_max_f32_e32 v24, v24, v24
	v_max_f32_e32 v23, 0, v23
	v_fmac_f32_e32 v18, v170, v22
	v_max_f32_e32 v25, v25, v25
	v_max_f32_e32 v24, 0, v24
	v_fmac_f32_e32 v18, v169, v23
	v_max_f32_e32 v26, v26, v26
	v_max_f32_e32 v25, 0, v25
	v_fmac_f32_e32 v18, v168, v24
	v_max_f32_e32 v27, v27, v27
	v_max_f32_e32 v26, 0, v26
	v_fmac_f32_e32 v18, v167, v25
	v_max_f32_e32 v28, v28, v28
	v_max_f32_e32 v27, 0, v27
	v_fmac_f32_e32 v18, v166, v26
	v_max_f32_e32 v29, v29, v29
	v_max_f32_e32 v28, 0, v28
	v_fmac_f32_e32 v18, v165, v27
	v_max_f32_e32 v30, v30, v30
	v_max_f32_e32 v29, 0, v29
	v_fmac_f32_e32 v18, v164, v28
	v_max_f32_e32 v31, v31, v31
	v_max_f32_e32 v30, 0, v30
	v_fmac_f32_e32 v18, v163, v29
	v_fmac_f32_e32 v18, v162, v30
	v_max_f32_e32 v19, 0, v31
	v_fmac_f32_e32 v18, v161, v19
	v_max_f32_e32 v19, v32, v32
	v_max_f32_e32 v19, 0, v19
	v_fmac_f32_e32 v18, v160, v19
	v_max_f32_e32 v19, v33, v33
	v_max_f32_e32 v19, 0, v19
	v_fmac_f32_e32 v18, v89, v19
	v_not_b32_e32 v19, v18
	v_or_b32_e32 v20, 0x80000000, v18
	v_cmp_gt_i32_e32 vcc, 0, v18
	s_nop 1
	v_cndmask_b32_e32 v18, v20, v19, vcc
	v_cmp_le_u32_e32 vcc, v108, v87
	s_nop 1
	v_cndmask_b32_e32 v189, 0, v18, vcc
.LBB0_453:
	s_or_b64 exec, exec, s[82:83]
	s_movk_i32 s2, 0x1bf
	v_cmp_lt_u32_e32 vcc, s2, v177
	v_mov_b32_e32 v190, 0
	s_and_saveexec_b64 s[82:83], vcc
	s_cbranch_execz .LBB0_457
	s_movk_i32 s2, 0x1df
	s_waitcnt lgkmcnt(0)
	v_cmp_lt_u32_e32 vcc, s2, v177
	s_and_saveexec_b64 s[84:85], vcc
	s_cbranch_execz .LBB0_456
	s_nop 0
	global_load_lds_dwordx4 v72, s[100:101]
	s_add_u32 m0, m0, 0x400
	s_add_u32 s100, s100, 0x1a000
	s_addc_u32 s101, s101, 0
	s_nop 0
	global_load_lds_dwordx4 v73, s[100:101]
	s_add_u32 m0, m0, 0x400
	s_add_u32 s100, s100, 0x1a000
	s_addc_u32 s101, s101, 0
	s_nop 0
	global_load_lds_dwordx4 v72, s[100:101]
	s_add_u32 m0, m0, 0x400
	s_add_u32 s100, s100, 0x1a000
	s_addc_u32 s101, s101, 0
	s_nop 0
	global_load_lds_dwordx4 v73, s[100:101]
	s_add_u32 m0, m0, 0x400
	s_add_u32 s100, s100, 0x1a000
	s_addc_u32 s101, s101, 0
.LBB0_456:
	s_or_b64 exec, exec, s[84:85]
	v_mfma_f32_32x32x16_bf16 v[18:33], v[38:41], v[58:61], 0
	v_mfma_f32_32x32x16_bf16 v[18:33], v[46:49], v[54:57], v[18:33]
	v_mfma_f32_32x32x16_bf16 v[18:33], v[34:37], v[50:53], v[18:33]
	v_mfma_f32_32x32x16_bf16 v[18:33], v[42:45], v[62:65], v[18:33]
	s_waitcnt vmcnt(12)
	ds_read_b128 v[58:61], v74 offset:12288
	ds_read_b128 v[54:57], v75 offset:12288
	ds_read_b128 v[50:53], v76 offset:12288
	ds_read_b128 v[62:65], v77 offset:12288
	s_nop 8
	v_max_f32_e32 v18, v18, v18
	v_max_f32_e32 v19, v19, v19
	v_max_f32_e32 v18, 0, v18
	v_max_f32_e32 v20, v20, v20
	v_max_f32_e32 v19, 0, v19
	v_fma_f32 v18, v174, v18, 0
	v_max_f32_e32 v21, v21, v21
	v_max_f32_e32 v20, 0, v20
	v_fmac_f32_e32 v18, v173, v19
	v_max_f32_e32 v22, v22, v22
	v_max_f32_e32 v21, 0, v21
	v_fmac_f32_e32 v18, v172, v20
	v_max_f32_e32 v23, v23, v23
	v_max_f32_e32 v22, 0, v22
	v_fmac_f32_e32 v18, v171, v21
	v_max_f32_e32 v24, v24, v24
	v_max_f32_e32 v23, 0, v23
	v_fmac_f32_e32 v18, v170, v22
	v_max_f32_e32 v25, v25, v25
	v_max_f32_e32 v24, 0, v24
	v_fmac_f32_e32 v18, v169, v23
	v_max_f32_e32 v26, v26, v26
	v_max_f32_e32 v25, 0, v25
	v_fmac_f32_e32 v18, v168, v24
	v_max_f32_e32 v27, v27, v27
	v_max_f32_e32 v26, 0, v26
	v_fmac_f32_e32 v18, v167, v25
	v_max_f32_e32 v28, v28, v28
	v_max_f32_e32 v27, 0, v27
	v_fmac_f32_e32 v18, v166, v26
	v_max_f32_e32 v29, v29, v29
	v_max_f32_e32 v28, 0, v28
	v_fmac_f32_e32 v18, v165, v27
	v_max_f32_e32 v30, v30, v30
	v_max_f32_e32 v29, 0, v29
	v_fmac_f32_e32 v18, v164, v28
	v_max_f32_e32 v31, v31, v31
	v_max_f32_e32 v30, 0, v30
	v_fmac_f32_e32 v18, v163, v29
	v_fmac_f32_e32 v18, v162, v30
	v_max_f32_e32 v19, 0, v31
	v_fmac_f32_e32 v18, v161, v19
	v_max_f32_e32 v19, v32, v32
	v_max_f32_e32 v19, 0, v19
	v_fmac_f32_e32 v18, v160, v19
	v_max_f32_e32 v19, v33, v33
	v_max_f32_e32 v19, 0, v19
	v_fmac_f32_e32 v18, v89, v19
	v_not_b32_e32 v19, v18
	v_or_b32_e32 v20, 0x80000000, v18
	v_cmp_gt_i32_e32 vcc, 0, v18
	s_nop 1
	v_cndmask_b32_e32 v18, v20, v19, vcc
	v_cmp_le_u32_e32 vcc, v109, v87
	s_nop 1
	v_cndmask_b32_e32 v190, 0, v18, vcc
.LBB0_457:
	s_or_b64 exec, exec, s[82:83]
	s_movk_i32 s2, 0x1df
	v_cmp_lt_u32_e32 vcc, s2, v177
	v_mov_b32_e32 v191, 0
	s_and_saveexec_b64 s[82:83], vcc
	s_cbranch_execz .LBB0_461
	s_movk_i32 s2, 0x1ff
	s_waitcnt lgkmcnt(0)
	v_cmp_lt_u32_e32 vcc, s2, v177
	s_and_saveexec_b64 s[84:85], vcc
	s_cbranch_execz .LBB0_460
	s_nop 0
	global_load_lds_dwordx4 v72, s[100:101]
	s_add_u32 m0, m0, 0x400
	s_add_u32 s100, s100, 0x1a000
	s_addc_u32 s101, s101, 0
	s_nop 0
	global_load_lds_dwordx4 v73, s[100:101]
	s_add_u32 m0, m0, 0x400
	s_add_u32 s100, s100, 0x1a000
	s_addc_u32 s101, s101, 0
	s_nop 0
	global_load_lds_dwordx4 v72, s[100:101]
	s_add_u32 m0, m0, 0x400
	s_add_u32 s100, s100, 0x1a000
	s_addc_u32 s101, s101, 0
	s_nop 0
	global_load_lds_dwordx4 v73, s[100:101]
	s_sub_u32 m0, m0, 0x3c00
	s_add_u32 s100, s100, 0x1a000
	s_addc_u32 s101, s101, 0
.LBB0_460:
	s_or_b64 exec, exec, s[84:85]
	v_mfma_f32_32x32x16_bf16 v[18:33], v[38:41], v[58:61], 0
	v_mfma_f32_32x32x16_bf16 v[18:33], v[46:49], v[54:57], v[18:33]
	v_mfma_f32_32x32x16_bf16 v[18:33], v[34:37], v[50:53], v[18:33]
	v_mfma_f32_32x32x16_bf16 v[18:33], v[42:45], v[62:65], v[18:33]
	s_waitcnt vmcnt(12)
	ds_read_b128 v[58:61], v74 offset:0
	ds_read_b128 v[54:57], v75 offset:0
	ds_read_b128 v[50:53], v76 offset:0
	ds_read_b128 v[62:65], v77 offset:0
	s_nop 8
	v_max_f32_e32 v18, v18, v18
	v_max_f32_e32 v19, v19, v19
	v_max_f32_e32 v18, 0, v18
	v_max_f32_e32 v20, v20, v20
	v_max_f32_e32 v19, 0, v19
	v_fma_f32 v18, v174, v18, 0
	v_max_f32_e32 v21, v21, v21
	v_max_f32_e32 v20, 0, v20
	v_fmac_f32_e32 v18, v173, v19
	v_max_f32_e32 v22, v22, v22
	v_max_f32_e32 v21, 0, v21
	v_fmac_f32_e32 v18, v172, v20
	v_max_f32_e32 v23, v23, v23
	v_max_f32_e32 v22, 0, v22
	v_fmac_f32_e32 v18, v171, v21
	v_max_f32_e32 v24, v24, v24
	v_max_f32_e32 v23, 0, v23
	v_fmac_f32_e32 v18, v170, v22
	v_max_f32_e32 v25, v25, v25
	v_max_f32_e32 v24, 0, v24
	v_fmac_f32_e32 v18, v169, v23
	v_max_f32_e32 v26, v26, v26
	v_max_f32_e32 v25, 0, v25
	v_fmac_f32_e32 v18, v168, v24
	v_max_f32_e32 v27, v27, v27
	v_max_f32_e32 v26, 0, v26
	v_fmac_f32_e32 v18, v167, v25
	v_max_f32_e32 v28, v28, v28
	v_max_f32_e32 v27, 0, v27
	v_fmac_f32_e32 v18, v166, v26
	v_max_f32_e32 v29, v29, v29
	v_max_f32_e32 v28, 0, v28
	v_fmac_f32_e32 v18, v165, v27
	v_max_f32_e32 v30, v30, v30
	v_max_f32_e32 v29, 0, v29
	v_fmac_f32_e32 v18, v164, v28
	v_max_f32_e32 v31, v31, v31
	v_max_f32_e32 v30, 0, v30
	v_fmac_f32_e32 v18, v163, v29
	v_fmac_f32_e32 v18, v162, v30
	v_max_f32_e32 v19, 0, v31
	v_fmac_f32_e32 v18, v161, v19
	v_max_f32_e32 v19, v32, v32
	v_max_f32_e32 v19, 0, v19
	v_fmac_f32_e32 v18, v160, v19
	v_max_f32_e32 v19, v33, v33
	v_max_f32_e32 v19, 0, v19
	v_fmac_f32_e32 v18, v89, v19
	v_not_b32_e32 v19, v18
	v_or_b32_e32 v20, 0x80000000, v18
	v_cmp_gt_i32_e32 vcc, 0, v18
	s_nop 1
	v_cndmask_b32_e32 v18, v20, v19, vcc
	v_cmp_le_u32_e32 vcc, v110, v87
	s_nop 1
	v_cndmask_b32_e32 v191, 0, v18, vcc
.LBB0_461:
	s_or_b64 exec, exec, s[82:83]
	s_movk_i32 s2, 0x1ff
	v_cmp_lt_u32_e32 vcc, s2, v177
	v_mov_b32_e32 v192, 0
	s_and_saveexec_b64 s[82:83], vcc
	s_cbranch_execz .LBB0_465
	s_movk_i32 s2, 0x21f
	s_waitcnt lgkmcnt(0)
	v_cmp_lt_u32_e32 vcc, s2, v177
	s_and_saveexec_b64 s[84:85], vcc
	s_cbranch_execz .LBB0_464
	s_nop 0
	global_load_lds_dwordx4 v72, s[100:101]
	s_add_u32 m0, m0, 0x400
	s_add_u32 s100, s100, 0x1a000
	s_addc_u32 s101, s101, 0
	s_nop 0
	global_load_lds_dwordx4 v73, s[100:101]
	s_add_u32 m0, m0, 0x400
	s_add_u32 s100, s100, 0x1a000
	s_addc_u32 s101, s101, 0
	s_nop 0
	global_load_lds_dwordx4 v72, s[100:101]
	s_add_u32 m0, m0, 0x400
	s_add_u32 s100, s100, 0x1a000
	s_addc_u32 s101, s101, 0
	s_nop 0
	global_load_lds_dwordx4 v73, s[100:101]
	s_add_u32 m0, m0, 0x400
	s_add_u32 s100, s100, 0x1a000
	s_addc_u32 s101, s101, 0
.LBB0_464:
	s_or_b64 exec, exec, s[84:85]
	v_mfma_f32_32x32x16_bf16 v[18:33], v[38:41], v[58:61], 0
	v_mfma_f32_32x32x16_bf16 v[18:33], v[46:49], v[54:57], v[18:33]
	v_mfma_f32_32x32x16_bf16 v[18:33], v[34:37], v[50:53], v[18:33]
	v_mfma_f32_32x32x16_bf16 v[18:33], v[42:45], v[62:65], v[18:33]
	s_waitcnt vmcnt(12)
	ds_read_b128 v[58:61], v74 offset:4096
	ds_read_b128 v[54:57], v75 offset:4096
	ds_read_b128 v[50:53], v76 offset:4096
	ds_read_b128 v[62:65], v77 offset:4096
	s_nop 8
	v_max_f32_e32 v18, v18, v18
	v_max_f32_e32 v19, v19, v19
	v_max_f32_e32 v18, 0, v18
	v_max_f32_e32 v20, v20, v20
	v_max_f32_e32 v19, 0, v19
	v_fma_f32 v18, v174, v18, 0
	v_max_f32_e32 v21, v21, v21
	v_max_f32_e32 v20, 0, v20
	v_fmac_f32_e32 v18, v173, v19
	v_max_f32_e32 v22, v22, v22
	v_max_f32_e32 v21, 0, v21
	v_fmac_f32_e32 v18, v172, v20
	v_max_f32_e32 v23, v23, v23
	v_max_f32_e32 v22, 0, v22
	v_fmac_f32_e32 v18, v171, v21
	v_max_f32_e32 v24, v24, v24
	v_max_f32_e32 v23, 0, v23
	v_fmac_f32_e32 v18, v170, v22
	v_max_f32_e32 v25, v25, v25
	v_max_f32_e32 v24, 0, v24
	v_fmac_f32_e32 v18, v169, v23
	v_max_f32_e32 v26, v26, v26
	v_max_f32_e32 v25, 0, v25
	v_fmac_f32_e32 v18, v168, v24
	v_max_f32_e32 v27, v27, v27
	v_max_f32_e32 v26, 0, v26
	v_fmac_f32_e32 v18, v167, v25
	v_max_f32_e32 v28, v28, v28
	v_max_f32_e32 v27, 0, v27
	v_fmac_f32_e32 v18, v166, v26
	v_max_f32_e32 v29, v29, v29
	v_max_f32_e32 v28, 0, v28
	v_fmac_f32_e32 v18, v165, v27
	v_max_f32_e32 v30, v30, v30
	v_max_f32_e32 v29, 0, v29
	v_fmac_f32_e32 v18, v164, v28
	v_max_f32_e32 v31, v31, v31
	v_max_f32_e32 v30, 0, v30
	v_fmac_f32_e32 v18, v163, v29
	v_fmac_f32_e32 v18, v162, v30
	v_max_f32_e32 v19, 0, v31
	v_fmac_f32_e32 v18, v161, v19
	v_max_f32_e32 v19, v32, v32
	v_max_f32_e32 v19, 0, v19
	v_fmac_f32_e32 v18, v160, v19
	v_max_f32_e32 v19, v33, v33
	v_max_f32_e32 v19, 0, v19
	v_fmac_f32_e32 v18, v89, v19
	v_not_b32_e32 v19, v18
	v_or_b32_e32 v20, 0x80000000, v18
	v_cmp_gt_i32_e32 vcc, 0, v18
	s_nop 1
	v_cndmask_b32_e32 v18, v20, v19, vcc
	v_cmp_le_u32_e32 vcc, v111, v87
	s_nop 1
	v_cndmask_b32_e32 v192, 0, v18, vcc
.LBB0_465:
	s_or_b64 exec, exec, s[82:83]
	s_movk_i32 s2, 0x21f
	v_cmp_lt_u32_e32 vcc, s2, v177
	v_mov_b32_e32 v193, 0
	s_and_saveexec_b64 s[82:83], vcc
	s_cbranch_execz .LBB0_469
	s_movk_i32 s2, 0x23f
	s_waitcnt lgkmcnt(0)
	v_cmp_lt_u32_e32 vcc, s2, v177
	s_and_saveexec_b64 s[84:85], vcc
	s_cbranch_execz .LBB0_468
	s_nop 0
	global_load_lds_dwordx4 v72, s[100:101]
	s_add_u32 m0, m0, 0x400
	s_add_u32 s100, s100, 0x1a000
	s_addc_u32 s101, s101, 0
	s_nop 0
	global_load_lds_dwordx4 v73, s[100:101]
	s_add_u32 m0, m0, 0x400
	s_add_u32 s100, s100, 0x1a000
	s_addc_u32 s101, s101, 0
	s_nop 0
	global_load_lds_dwordx4 v72, s[100:101]
	s_add_u32 m0, m0, 0x400
	s_add_u32 s100, s100, 0x1a000
	s_addc_u32 s101, s101, 0
	s_nop 0
	global_load_lds_dwordx4 v73, s[100:101]
	s_add_u32 m0, m0, 0x400
	s_add_u32 s100, s100, 0x1a000
	s_addc_u32 s101, s101, 0
.LBB0_468:
	s_or_b64 exec, exec, s[84:85]
	v_mfma_f32_32x32x16_bf16 v[18:33], v[38:41], v[58:61], 0
	v_mfma_f32_32x32x16_bf16 v[18:33], v[46:49], v[54:57], v[18:33]
	v_mfma_f32_32x32x16_bf16 v[18:33], v[34:37], v[50:53], v[18:33]
	v_mfma_f32_32x32x16_bf16 v[18:33], v[42:45], v[62:65], v[18:33]
	s_waitcnt vmcnt(12)
	ds_read_b128 v[58:61], v74 offset:8192
	ds_read_b128 v[54:57], v75 offset:8192
	ds_read_b128 v[50:53], v76 offset:8192
	ds_read_b128 v[62:65], v77 offset:8192
	s_nop 8
	v_max_f32_e32 v18, v18, v18
	v_max_f32_e32 v19, v19, v19
	v_max_f32_e32 v18, 0, v18
	v_max_f32_e32 v20, v20, v20
	v_max_f32_e32 v19, 0, v19
	v_fma_f32 v18, v174, v18, 0
	v_max_f32_e32 v21, v21, v21
	v_max_f32_e32 v20, 0, v20
	v_fmac_f32_e32 v18, v173, v19
	v_max_f32_e32 v22, v22, v22
	v_max_f32_e32 v21, 0, v21
	v_fmac_f32_e32 v18, v172, v20
	v_max_f32_e32 v23, v23, v23
	v_max_f32_e32 v22, 0, v22
	v_fmac_f32_e32 v18, v171, v21
	v_max_f32_e32 v24, v24, v24
	v_max_f32_e32 v23, 0, v23
	v_fmac_f32_e32 v18, v170, v22
	v_max_f32_e32 v25, v25, v25
	v_max_f32_e32 v24, 0, v24
	v_fmac_f32_e32 v18, v169, v23
	v_max_f32_e32 v26, v26, v26
	v_max_f32_e32 v25, 0, v25
	v_fmac_f32_e32 v18, v168, v24
	v_max_f32_e32 v27, v27, v27
	v_max_f32_e32 v26, 0, v26
	v_fmac_f32_e32 v18, v167, v25
	v_max_f32_e32 v28, v28, v28
	v_max_f32_e32 v27, 0, v27
	v_fmac_f32_e32 v18, v166, v26
	v_max_f32_e32 v29, v29, v29
	v_max_f32_e32 v28, 0, v28
	v_fmac_f32_e32 v18, v165, v27
	v_max_f32_e32 v30, v30, v30
	v_max_f32_e32 v29, 0, v29
	v_fmac_f32_e32 v18, v164, v28
	v_max_f32_e32 v31, v31, v31
	v_max_f32_e32 v30, 0, v30
	v_fmac_f32_e32 v18, v163, v29
	v_fmac_f32_e32 v18, v162, v30
	v_max_f32_e32 v19, 0, v31
	v_fmac_f32_e32 v18, v161, v19
	v_max_f32_e32 v19, v32, v32
	v_max_f32_e32 v19, 0, v19
	v_fmac_f32_e32 v18, v160, v19
	v_max_f32_e32 v19, v33, v33
	v_max_f32_e32 v19, 0, v19
	v_fmac_f32_e32 v18, v89, v19
	v_not_b32_e32 v19, v18
	v_or_b32_e32 v20, 0x80000000, v18
	v_cmp_gt_i32_e32 vcc, 0, v18
	s_nop 1
	v_cndmask_b32_e32 v18, v20, v19, vcc
	v_cmp_le_u32_e32 vcc, v112, v87
	s_nop 1
	v_cndmask_b32_e32 v193, 0, v18, vcc
.LBB0_469:
	s_or_b64 exec, exec, s[82:83]
	s_movk_i32 s2, 0x23f
	v_cmp_lt_u32_e32 vcc, s2, v177
	v_mov_b32_e32 v194, 0
	s_and_saveexec_b64 s[82:83], vcc
	s_cbranch_execz .LBB0_473
	s_movk_i32 s2, 0x25f
	s_waitcnt lgkmcnt(0)
	v_cmp_lt_u32_e32 vcc, s2, v177
	s_and_saveexec_b64 s[84:85], vcc
	s_cbranch_execz .LBB0_472
	s_nop 0
	global_load_lds_dwordx4 v72, s[100:101]
	s_add_u32 m0, m0, 0x400
	s_add_u32 s100, s100, 0x1a000
	s_addc_u32 s101, s101, 0
	s_nop 0
	global_load_lds_dwordx4 v73, s[100:101]
	s_add_u32 m0, m0, 0x400
	s_add_u32 s100, s100, 0x1a000
	s_addc_u32 s101, s101, 0
	s_nop 0
	global_load_lds_dwordx4 v72, s[100:101]
	s_add_u32 m0, m0, 0x400
	s_add_u32 s100, s100, 0x1a000
	s_addc_u32 s101, s101, 0
	s_nop 0
	global_load_lds_dwordx4 v73, s[100:101]
	s_add_u32 m0, m0, 0x400
	s_add_u32 s100, s100, 0x1a000
	s_addc_u32 s101, s101, 0
.LBB0_472:
	s_or_b64 exec, exec, s[84:85]
	v_mfma_f32_32x32x16_bf16 v[18:33], v[38:41], v[58:61], 0
	v_mfma_f32_32x32x16_bf16 v[18:33], v[46:49], v[54:57], v[18:33]
	v_mfma_f32_32x32x16_bf16 v[18:33], v[34:37], v[50:53], v[18:33]
	v_mfma_f32_32x32x16_bf16 v[18:33], v[42:45], v[62:65], v[18:33]
	s_waitcnt vmcnt(12)
	ds_read_b128 v[58:61], v74 offset:12288
	ds_read_b128 v[54:57], v75 offset:12288
	ds_read_b128 v[50:53], v76 offset:12288
	ds_read_b128 v[62:65], v77 offset:12288
	s_nop 8
	v_max_f32_e32 v18, v18, v18
	v_max_f32_e32 v19, v19, v19
	v_max_f32_e32 v18, 0, v18
	v_max_f32_e32 v20, v20, v20
	v_max_f32_e32 v19, 0, v19
	v_fma_f32 v18, v174, v18, 0
	v_max_f32_e32 v21, v21, v21
	v_max_f32_e32 v20, 0, v20
	v_fmac_f32_e32 v18, v173, v19
	v_max_f32_e32 v22, v22, v22
	v_max_f32_e32 v21, 0, v21
	v_fmac_f32_e32 v18, v172, v20
	v_max_f32_e32 v23, v23, v23
	v_max_f32_e32 v22, 0, v22
	v_fmac_f32_e32 v18, v171, v21
	v_max_f32_e32 v24, v24, v24
	v_max_f32_e32 v23, 0, v23
	v_fmac_f32_e32 v18, v170, v22
	v_max_f32_e32 v25, v25, v25
	v_max_f32_e32 v24, 0, v24
	v_fmac_f32_e32 v18, v169, v23
	v_max_f32_e32 v26, v26, v26
	v_max_f32_e32 v25, 0, v25
	v_fmac_f32_e32 v18, v168, v24
	v_max_f32_e32 v27, v27, v27
	v_max_f32_e32 v26, 0, v26
	v_fmac_f32_e32 v18, v167, v25
	v_max_f32_e32 v28, v28, v28
	v_max_f32_e32 v27, 0, v27
	v_fmac_f32_e32 v18, v166, v26
	v_max_f32_e32 v29, v29, v29
	v_max_f32_e32 v28, 0, v28
	v_fmac_f32_e32 v18, v165, v27
	v_max_f32_e32 v30, v30, v30
	v_max_f32_e32 v29, 0, v29
	v_fmac_f32_e32 v18, v164, v28
	v_max_f32_e32 v31, v31, v31
	v_max_f32_e32 v30, 0, v30
	v_fmac_f32_e32 v18, v163, v29
	v_fmac_f32_e32 v18, v162, v30
	v_max_f32_e32 v19, 0, v31
	v_fmac_f32_e32 v18, v161, v19
	v_max_f32_e32 v19, v32, v32
	v_max_f32_e32 v19, 0, v19
	v_fmac_f32_e32 v18, v160, v19
	v_max_f32_e32 v19, v33, v33
	v_max_f32_e32 v19, 0, v19
	v_fmac_f32_e32 v18, v89, v19
	v_not_b32_e32 v19, v18
	v_or_b32_e32 v20, 0x80000000, v18
	v_cmp_gt_i32_e32 vcc, 0, v18
	s_nop 1
	v_cndmask_b32_e32 v18, v20, v19, vcc
	v_cmp_le_u32_e32 vcc, v113, v87
	s_nop 1
	v_cndmask_b32_e32 v194, 0, v18, vcc
.LBB0_473:
	s_or_b64 exec, exec, s[82:83]
	s_movk_i32 s2, 0x25f
	v_cmp_lt_u32_e32 vcc, s2, v177
	v_mov_b32_e32 v195, 0
	s_and_saveexec_b64 s[82:83], vcc
	s_cbranch_execz .LBB0_477
	s_movk_i32 s2, 0x27f
	s_waitcnt lgkmcnt(0)
	v_cmp_lt_u32_e32 vcc, s2, v177
	s_and_saveexec_b64 s[84:85], vcc
	s_cbranch_execz .LBB0_476
	s_nop 0
	global_load_lds_dwordx4 v72, s[100:101]
	s_add_u32 m0, m0, 0x400
	s_add_u32 s100, s100, 0x1a000
	s_addc_u32 s101, s101, 0
	s_nop 0
	global_load_lds_dwordx4 v73, s[100:101]
	s_add_u32 m0, m0, 0x400
	s_add_u32 s100, s100, 0x1a000
	s_addc_u32 s101, s101, 0
	s_nop 0
	global_load_lds_dwordx4 v72, s[100:101]
	s_add_u32 m0, m0, 0x400
	s_add_u32 s100, s100, 0x1a000
	s_addc_u32 s101, s101, 0
	s_nop 0
	global_load_lds_dwordx4 v73, s[100:101]
	s_sub_u32 m0, m0, 0x3c00
	s_add_u32 s100, s100, 0x1a000
	s_addc_u32 s101, s101, 0
.LBB0_476:
	s_or_b64 exec, exec, s[84:85]
	v_mfma_f32_32x32x16_bf16 v[18:33], v[38:41], v[58:61], 0
	v_mfma_f32_32x32x16_bf16 v[18:33], v[46:49], v[54:57], v[18:33]
	v_mfma_f32_32x32x16_bf16 v[18:33], v[34:37], v[50:53], v[18:33]
	v_mfma_f32_32x32x16_bf16 v[18:33], v[42:45], v[62:65], v[18:33]
	s_waitcnt vmcnt(12)
	ds_read_b128 v[58:61], v74 offset:0
	ds_read_b128 v[54:57], v75 offset:0
	ds_read_b128 v[50:53], v76 offset:0
	ds_read_b128 v[62:65], v77 offset:0
	s_nop 8
	v_max_f32_e32 v18, v18, v18
	v_max_f32_e32 v19, v19, v19
	v_max_f32_e32 v18, 0, v18
	v_max_f32_e32 v20, v20, v20
	v_max_f32_e32 v19, 0, v19
	v_fma_f32 v18, v174, v18, 0
	v_max_f32_e32 v21, v21, v21
	v_max_f32_e32 v20, 0, v20
	v_fmac_f32_e32 v18, v173, v19
	v_max_f32_e32 v22, v22, v22
	v_max_f32_e32 v21, 0, v21
	v_fmac_f32_e32 v18, v172, v20
	v_max_f32_e32 v23, v23, v23
	v_max_f32_e32 v22, 0, v22
	v_fmac_f32_e32 v18, v171, v21
	v_max_f32_e32 v24, v24, v24
	v_max_f32_e32 v23, 0, v23
	v_fmac_f32_e32 v18, v170, v22
	v_max_f32_e32 v25, v25, v25
	v_max_f32_e32 v24, 0, v24
	v_fmac_f32_e32 v18, v169, v23
	v_max_f32_e32 v26, v26, v26
	v_max_f32_e32 v25, 0, v25
	v_fmac_f32_e32 v18, v168, v24
	v_max_f32_e32 v27, v27, v27
	v_max_f32_e32 v26, 0, v26
	v_fmac_f32_e32 v18, v167, v25
	v_max_f32_e32 v28, v28, v28
	v_max_f32_e32 v27, 0, v27
	v_fmac_f32_e32 v18, v166, v26
	v_max_f32_e32 v29, v29, v29
	v_max_f32_e32 v28, 0, v28
	v_fmac_f32_e32 v18, v165, v27
	v_max_f32_e32 v30, v30, v30
	v_max_f32_e32 v29, 0, v29
	v_fmac_f32_e32 v18, v164, v28
	v_max_f32_e32 v31, v31, v31
	v_max_f32_e32 v30, 0, v30
	v_fmac_f32_e32 v18, v163, v29
	v_fmac_f32_e32 v18, v162, v30
	v_max_f32_e32 v19, 0, v31
	v_fmac_f32_e32 v18, v161, v19
	v_max_f32_e32 v19, v32, v32
	v_max_f32_e32 v19, 0, v19
	v_fmac_f32_e32 v18, v160, v19
	v_max_f32_e32 v19, v33, v33
	v_max_f32_e32 v19, 0, v19
	v_fmac_f32_e32 v18, v89, v19
	v_not_b32_e32 v19, v18
	v_or_b32_e32 v20, 0x80000000, v18
	v_cmp_gt_i32_e32 vcc, 0, v18
	s_nop 1
	v_cndmask_b32_e32 v18, v20, v19, vcc
	v_cmp_le_u32_e32 vcc, v114, v87
	s_nop 1
	v_cndmask_b32_e32 v195, 0, v18, vcc
.LBB0_477:
	s_or_b64 exec, exec, s[82:83]
	s_movk_i32 s2, 0x27f
	v_cmp_lt_u32_e32 vcc, s2, v177
	v_mov_b32_e32 v196, 0
	s_and_saveexec_b64 s[82:83], vcc
	s_cbranch_execz .LBB0_481
	s_movk_i32 s2, 0x29f
	s_waitcnt lgkmcnt(0)
	v_cmp_lt_u32_e32 vcc, s2, v177
	s_and_saveexec_b64 s[84:85], vcc
	s_cbranch_execz .LBB0_480
	s_nop 0
	global_load_lds_dwordx4 v72, s[100:101]
	s_add_u32 m0, m0, 0x400
	s_add_u32 s100, s100, 0x1a000
	s_addc_u32 s101, s101, 0
	s_nop 0
	global_load_lds_dwordx4 v73, s[100:101]
	s_add_u32 m0, m0, 0x400
	s_add_u32 s100, s100, 0x1a000
	s_addc_u32 s101, s101, 0
	s_nop 0
	global_load_lds_dwordx4 v72, s[100:101]
	s_add_u32 m0, m0, 0x400
	s_add_u32 s100, s100, 0x1a000
	s_addc_u32 s101, s101, 0
	s_nop 0
	global_load_lds_dwordx4 v73, s[100:101]
	s_add_u32 m0, m0, 0x400
	s_add_u32 s100, s100, 0x1a000
	s_addc_u32 s101, s101, 0
.LBB0_480:
	s_or_b64 exec, exec, s[84:85]
	v_mfma_f32_32x32x16_bf16 v[18:33], v[38:41], v[58:61], 0
	v_mfma_f32_32x32x16_bf16 v[18:33], v[46:49], v[54:57], v[18:33]
	v_mfma_f32_32x32x16_bf16 v[18:33], v[34:37], v[50:53], v[18:33]
	v_mfma_f32_32x32x16_bf16 v[18:33], v[42:45], v[62:65], v[18:33]
	s_waitcnt vmcnt(12)
	ds_read_b128 v[58:61], v74 offset:4096
	ds_read_b128 v[54:57], v75 offset:4096
	ds_read_b128 v[50:53], v76 offset:4096
	ds_read_b128 v[62:65], v77 offset:4096
	s_nop 8
	v_max_f32_e32 v18, v18, v18
	v_max_f32_e32 v19, v19, v19
	v_max_f32_e32 v18, 0, v18
	v_max_f32_e32 v20, v20, v20
	v_max_f32_e32 v19, 0, v19
	v_fma_f32 v18, v174, v18, 0
	v_max_f32_e32 v21, v21, v21
	v_max_f32_e32 v20, 0, v20
	v_fmac_f32_e32 v18, v173, v19
	v_max_f32_e32 v22, v22, v22
	v_max_f32_e32 v21, 0, v21
	v_fmac_f32_e32 v18, v172, v20
	v_max_f32_e32 v23, v23, v23
	v_max_f32_e32 v22, 0, v22
	v_fmac_f32_e32 v18, v171, v21
	v_max_f32_e32 v24, v24, v24
	v_max_f32_e32 v23, 0, v23
	v_fmac_f32_e32 v18, v170, v22
	v_max_f32_e32 v25, v25, v25
	v_max_f32_e32 v24, 0, v24
	v_fmac_f32_e32 v18, v169, v23
	v_max_f32_e32 v26, v26, v26
	v_max_f32_e32 v25, 0, v25
	v_fmac_f32_e32 v18, v168, v24
	v_max_f32_e32 v27, v27, v27
	v_max_f32_e32 v26, 0, v26
	v_fmac_f32_e32 v18, v167, v25
	v_max_f32_e32 v28, v28, v28
	v_max_f32_e32 v27, 0, v27
	v_fmac_f32_e32 v18, v166, v26
	v_max_f32_e32 v29, v29, v29
	v_max_f32_e32 v28, 0, v28
	v_fmac_f32_e32 v18, v165, v27
	v_max_f32_e32 v30, v30, v30
	v_max_f32_e32 v29, 0, v29
	v_fmac_f32_e32 v18, v164, v28
	v_max_f32_e32 v31, v31, v31
	v_max_f32_e32 v30, 0, v30
	v_fmac_f32_e32 v18, v163, v29
	v_fmac_f32_e32 v18, v162, v30
	v_max_f32_e32 v19, 0, v31
	v_fmac_f32_e32 v18, v161, v19
	v_max_f32_e32 v19, v32, v32
	v_max_f32_e32 v19, 0, v19
	v_fmac_f32_e32 v18, v160, v19
	v_max_f32_e32 v19, v33, v33
	v_max_f32_e32 v19, 0, v19
	v_fmac_f32_e32 v18, v89, v19
	v_not_b32_e32 v19, v18
	v_or_b32_e32 v20, 0x80000000, v18
	v_cmp_gt_i32_e32 vcc, 0, v18
	s_nop 1
	v_cndmask_b32_e32 v18, v20, v19, vcc
	v_cmp_le_u32_e32 vcc, v115, v87
	s_nop 1
	v_cndmask_b32_e32 v196, 0, v18, vcc
.LBB0_481:
	s_or_b64 exec, exec, s[82:83]
	s_movk_i32 s2, 0x29f
	v_cmp_lt_u32_e32 vcc, s2, v177
	v_mov_b32_e32 v197, 0
	s_and_saveexec_b64 s[82:83], vcc
	s_cbranch_execz .LBB0_485
	s_movk_i32 s2, 0x2bf
	s_waitcnt lgkmcnt(0)
	v_cmp_lt_u32_e32 vcc, s2, v177
	s_and_saveexec_b64 s[84:85], vcc
	s_cbranch_execz .LBB0_484
	s_nop 0
	global_load_lds_dwordx4 v72, s[100:101]
	s_add_u32 m0, m0, 0x400
	s_add_u32 s100, s100, 0x1a000
	s_addc_u32 s101, s101, 0
	s_nop 0
	global_load_lds_dwordx4 v73, s[100:101]
	s_add_u32 m0, m0, 0x400
	s_add_u32 s100, s100, 0x1a000
	s_addc_u32 s101, s101, 0
	s_nop 0
	global_load_lds_dwordx4 v72, s[100:101]
	s_add_u32 m0, m0, 0x400
	s_add_u32 s100, s100, 0x1a000
	s_addc_u32 s101, s101, 0
	s_nop 0
	global_load_lds_dwordx4 v73, s[100:101]
	s_add_u32 m0, m0, 0x400
	s_add_u32 s100, s100, 0x1a000
	s_addc_u32 s101, s101, 0
.LBB0_484:
	s_or_b64 exec, exec, s[84:85]
	v_mfma_f32_32x32x16_bf16 v[18:33], v[38:41], v[58:61], 0
	v_mfma_f32_32x32x16_bf16 v[18:33], v[46:49], v[54:57], v[18:33]
	v_mfma_f32_32x32x16_bf16 v[18:33], v[34:37], v[50:53], v[18:33]
	v_mfma_f32_32x32x16_bf16 v[18:33], v[42:45], v[62:65], v[18:33]
	s_waitcnt vmcnt(12)
	ds_read_b128 v[58:61], v74 offset:8192
	ds_read_b128 v[54:57], v75 offset:8192
	ds_read_b128 v[50:53], v76 offset:8192
	ds_read_b128 v[62:65], v77 offset:8192
	s_nop 8
	v_max_f32_e32 v18, v18, v18
	v_max_f32_e32 v19, v19, v19
	v_max_f32_e32 v18, 0, v18
	v_max_f32_e32 v20, v20, v20
	v_max_f32_e32 v19, 0, v19
	v_fma_f32 v18, v174, v18, 0
	v_max_f32_e32 v21, v21, v21
	v_max_f32_e32 v20, 0, v20
	v_fmac_f32_e32 v18, v173, v19
	v_max_f32_e32 v22, v22, v22
	v_max_f32_e32 v21, 0, v21
	v_fmac_f32_e32 v18, v172, v20
	v_max_f32_e32 v23, v23, v23
	v_max_f32_e32 v22, 0, v22
	v_fmac_f32_e32 v18, v171, v21
	v_max_f32_e32 v24, v24, v24
	v_max_f32_e32 v23, 0, v23
	v_fmac_f32_e32 v18, v170, v22
	v_max_f32_e32 v25, v25, v25
	v_max_f32_e32 v24, 0, v24
	v_fmac_f32_e32 v18, v169, v23
	v_max_f32_e32 v26, v26, v26
	v_max_f32_e32 v25, 0, v25
	v_fmac_f32_e32 v18, v168, v24
	v_max_f32_e32 v27, v27, v27
	v_max_f32_e32 v26, 0, v26
	v_fmac_f32_e32 v18, v167, v25
	v_max_f32_e32 v28, v28, v28
	v_max_f32_e32 v27, 0, v27
	v_fmac_f32_e32 v18, v166, v26
	v_max_f32_e32 v29, v29, v29
	v_max_f32_e32 v28, 0, v28
	v_fmac_f32_e32 v18, v165, v27
	v_max_f32_e32 v30, v30, v30
	v_max_f32_e32 v29, 0, v29
	v_fmac_f32_e32 v18, v164, v28
	v_max_f32_e32 v31, v31, v31
	v_max_f32_e32 v30, 0, v30
	v_fmac_f32_e32 v18, v163, v29
	v_fmac_f32_e32 v18, v162, v30
	v_max_f32_e32 v19, 0, v31
	v_fmac_f32_e32 v18, v161, v19
	v_max_f32_e32 v19, v32, v32
	v_max_f32_e32 v19, 0, v19
	v_fmac_f32_e32 v18, v160, v19
	v_max_f32_e32 v19, v33, v33
	v_max_f32_e32 v19, 0, v19
	v_fmac_f32_e32 v18, v89, v19
	v_not_b32_e32 v19, v18
	v_or_b32_e32 v20, 0x80000000, v18
	v_cmp_gt_i32_e32 vcc, 0, v18
	s_nop 1
	v_cndmask_b32_e32 v18, v20, v19, vcc
	v_cmp_le_u32_e32 vcc, v116, v87
	s_nop 1
	v_cndmask_b32_e32 v197, 0, v18, vcc
.LBB0_485:
	s_or_b64 exec, exec, s[82:83]
	s_movk_i32 s2, 0x2bf
	v_cmp_lt_u32_e32 vcc, s2, v177
	v_mov_b32_e32 v216, 0
	s_and_saveexec_b64 s[82:83], vcc
	s_cbranch_execz .LBB0_489
	s_movk_i32 s2, 0x2df
	s_waitcnt lgkmcnt(0)
	v_cmp_lt_u32_e32 vcc, s2, v177
	s_and_saveexec_b64 s[84:85], vcc
	s_cbranch_execz .LBB0_488
	s_nop 0
	global_load_lds_dwordx4 v72, s[100:101]
	s_add_u32 m0, m0, 0x400
	s_add_u32 s100, s100, 0x1a000
	s_addc_u32 s101, s101, 0
	s_nop 0
	global_load_lds_dwordx4 v73, s[100:101]
	s_add_u32 m0, m0, 0x400
	s_add_u32 s100, s100, 0x1a000
	s_addc_u32 s101, s101, 0
	s_nop 0
	global_load_lds_dwordx4 v72, s[100:101]
	s_add_u32 m0, m0, 0x400
	s_add_u32 s100, s100, 0x1a000
	s_addc_u32 s101, s101, 0
	s_nop 0
	global_load_lds_dwordx4 v73, s[100:101]
	s_add_u32 m0, m0, 0x400
	s_add_u32 s100, s100, 0x1a000
	s_addc_u32 s101, s101, 0
.LBB0_488:
	s_or_b64 exec, exec, s[84:85]
	v_mfma_f32_32x32x16_bf16 v[18:33], v[38:41], v[58:61], 0
	v_mfma_f32_32x32x16_bf16 v[18:33], v[46:49], v[54:57], v[18:33]
	v_mfma_f32_32x32x16_bf16 v[18:33], v[34:37], v[50:53], v[18:33]
	v_mfma_f32_32x32x16_bf16 v[18:33], v[42:45], v[62:65], v[18:33]
	s_waitcnt vmcnt(12)
	ds_read_b128 v[58:61], v74 offset:12288
	ds_read_b128 v[54:57], v75 offset:12288
	ds_read_b128 v[50:53], v76 offset:12288
	ds_read_b128 v[62:65], v77 offset:12288
	s_nop 8
	v_max_f32_e32 v18, v18, v18
	v_max_f32_e32 v19, v19, v19
	v_max_f32_e32 v18, 0, v18
	v_max_f32_e32 v20, v20, v20
	v_max_f32_e32 v19, 0, v19
	v_fma_f32 v18, v174, v18, 0
	v_max_f32_e32 v21, v21, v21
	v_max_f32_e32 v20, 0, v20
	v_fmac_f32_e32 v18, v173, v19
	v_max_f32_e32 v22, v22, v22
	v_max_f32_e32 v21, 0, v21
	v_fmac_f32_e32 v18, v172, v20
	v_max_f32_e32 v23, v23, v23
	v_max_f32_e32 v22, 0, v22
	v_fmac_f32_e32 v18, v171, v21
	v_max_f32_e32 v24, v24, v24
	v_max_f32_e32 v23, 0, v23
	v_fmac_f32_e32 v18, v170, v22
	v_max_f32_e32 v25, v25, v25
	v_max_f32_e32 v24, 0, v24
	v_fmac_f32_e32 v18, v169, v23
	v_max_f32_e32 v26, v26, v26
	v_max_f32_e32 v25, 0, v25
	v_fmac_f32_e32 v18, v168, v24
	v_max_f32_e32 v27, v27, v27
	v_max_f32_e32 v26, 0, v26
	v_fmac_f32_e32 v18, v167, v25
	v_max_f32_e32 v28, v28, v28
	v_max_f32_e32 v27, 0, v27
	v_fmac_f32_e32 v18, v166, v26
	v_max_f32_e32 v29, v29, v29
	v_max_f32_e32 v28, 0, v28
	v_fmac_f32_e32 v18, v165, v27
	v_max_f32_e32 v30, v30, v30
	v_max_f32_e32 v29, 0, v29
	v_fmac_f32_e32 v18, v164, v28
	v_max_f32_e32 v31, v31, v31
	v_max_f32_e32 v30, 0, v30
	v_fmac_f32_e32 v18, v163, v29
	v_fmac_f32_e32 v18, v162, v30
	v_max_f32_e32 v19, 0, v31
	v_fmac_f32_e32 v18, v161, v19
	v_max_f32_e32 v19, v32, v32
	v_max_f32_e32 v19, 0, v19
	v_fmac_f32_e32 v18, v160, v19
	v_max_f32_e32 v19, v33, v33
	v_max_f32_e32 v19, 0, v19
	v_fmac_f32_e32 v18, v89, v19
	v_not_b32_e32 v19, v18
	v_or_b32_e32 v20, 0x80000000, v18
	v_cmp_gt_i32_e32 vcc, 0, v18
	s_nop 1
	v_cndmask_b32_e32 v18, v20, v19, vcc
	v_cmp_le_u32_e32 vcc, v117, v87
	s_nop 1
	v_cndmask_b32_e32 v216, 0, v18, vcc
.LBB0_489:
	s_or_b64 exec, exec, s[82:83]
	s_movk_i32 s2, 0x2df
	v_cmp_lt_u32_e32 vcc, s2, v177
	v_mov_b32_e32 v217, 0
	s_and_saveexec_b64 s[82:83], vcc
	s_cbranch_execz .LBB0_493
	s_movk_i32 s2, 0x2ff
	s_waitcnt lgkmcnt(0)
	v_cmp_lt_u32_e32 vcc, s2, v177
	s_and_saveexec_b64 s[84:85], vcc
	s_cbranch_execz .LBB0_492
	s_nop 0
	global_load_lds_dwordx4 v72, s[100:101]
	s_add_u32 m0, m0, 0x400
	s_add_u32 s100, s100, 0x1a000
	s_addc_u32 s101, s101, 0
	s_nop 0
	global_load_lds_dwordx4 v73, s[100:101]
	s_add_u32 m0, m0, 0x400
	s_add_u32 s100, s100, 0x1a000
	s_addc_u32 s101, s101, 0
	s_nop 0
	global_load_lds_dwordx4 v72, s[100:101]
	s_add_u32 m0, m0, 0x400
	s_add_u32 s100, s100, 0x1a000
	s_addc_u32 s101, s101, 0
	s_nop 0
	global_load_lds_dwordx4 v73, s[100:101]
	s_sub_u32 m0, m0, 0x3c00
	s_add_u32 s100, s100, 0x1a000
	s_addc_u32 s101, s101, 0
.LBB0_492:
	s_or_b64 exec, exec, s[84:85]
	v_mfma_f32_32x32x16_bf16 v[18:33], v[38:41], v[58:61], 0
	v_mfma_f32_32x32x16_bf16 v[18:33], v[46:49], v[54:57], v[18:33]
	v_mfma_f32_32x32x16_bf16 v[18:33], v[34:37], v[50:53], v[18:33]
	v_mfma_f32_32x32x16_bf16 v[18:33], v[42:45], v[62:65], v[18:33]
	s_waitcnt vmcnt(12)
	ds_read_b128 v[58:61], v74 offset:0
	ds_read_b128 v[54:57], v75 offset:0
	ds_read_b128 v[50:53], v76 offset:0
	ds_read_b128 v[62:65], v77 offset:0
	s_nop 8
	v_max_f32_e32 v18, v18, v18
	v_max_f32_e32 v19, v19, v19
	v_max_f32_e32 v18, 0, v18
	v_max_f32_e32 v20, v20, v20
	v_max_f32_e32 v19, 0, v19
	v_fma_f32 v18, v174, v18, 0
	v_max_f32_e32 v21, v21, v21
	v_max_f32_e32 v20, 0, v20
	v_fmac_f32_e32 v18, v173, v19
	v_max_f32_e32 v22, v22, v22
	v_max_f32_e32 v21, 0, v21
	v_fmac_f32_e32 v18, v172, v20
	v_max_f32_e32 v23, v23, v23
	v_max_f32_e32 v22, 0, v22
	v_fmac_f32_e32 v18, v171, v21
	v_max_f32_e32 v24, v24, v24
	v_max_f32_e32 v23, 0, v23
	v_fmac_f32_e32 v18, v170, v22
	v_max_f32_e32 v25, v25, v25
	v_max_f32_e32 v24, 0, v24
	v_fmac_f32_e32 v18, v169, v23
	v_max_f32_e32 v26, v26, v26
	v_max_f32_e32 v25, 0, v25
	v_fmac_f32_e32 v18, v168, v24
	v_max_f32_e32 v27, v27, v27
	v_max_f32_e32 v26, 0, v26
	v_fmac_f32_e32 v18, v167, v25
	v_max_f32_e32 v28, v28, v28
	v_max_f32_e32 v27, 0, v27
	v_fmac_f32_e32 v18, v166, v26
	v_max_f32_e32 v29, v29, v29
	v_max_f32_e32 v28, 0, v28
	v_fmac_f32_e32 v18, v165, v27
	v_max_f32_e32 v30, v30, v30
	v_max_f32_e32 v29, 0, v29
	v_fmac_f32_e32 v18, v164, v28
	v_max_f32_e32 v31, v31, v31
	v_max_f32_e32 v30, 0, v30
	v_fmac_f32_e32 v18, v163, v29
	v_fmac_f32_e32 v18, v162, v30
	v_max_f32_e32 v19, 0, v31
	v_fmac_f32_e32 v18, v161, v19
	v_max_f32_e32 v19, v32, v32
	v_max_f32_e32 v19, 0, v19
	v_fmac_f32_e32 v18, v160, v19
	v_max_f32_e32 v19, v33, v33
	v_max_f32_e32 v19, 0, v19
	v_fmac_f32_e32 v18, v89, v19
	v_not_b32_e32 v19, v18
	v_or_b32_e32 v20, 0x80000000, v18
	v_cmp_gt_i32_e32 vcc, 0, v18
	s_nop 1
	v_cndmask_b32_e32 v18, v20, v19, vcc
	v_cmp_le_u32_e32 vcc, v118, v87
	s_nop 1
	v_cndmask_b32_e32 v217, 0, v18, vcc
.LBB0_493:
	s_or_b64 exec, exec, s[82:83]
	s_movk_i32 s2, 0x2ff
	v_cmp_lt_u32_e32 vcc, s2, v177
	v_mov_b32_e32 v218, 0
	s_and_saveexec_b64 s[82:83], vcc
	s_cbranch_execz .LBB0_497
	s_movk_i32 s2, 0x31f
	s_waitcnt lgkmcnt(0)
	v_cmp_lt_u32_e32 vcc, s2, v177
	s_and_saveexec_b64 s[84:85], vcc
	s_cbranch_execz .LBB0_496
	s_nop 0
	global_load_lds_dwordx4 v72, s[100:101]
	s_add_u32 m0, m0, 0x400
	s_add_u32 s100, s100, 0x1a000
	s_addc_u32 s101, s101, 0
	s_nop 0
	global_load_lds_dwordx4 v73, s[100:101]
	s_add_u32 m0, m0, 0x400
	s_add_u32 s100, s100, 0x1a000
	s_addc_u32 s101, s101, 0
	s_nop 0
	global_load_lds_dwordx4 v72, s[100:101]
	s_add_u32 m0, m0, 0x400
	s_add_u32 s100, s100, 0x1a000
	s_addc_u32 s101, s101, 0
	s_nop 0
	global_load_lds_dwordx4 v73, s[100:101]
	s_add_u32 m0, m0, 0x400
	s_add_u32 s100, s100, 0x1a000
	s_addc_u32 s101, s101, 0
.LBB0_496:
	s_or_b64 exec, exec, s[84:85]
	v_mfma_f32_32x32x16_bf16 v[18:33], v[38:41], v[58:61], 0
	v_mfma_f32_32x32x16_bf16 v[18:33], v[46:49], v[54:57], v[18:33]
	v_mfma_f32_32x32x16_bf16 v[18:33], v[34:37], v[50:53], v[18:33]
	v_mfma_f32_32x32x16_bf16 v[18:33], v[42:45], v[62:65], v[18:33]
	s_waitcnt vmcnt(12)
	ds_read_b128 v[58:61], v74 offset:4096
	ds_read_b128 v[54:57], v75 offset:4096
	ds_read_b128 v[50:53], v76 offset:4096
	ds_read_b128 v[62:65], v77 offset:4096
	s_nop 8
	v_max_f32_e32 v18, v18, v18
	v_max_f32_e32 v19, v19, v19
	v_max_f32_e32 v18, 0, v18
	v_max_f32_e32 v20, v20, v20
	v_max_f32_e32 v19, 0, v19
	v_fma_f32 v18, v174, v18, 0
	v_max_f32_e32 v21, v21, v21
	v_max_f32_e32 v20, 0, v20
	v_fmac_f32_e32 v18, v173, v19
	v_max_f32_e32 v22, v22, v22
	v_max_f32_e32 v21, 0, v21
	v_fmac_f32_e32 v18, v172, v20
	v_max_f32_e32 v23, v23, v23
	v_max_f32_e32 v22, 0, v22
	v_fmac_f32_e32 v18, v171, v21
	v_max_f32_e32 v24, v24, v24
	v_max_f32_e32 v23, 0, v23
	v_fmac_f32_e32 v18, v170, v22
	v_max_f32_e32 v25, v25, v25
	v_max_f32_e32 v24, 0, v24
	v_fmac_f32_e32 v18, v169, v23
	v_max_f32_e32 v26, v26, v26
	v_max_f32_e32 v25, 0, v25
	v_fmac_f32_e32 v18, v168, v24
	v_max_f32_e32 v27, v27, v27
	v_max_f32_e32 v26, 0, v26
	v_fmac_f32_e32 v18, v167, v25
	v_max_f32_e32 v28, v28, v28
	v_max_f32_e32 v27, 0, v27
	v_fmac_f32_e32 v18, v166, v26
	v_max_f32_e32 v29, v29, v29
	v_max_f32_e32 v28, 0, v28
	v_fmac_f32_e32 v18, v165, v27
	v_max_f32_e32 v30, v30, v30
	v_max_f32_e32 v29, 0, v29
	v_fmac_f32_e32 v18, v164, v28
	v_max_f32_e32 v31, v31, v31
	v_max_f32_e32 v30, 0, v30
	v_fmac_f32_e32 v18, v163, v29
	v_fmac_f32_e32 v18, v162, v30
	v_max_f32_e32 v19, 0, v31
	v_fmac_f32_e32 v18, v161, v19
	v_max_f32_e32 v19, v32, v32
	v_max_f32_e32 v19, 0, v19
	v_fmac_f32_e32 v18, v160, v19
	v_max_f32_e32 v19, v33, v33
	v_max_f32_e32 v19, 0, v19
	v_fmac_f32_e32 v18, v89, v19
	v_not_b32_e32 v19, v18
	v_or_b32_e32 v20, 0x80000000, v18
	v_cmp_gt_i32_e32 vcc, 0, v18
	s_nop 1
	v_cndmask_b32_e32 v18, v20, v19, vcc
	v_cmp_le_u32_e32 vcc, v119, v87
	s_nop 1
	v_cndmask_b32_e32 v218, 0, v18, vcc
.LBB0_497:
	s_or_b64 exec, exec, s[82:83]
	s_movk_i32 s2, 0x31f
	v_cmp_lt_u32_e32 vcc, s2, v177
	v_mov_b32_e32 v219, 0
	s_and_saveexec_b64 s[82:83], vcc
	s_cbranch_execz .LBB0_501
	s_movk_i32 s2, 0x33f
	s_waitcnt lgkmcnt(0)
	v_cmp_lt_u32_e32 vcc, s2, v177
	s_and_saveexec_b64 s[84:85], vcc
	s_cbranch_execz .LBB0_500
	s_nop 0
	global_load_lds_dwordx4 v72, s[100:101]
	s_add_u32 m0, m0, 0x400
	s_add_u32 s100, s100, 0x1a000
	s_addc_u32 s101, s101, 0
	s_nop 0
	global_load_lds_dwordx4 v73, s[100:101]
	s_add_u32 m0, m0, 0x400
	s_add_u32 s100, s100, 0x1a000
	s_addc_u32 s101, s101, 0
	s_nop 0
	global_load_lds_dwordx4 v72, s[100:101]
	s_add_u32 m0, m0, 0x400
	s_add_u32 s100, s100, 0x1a000
	s_addc_u32 s101, s101, 0
	s_nop 0
	global_load_lds_dwordx4 v73, s[100:101]
	s_add_u32 m0, m0, 0x400
	s_add_u32 s100, s100, 0x1a000
	s_addc_u32 s101, s101, 0
.LBB0_500:
	s_or_b64 exec, exec, s[84:85]
	v_mfma_f32_32x32x16_bf16 v[18:33], v[38:41], v[58:61], 0
	v_mfma_f32_32x32x16_bf16 v[18:33], v[46:49], v[54:57], v[18:33]
	v_mfma_f32_32x32x16_bf16 v[18:33], v[34:37], v[50:53], v[18:33]
	v_mfma_f32_32x32x16_bf16 v[18:33], v[42:45], v[62:65], v[18:33]
	s_waitcnt vmcnt(12)
	ds_read_b128 v[58:61], v74 offset:8192
	ds_read_b128 v[54:57], v75 offset:8192
	ds_read_b128 v[50:53], v76 offset:8192
	ds_read_b128 v[62:65], v77 offset:8192
	s_nop 8
	v_max_f32_e32 v18, v18, v18
	v_max_f32_e32 v19, v19, v19
	v_max_f32_e32 v18, 0, v18
	v_max_f32_e32 v20, v20, v20
	v_max_f32_e32 v19, 0, v19
	v_fma_f32 v18, v174, v18, 0
	v_max_f32_e32 v21, v21, v21
	v_max_f32_e32 v20, 0, v20
	v_fmac_f32_e32 v18, v173, v19
	v_max_f32_e32 v22, v22, v22
	v_max_f32_e32 v21, 0, v21
	v_fmac_f32_e32 v18, v172, v20
	v_max_f32_e32 v23, v23, v23
	v_max_f32_e32 v22, 0, v22
	v_fmac_f32_e32 v18, v171, v21
	v_max_f32_e32 v24, v24, v24
	v_max_f32_e32 v23, 0, v23
	v_fmac_f32_e32 v18, v170, v22
	v_max_f32_e32 v25, v25, v25
	v_max_f32_e32 v24, 0, v24
	v_fmac_f32_e32 v18, v169, v23
	v_max_f32_e32 v26, v26, v26
	v_max_f32_e32 v25, 0, v25
	v_fmac_f32_e32 v18, v168, v24
	v_max_f32_e32 v27, v27, v27
	v_max_f32_e32 v26, 0, v26
	v_fmac_f32_e32 v18, v167, v25
	v_max_f32_e32 v28, v28, v28
	v_max_f32_e32 v27, 0, v27
	v_fmac_f32_e32 v18, v166, v26
	v_max_f32_e32 v29, v29, v29
	v_max_f32_e32 v28, 0, v28
	v_fmac_f32_e32 v18, v165, v27
	v_max_f32_e32 v30, v30, v30
	v_max_f32_e32 v29, 0, v29
	v_fmac_f32_e32 v18, v164, v28
	v_max_f32_e32 v31, v31, v31
	v_max_f32_e32 v30, 0, v30
	v_fmac_f32_e32 v18, v163, v29
	v_fmac_f32_e32 v18, v162, v30
	v_max_f32_e32 v19, 0, v31
	v_fmac_f32_e32 v18, v161, v19
	v_max_f32_e32 v19, v32, v32
	v_max_f32_e32 v19, 0, v19
	v_fmac_f32_e32 v18, v160, v19
	v_max_f32_e32 v19, v33, v33
	v_max_f32_e32 v19, 0, v19
	v_fmac_f32_e32 v18, v89, v19
	v_not_b32_e32 v19, v18
	v_or_b32_e32 v20, 0x80000000, v18
	v_cmp_gt_i32_e32 vcc, 0, v18
	s_nop 1
	v_cndmask_b32_e32 v18, v20, v19, vcc
	v_cmp_le_u32_e32 vcc, v120, v87
	s_nop 1
	v_cndmask_b32_e32 v219, 0, v18, vcc
.LBB0_501:
	s_or_b64 exec, exec, s[82:83]
	s_movk_i32 s2, 0x33f
	v_cmp_lt_u32_e32 vcc, s2, v177
	v_mov_b32_e32 v220, 0
	s_and_saveexec_b64 s[82:83], vcc
	s_cbranch_execz .LBB0_505
	s_movk_i32 s2, 0x35f
	s_waitcnt lgkmcnt(0)
	v_cmp_lt_u32_e32 vcc, s2, v177
	s_and_saveexec_b64 s[84:85], vcc
	s_cbranch_execz .LBB0_504
	s_nop 0
	global_load_lds_dwordx4 v72, s[100:101]
	s_add_u32 m0, m0, 0x400
	s_add_u32 s100, s100, 0x1a000
	s_addc_u32 s101, s101, 0
	s_nop 0
	global_load_lds_dwordx4 v73, s[100:101]
	s_add_u32 m0, m0, 0x400
	s_add_u32 s100, s100, 0x1a000
	s_addc_u32 s101, s101, 0
	s_nop 0
	global_load_lds_dwordx4 v72, s[100:101]
	s_add_u32 m0, m0, 0x400
	s_add_u32 s100, s100, 0x1a000
	s_addc_u32 s101, s101, 0
	s_nop 0
	global_load_lds_dwordx4 v73, s[100:101]
	s_add_u32 m0, m0, 0x400
	s_add_u32 s100, s100, 0x1a000
	s_addc_u32 s101, s101, 0
.LBB0_504:
	s_or_b64 exec, exec, s[84:85]
	v_mfma_f32_32x32x16_bf16 v[18:33], v[38:41], v[58:61], 0
	v_mfma_f32_32x32x16_bf16 v[18:33], v[46:49], v[54:57], v[18:33]
	v_mfma_f32_32x32x16_bf16 v[18:33], v[34:37], v[50:53], v[18:33]
	v_mfma_f32_32x32x16_bf16 v[18:33], v[42:45], v[62:65], v[18:33]
	s_waitcnt vmcnt(12)
	ds_read_b128 v[58:61], v74 offset:12288
	ds_read_b128 v[54:57], v75 offset:12288
	ds_read_b128 v[50:53], v76 offset:12288
	ds_read_b128 v[62:65], v77 offset:12288
	s_nop 8
	v_max_f32_e32 v18, v18, v18
	v_max_f32_e32 v19, v19, v19
	v_max_f32_e32 v18, 0, v18
	v_max_f32_e32 v20, v20, v20
	v_max_f32_e32 v19, 0, v19
	v_fma_f32 v18, v174, v18, 0
	v_max_f32_e32 v21, v21, v21
	v_max_f32_e32 v20, 0, v20
	v_fmac_f32_e32 v18, v173, v19
	v_max_f32_e32 v22, v22, v22
	v_max_f32_e32 v21, 0, v21
	v_fmac_f32_e32 v18, v172, v20
	v_max_f32_e32 v23, v23, v23
	v_max_f32_e32 v22, 0, v22
	v_fmac_f32_e32 v18, v171, v21
	v_max_f32_e32 v24, v24, v24
	v_max_f32_e32 v23, 0, v23
	v_fmac_f32_e32 v18, v170, v22
	v_max_f32_e32 v25, v25, v25
	v_max_f32_e32 v24, 0, v24
	v_fmac_f32_e32 v18, v169, v23
	v_max_f32_e32 v26, v26, v26
	v_max_f32_e32 v25, 0, v25
	v_fmac_f32_e32 v18, v168, v24
	v_max_f32_e32 v27, v27, v27
	v_max_f32_e32 v26, 0, v26
	v_fmac_f32_e32 v18, v167, v25
	v_max_f32_e32 v28, v28, v28
	v_max_f32_e32 v27, 0, v27
	v_fmac_f32_e32 v18, v166, v26
	v_max_f32_e32 v29, v29, v29
	v_max_f32_e32 v28, 0, v28
	v_fmac_f32_e32 v18, v165, v27
	v_max_f32_e32 v30, v30, v30
	v_max_f32_e32 v29, 0, v29
	v_fmac_f32_e32 v18, v164, v28
	v_max_f32_e32 v31, v31, v31
	v_max_f32_e32 v30, 0, v30
	v_fmac_f32_e32 v18, v163, v29
	v_fmac_f32_e32 v18, v162, v30
	v_max_f32_e32 v19, 0, v31
	v_fmac_f32_e32 v18, v161, v19
	v_max_f32_e32 v19, v32, v32
	v_max_f32_e32 v19, 0, v19
	v_fmac_f32_e32 v18, v160, v19
	v_max_f32_e32 v19, v33, v33
	v_max_f32_e32 v19, 0, v19
	v_fmac_f32_e32 v18, v89, v19
	v_not_b32_e32 v19, v18
	v_or_b32_e32 v20, 0x80000000, v18
	v_cmp_gt_i32_e32 vcc, 0, v18
	s_nop 1
	v_cndmask_b32_e32 v18, v20, v19, vcc
	v_cmp_le_u32_e32 vcc, v121, v87
	s_nop 1
	v_cndmask_b32_e32 v220, 0, v18, vcc
.LBB0_505:
	s_or_b64 exec, exec, s[82:83]
	s_movk_i32 s2, 0x35f
	v_cmp_lt_u32_e32 vcc, s2, v177
	v_mov_b32_e32 v221, 0
	s_and_saveexec_b64 s[82:83], vcc
	s_cbranch_execz .LBB0_509
	s_movk_i32 s2, 0x37f
	s_waitcnt lgkmcnt(0)
	v_cmp_lt_u32_e32 vcc, s2, v177
	s_and_saveexec_b64 s[84:85], vcc
	s_cbranch_execz .LBB0_508
	s_nop 0
	global_load_lds_dwordx4 v72, s[100:101]
	s_add_u32 m0, m0, 0x400
	s_add_u32 s100, s100, 0x1a000
	s_addc_u32 s101, s101, 0
	s_nop 0
	global_load_lds_dwordx4 v73, s[100:101]
	s_add_u32 m0, m0, 0x400
	s_add_u32 s100, s100, 0x1a000
	s_addc_u32 s101, s101, 0
	s_nop 0
	global_load_lds_dwordx4 v72, s[100:101]
	s_add_u32 m0, m0, 0x400
	s_add_u32 s100, s100, 0x1a000
	s_addc_u32 s101, s101, 0
	s_nop 0
	global_load_lds_dwordx4 v73, s[100:101]
	s_sub_u32 m0, m0, 0x3c00
	s_add_u32 s100, s100, 0x1a000
	s_addc_u32 s101, s101, 0
.LBB0_508:
	s_or_b64 exec, exec, s[84:85]
	v_mfma_f32_32x32x16_bf16 v[18:33], v[38:41], v[58:61], 0
	v_mfma_f32_32x32x16_bf16 v[18:33], v[46:49], v[54:57], v[18:33]
	v_mfma_f32_32x32x16_bf16 v[18:33], v[34:37], v[50:53], v[18:33]
	v_mfma_f32_32x32x16_bf16 v[18:33], v[42:45], v[62:65], v[18:33]
	s_waitcnt vmcnt(12)
	ds_read_b128 v[58:61], v74 offset:0
	ds_read_b128 v[54:57], v75 offset:0
	ds_read_b128 v[50:53], v76 offset:0
	ds_read_b128 v[62:65], v77 offset:0
	s_nop 8
	v_max_f32_e32 v18, v18, v18
	v_max_f32_e32 v19, v19, v19
	v_max_f32_e32 v18, 0, v18
	v_max_f32_e32 v20, v20, v20
	v_max_f32_e32 v19, 0, v19
	v_fma_f32 v18, v174, v18, 0
	v_max_f32_e32 v21, v21, v21
	v_max_f32_e32 v20, 0, v20
	v_fmac_f32_e32 v18, v173, v19
	v_max_f32_e32 v22, v22, v22
	v_max_f32_e32 v21, 0, v21
	v_fmac_f32_e32 v18, v172, v20
	v_max_f32_e32 v23, v23, v23
	v_max_f32_e32 v22, 0, v22
	v_fmac_f32_e32 v18, v171, v21
	v_max_f32_e32 v24, v24, v24
	v_max_f32_e32 v23, 0, v23
	v_fmac_f32_e32 v18, v170, v22
	v_max_f32_e32 v25, v25, v25
	v_max_f32_e32 v24, 0, v24
	v_fmac_f32_e32 v18, v169, v23
	v_max_f32_e32 v26, v26, v26
	v_max_f32_e32 v25, 0, v25
	v_fmac_f32_e32 v18, v168, v24
	v_max_f32_e32 v27, v27, v27
	v_max_f32_e32 v26, 0, v26
	v_fmac_f32_e32 v18, v167, v25
	v_max_f32_e32 v28, v28, v28
	v_max_f32_e32 v27, 0, v27
	v_fmac_f32_e32 v18, v166, v26
	v_max_f32_e32 v29, v29, v29
	v_max_f32_e32 v28, 0, v28
	v_fmac_f32_e32 v18, v165, v27
	v_max_f32_e32 v30, v30, v30
	v_max_f32_e32 v29, 0, v29
	v_fmac_f32_e32 v18, v164, v28
	v_max_f32_e32 v31, v31, v31
	v_max_f32_e32 v30, 0, v30
	v_fmac_f32_e32 v18, v163, v29
	v_fmac_f32_e32 v18, v162, v30
	v_max_f32_e32 v19, 0, v31
	v_fmac_f32_e32 v18, v161, v19
	v_max_f32_e32 v19, v32, v32
	v_max_f32_e32 v19, 0, v19
	v_fmac_f32_e32 v18, v160, v19
	v_max_f32_e32 v19, v33, v33
	v_max_f32_e32 v19, 0, v19
	v_fmac_f32_e32 v18, v89, v19
	v_not_b32_e32 v19, v18
	v_or_b32_e32 v20, 0x80000000, v18
	v_cmp_gt_i32_e32 vcc, 0, v18
	s_nop 1
	v_cndmask_b32_e32 v18, v20, v19, vcc
	v_cmp_le_u32_e32 vcc, v122, v87
	s_nop 1
	v_cndmask_b32_e32 v221, 0, v18, vcc
.LBB0_509:
	s_or_b64 exec, exec, s[82:83]
	s_movk_i32 s2, 0x37f
	v_cmp_lt_u32_e32 vcc, s2, v177
	v_mov_b32_e32 v222, 0
	s_and_saveexec_b64 s[82:83], vcc
	s_cbranch_execz .LBB0_513
	s_movk_i32 s2, 0x39f
	s_waitcnt lgkmcnt(0)
	v_cmp_lt_u32_e32 vcc, s2, v177
	s_and_saveexec_b64 s[84:85], vcc
	s_cbranch_execz .LBB0_512
	s_nop 0
	global_load_lds_dwordx4 v72, s[100:101]
	s_add_u32 m0, m0, 0x400
	s_add_u32 s100, s100, 0x1a000
	s_addc_u32 s101, s101, 0
	s_nop 0
	global_load_lds_dwordx4 v73, s[100:101]
	s_add_u32 m0, m0, 0x400
	s_add_u32 s100, s100, 0x1a000
	s_addc_u32 s101, s101, 0
	s_nop 0
	global_load_lds_dwordx4 v72, s[100:101]
	s_add_u32 m0, m0, 0x400
	s_add_u32 s100, s100, 0x1a000
	s_addc_u32 s101, s101, 0
	s_nop 0
	global_load_lds_dwordx4 v73, s[100:101]
	s_add_u32 m0, m0, 0x400
	s_add_u32 s100, s100, 0x1a000
	s_addc_u32 s101, s101, 0
.LBB0_512:
	s_or_b64 exec, exec, s[84:85]
	v_mfma_f32_32x32x16_bf16 v[18:33], v[38:41], v[58:61], 0
	v_mfma_f32_32x32x16_bf16 v[18:33], v[46:49], v[54:57], v[18:33]
	v_mfma_f32_32x32x16_bf16 v[18:33], v[34:37], v[50:53], v[18:33]
	v_mfma_f32_32x32x16_bf16 v[18:33], v[42:45], v[62:65], v[18:33]
	s_waitcnt vmcnt(12)
	ds_read_b128 v[58:61], v74 offset:4096
	ds_read_b128 v[54:57], v75 offset:4096
	ds_read_b128 v[50:53], v76 offset:4096
	ds_read_b128 v[62:65], v77 offset:4096
	s_nop 8
	v_max_f32_e32 v18, v18, v18
	v_max_f32_e32 v19, v19, v19
	v_max_f32_e32 v18, 0, v18
	v_max_f32_e32 v20, v20, v20
	v_max_f32_e32 v19, 0, v19
	v_fma_f32 v18, v174, v18, 0
	v_max_f32_e32 v21, v21, v21
	v_max_f32_e32 v20, 0, v20
	v_fmac_f32_e32 v18, v173, v19
	v_max_f32_e32 v22, v22, v22
	v_max_f32_e32 v21, 0, v21
	v_fmac_f32_e32 v18, v172, v20
	v_max_f32_e32 v23, v23, v23
	v_max_f32_e32 v22, 0, v22
	v_fmac_f32_e32 v18, v171, v21
	v_max_f32_e32 v24, v24, v24
	v_max_f32_e32 v23, 0, v23
	v_fmac_f32_e32 v18, v170, v22
	v_max_f32_e32 v25, v25, v25
	v_max_f32_e32 v24, 0, v24
	v_fmac_f32_e32 v18, v169, v23
	v_max_f32_e32 v26, v26, v26
	v_max_f32_e32 v25, 0, v25
	v_fmac_f32_e32 v18, v168, v24
	v_max_f32_e32 v27, v27, v27
	v_max_f32_e32 v26, 0, v26
	v_fmac_f32_e32 v18, v167, v25
	v_max_f32_e32 v28, v28, v28
	v_max_f32_e32 v27, 0, v27
	v_fmac_f32_e32 v18, v166, v26
	v_max_f32_e32 v29, v29, v29
	v_max_f32_e32 v28, 0, v28
	v_fmac_f32_e32 v18, v165, v27
	v_max_f32_e32 v30, v30, v30
	v_max_f32_e32 v29, 0, v29
	v_fmac_f32_e32 v18, v164, v28
	v_max_f32_e32 v31, v31, v31
	v_max_f32_e32 v30, 0, v30
	v_fmac_f32_e32 v18, v163, v29
	v_fmac_f32_e32 v18, v162, v30
	v_max_f32_e32 v19, 0, v31
	v_fmac_f32_e32 v18, v161, v19
	v_max_f32_e32 v19, v32, v32
	v_max_f32_e32 v19, 0, v19
	v_fmac_f32_e32 v18, v160, v19
	v_max_f32_e32 v19, v33, v33
	v_max_f32_e32 v19, 0, v19
	v_fmac_f32_e32 v18, v89, v19
	v_not_b32_e32 v19, v18
	v_or_b32_e32 v20, 0x80000000, v18
	v_cmp_gt_i32_e32 vcc, 0, v18
	s_nop 1
	v_cndmask_b32_e32 v18, v20, v19, vcc
	v_cmp_le_u32_e32 vcc, v123, v87
	s_nop 1
	v_cndmask_b32_e32 v222, 0, v18, vcc
.LBB0_513:
	s_or_b64 exec, exec, s[82:83]
	s_movk_i32 s2, 0x39f
	v_cmp_lt_u32_e32 vcc, s2, v177
	v_mov_b32_e32 v223, 0
	s_and_saveexec_b64 s[82:83], vcc
	s_cbranch_execz .LBB0_517
	s_movk_i32 s2, 0x3bf
	s_waitcnt lgkmcnt(0)
	v_cmp_lt_u32_e32 vcc, s2, v177
	s_and_saveexec_b64 s[84:85], vcc
	s_cbranch_execz .LBB0_516
	s_nop 0
	global_load_lds_dwordx4 v72, s[100:101]
	s_add_u32 m0, m0, 0x400
	s_add_u32 s100, s100, 0x1a000
	s_addc_u32 s101, s101, 0
	s_nop 0
	global_load_lds_dwordx4 v73, s[100:101]
	s_add_u32 m0, m0, 0x400
	s_add_u32 s100, s100, 0x1a000
	s_addc_u32 s101, s101, 0
	s_nop 0
	global_load_lds_dwordx4 v72, s[100:101]
	s_add_u32 m0, m0, 0x400
	s_add_u32 s100, s100, 0x1a000
	s_addc_u32 s101, s101, 0
	s_nop 0
	global_load_lds_dwordx4 v73, s[100:101]
	s_add_u32 m0, m0, 0x400
	s_add_u32 s100, s100, 0x1a000
	s_addc_u32 s101, s101, 0
.LBB0_516:
	s_or_b64 exec, exec, s[84:85]
	v_mfma_f32_32x32x16_bf16 v[18:33], v[38:41], v[58:61], 0
	v_mfma_f32_32x32x16_bf16 v[18:33], v[46:49], v[54:57], v[18:33]
	v_mfma_f32_32x32x16_bf16 v[18:33], v[34:37], v[50:53], v[18:33]
	v_mfma_f32_32x32x16_bf16 v[18:33], v[42:45], v[62:65], v[18:33]
	s_waitcnt vmcnt(12)
	ds_read_b128 v[58:61], v74 offset:8192
	ds_read_b128 v[54:57], v75 offset:8192
	ds_read_b128 v[50:53], v76 offset:8192
	ds_read_b128 v[62:65], v77 offset:8192
	s_nop 8
	v_max_f32_e32 v18, v18, v18
	v_max_f32_e32 v19, v19, v19
	v_max_f32_e32 v18, 0, v18
	v_max_f32_e32 v20, v20, v20
	v_max_f32_e32 v19, 0, v19
	v_fma_f32 v18, v174, v18, 0
	v_max_f32_e32 v21, v21, v21
	v_max_f32_e32 v20, 0, v20
	v_fmac_f32_e32 v18, v173, v19
	v_max_f32_e32 v22, v22, v22
	v_max_f32_e32 v21, 0, v21
	v_fmac_f32_e32 v18, v172, v20
	v_max_f32_e32 v23, v23, v23
	v_max_f32_e32 v22, 0, v22
	v_fmac_f32_e32 v18, v171, v21
	v_max_f32_e32 v24, v24, v24
	v_max_f32_e32 v23, 0, v23
	v_fmac_f32_e32 v18, v170, v22
	v_max_f32_e32 v25, v25, v25
	v_max_f32_e32 v24, 0, v24
	v_fmac_f32_e32 v18, v169, v23
	v_max_f32_e32 v26, v26, v26
	v_max_f32_e32 v25, 0, v25
	v_fmac_f32_e32 v18, v168, v24
	v_max_f32_e32 v27, v27, v27
	v_max_f32_e32 v26, 0, v26
	v_fmac_f32_e32 v18, v167, v25
	v_max_f32_e32 v28, v28, v28
	v_max_f32_e32 v27, 0, v27
	v_fmac_f32_e32 v18, v166, v26
	v_max_f32_e32 v29, v29, v29
	v_max_f32_e32 v28, 0, v28
	v_fmac_f32_e32 v18, v165, v27
	v_max_f32_e32 v30, v30, v30
	v_max_f32_e32 v29, 0, v29
	v_fmac_f32_e32 v18, v164, v28
	v_max_f32_e32 v31, v31, v31
	v_max_f32_e32 v30, 0, v30
	v_fmac_f32_e32 v18, v163, v29
	v_fmac_f32_e32 v18, v162, v30
	v_max_f32_e32 v19, 0, v31
	v_fmac_f32_e32 v18, v161, v19
	v_max_f32_e32 v19, v32, v32
	v_max_f32_e32 v19, 0, v19
	v_fmac_f32_e32 v18, v160, v19
	v_max_f32_e32 v19, v33, v33
	v_max_f32_e32 v19, 0, v19
	v_fmac_f32_e32 v18, v89, v19
	v_not_b32_e32 v19, v18
	v_or_b32_e32 v20, 0x80000000, v18
	v_cmp_gt_i32_e32 vcc, 0, v18
	s_nop 1
	v_cndmask_b32_e32 v18, v20, v19, vcc
	v_cmp_le_u32_e32 vcc, v124, v87
	s_nop 1
	v_cndmask_b32_e32 v223, 0, v18, vcc
.LBB0_517:
	s_or_b64 exec, exec, s[82:83]
	s_movk_i32 s2, 0x3bf
	v_cmp_lt_u32_e32 vcc, s2, v177
	v_mov_b32_e32 v224, 0
	s_and_saveexec_b64 s[82:83], vcc
	s_cbranch_execz .LBB0_521
	s_movk_i32 s2, 0x3df
	s_waitcnt lgkmcnt(0)
	v_cmp_lt_u32_e32 vcc, s2, v177
	s_and_saveexec_b64 s[84:85], vcc
	s_cbranch_execz .LBB0_520
	s_nop 0
	global_load_lds_dwordx4 v72, s[100:101]
	s_add_u32 m0, m0, 0x400
	s_add_u32 s100, s100, 0x1a000
	s_addc_u32 s101, s101, 0
	s_nop 0
	global_load_lds_dwordx4 v73, s[100:101]
	s_add_u32 m0, m0, 0x400
	s_add_u32 s100, s100, 0x1a000
	s_addc_u32 s101, s101, 0
	s_nop 0
	global_load_lds_dwordx4 v72, s[100:101]
	s_add_u32 m0, m0, 0x400
	s_add_u32 s100, s100, 0x1a000
	s_addc_u32 s101, s101, 0
	s_nop 0
	global_load_lds_dwordx4 v73, s[100:101]
	s_add_u32 m0, m0, 0x400
	s_add_u32 s100, s100, 0x1a000
	s_addc_u32 s101, s101, 0
.LBB0_520:
	s_or_b64 exec, exec, s[84:85]
	v_mfma_f32_32x32x16_bf16 v[18:33], v[38:41], v[58:61], 0
	v_mfma_f32_32x32x16_bf16 v[18:33], v[46:49], v[54:57], v[18:33]
	v_mfma_f32_32x32x16_bf16 v[18:33], v[34:37], v[50:53], v[18:33]
	v_mfma_f32_32x32x16_bf16 v[18:33], v[42:45], v[62:65], v[18:33]
	s_waitcnt vmcnt(12)
	ds_read_b128 v[58:61], v74 offset:12288
	ds_read_b128 v[54:57], v75 offset:12288
	ds_read_b128 v[50:53], v76 offset:12288
	ds_read_b128 v[62:65], v77 offset:12288
	s_nop 8
	v_max_f32_e32 v18, v18, v18
	v_max_f32_e32 v19, v19, v19
	v_max_f32_e32 v18, 0, v18
	v_max_f32_e32 v20, v20, v20
	v_max_f32_e32 v19, 0, v19
	v_fma_f32 v18, v174, v18, 0
	v_max_f32_e32 v21, v21, v21
	v_max_f32_e32 v20, 0, v20
	v_fmac_f32_e32 v18, v173, v19
	v_max_f32_e32 v22, v22, v22
	v_max_f32_e32 v21, 0, v21
	v_fmac_f32_e32 v18, v172, v20
	v_max_f32_e32 v23, v23, v23
	v_max_f32_e32 v22, 0, v22
	v_fmac_f32_e32 v18, v171, v21
	v_max_f32_e32 v24, v24, v24
	v_max_f32_e32 v23, 0, v23
	v_fmac_f32_e32 v18, v170, v22
	v_max_f32_e32 v25, v25, v25
	v_max_f32_e32 v24, 0, v24
	v_fmac_f32_e32 v18, v169, v23
	v_max_f32_e32 v26, v26, v26
	v_max_f32_e32 v25, 0, v25
	v_fmac_f32_e32 v18, v168, v24
	v_max_f32_e32 v27, v27, v27
	v_max_f32_e32 v26, 0, v26
	v_fmac_f32_e32 v18, v167, v25
	v_max_f32_e32 v28, v28, v28
	v_max_f32_e32 v27, 0, v27
	v_fmac_f32_e32 v18, v166, v26
	v_max_f32_e32 v29, v29, v29
	v_max_f32_e32 v28, 0, v28
	v_fmac_f32_e32 v18, v165, v27
	v_max_f32_e32 v30, v30, v30
	v_max_f32_e32 v29, 0, v29
	v_fmac_f32_e32 v18, v164, v28
	v_max_f32_e32 v31, v31, v31
	v_max_f32_e32 v30, 0, v30
	v_fmac_f32_e32 v18, v163, v29
	v_fmac_f32_e32 v18, v162, v30
	v_max_f32_e32 v19, 0, v31
	v_fmac_f32_e32 v18, v161, v19
	v_max_f32_e32 v19, v32, v32
	v_max_f32_e32 v19, 0, v19
	v_fmac_f32_e32 v18, v160, v19
	v_max_f32_e32 v19, v33, v33
	v_max_f32_e32 v19, 0, v19
	v_fmac_f32_e32 v18, v89, v19
	v_not_b32_e32 v19, v18
	v_or_b32_e32 v20, 0x80000000, v18
	v_cmp_gt_i32_e32 vcc, 0, v18
	s_nop 1
	v_cndmask_b32_e32 v18, v20, v19, vcc
	v_cmp_le_u32_e32 vcc, v125, v87
	s_nop 1
	v_cndmask_b32_e32 v224, 0, v18, vcc
.LBB0_521:
	s_or_b64 exec, exec, s[82:83]
	s_movk_i32 s2, 0x3df
	v_cmp_lt_u32_e32 vcc, s2, v177
	v_mov_b32_e32 v225, 0
	s_and_saveexec_b64 s[82:83], vcc
	s_cbranch_execz .LBB0_525
	s_movk_i32 s2, 0x3ff
	s_waitcnt lgkmcnt(0)
	v_cmp_lt_u32_e32 vcc, s2, v177
	s_and_saveexec_b64 s[84:85], vcc
	s_cbranch_execz .LBB0_524
	s_nop 0
	global_load_lds_dwordx4 v72, s[100:101]
	s_add_u32 m0, m0, 0x400
	s_add_u32 s100, s100, 0x1a000
	s_addc_u32 s101, s101, 0
	s_nop 0
	global_load_lds_dwordx4 v73, s[100:101]
	s_add_u32 m0, m0, 0x400
	s_add_u32 s100, s100, 0x1a000
	s_addc_u32 s101, s101, 0
	s_nop 0
	global_load_lds_dwordx4 v72, s[100:101]
	s_add_u32 m0, m0, 0x400
	s_add_u32 s100, s100, 0x1a000
	s_addc_u32 s101, s101, 0
	s_nop 0
	global_load_lds_dwordx4 v73, s[100:101]
	s_sub_u32 m0, m0, 0x3c00
	s_add_u32 s100, s100, 0x1a000
	s_addc_u32 s101, s101, 0
.LBB0_524:
	s_or_b64 exec, exec, s[84:85]
	v_mfma_f32_32x32x16_bf16 v[18:33], v[38:41], v[58:61], 0
	v_mfma_f32_32x32x16_bf16 v[18:33], v[46:49], v[54:57], v[18:33]
	v_mfma_f32_32x32x16_bf16 v[18:33], v[34:37], v[50:53], v[18:33]
	v_mfma_f32_32x32x16_bf16 v[18:33], v[42:45], v[62:65], v[18:33]
	s_waitcnt vmcnt(12)
	ds_read_b128 v[58:61], v74 offset:0
	ds_read_b128 v[54:57], v75 offset:0
	ds_read_b128 v[50:53], v76 offset:0
	ds_read_b128 v[62:65], v77 offset:0
	s_nop 8
	v_max_f32_e32 v18, v18, v18
	v_max_f32_e32 v19, v19, v19
	v_max_f32_e32 v18, 0, v18
	v_max_f32_e32 v20, v20, v20
	v_max_f32_e32 v19, 0, v19
	v_fma_f32 v18, v174, v18, 0
	v_max_f32_e32 v21, v21, v21
	v_max_f32_e32 v20, 0, v20
	v_fmac_f32_e32 v18, v173, v19
	v_max_f32_e32 v22, v22, v22
	v_max_f32_e32 v21, 0, v21
	v_fmac_f32_e32 v18, v172, v20
	v_max_f32_e32 v23, v23, v23
	v_max_f32_e32 v22, 0, v22
	v_fmac_f32_e32 v18, v171, v21
	v_max_f32_e32 v24, v24, v24
	v_max_f32_e32 v23, 0, v23
	v_fmac_f32_e32 v18, v170, v22
	v_max_f32_e32 v25, v25, v25
	v_max_f32_e32 v24, 0, v24
	v_fmac_f32_e32 v18, v169, v23
	v_max_f32_e32 v26, v26, v26
	v_max_f32_e32 v25, 0, v25
	v_fmac_f32_e32 v18, v168, v24
	v_max_f32_e32 v27, v27, v27
	v_max_f32_e32 v26, 0, v26
	v_fmac_f32_e32 v18, v167, v25
	v_max_f32_e32 v28, v28, v28
	v_max_f32_e32 v27, 0, v27
	v_fmac_f32_e32 v18, v166, v26
	v_max_f32_e32 v29, v29, v29
	v_max_f32_e32 v28, 0, v28
	v_fmac_f32_e32 v18, v165, v27
	v_max_f32_e32 v30, v30, v30
	v_max_f32_e32 v29, 0, v29
	v_fmac_f32_e32 v18, v164, v28
	v_max_f32_e32 v31, v31, v31
	v_max_f32_e32 v30, 0, v30
	v_fmac_f32_e32 v18, v163, v29
	v_fmac_f32_e32 v18, v162, v30
	v_max_f32_e32 v19, 0, v31
	v_fmac_f32_e32 v18, v161, v19
	v_max_f32_e32 v19, v32, v32
	v_max_f32_e32 v19, 0, v19
	v_fmac_f32_e32 v18, v160, v19
	v_max_f32_e32 v19, v33, v33
	v_max_f32_e32 v19, 0, v19
	v_fmac_f32_e32 v18, v89, v19
	v_not_b32_e32 v19, v18
	v_or_b32_e32 v20, 0x80000000, v18
	v_cmp_gt_i32_e32 vcc, 0, v18
	s_nop 1
	v_cndmask_b32_e32 v18, v20, v19, vcc
	v_cmp_le_u32_e32 vcc, v126, v87
	s_nop 1
	v_cndmask_b32_e32 v225, 0, v18, vcc
.LBB0_525:
	s_or_b64 exec, exec, s[82:83]
	s_movk_i32 s2, 0x3ff
	v_cmp_lt_u32_e32 vcc, s2, v177
	v_mov_b32_e32 v226, 0
	s_and_saveexec_b64 s[82:83], vcc
	s_cbranch_execz .LBB0_529
	s_movk_i32 s2, 0x41f
	s_waitcnt lgkmcnt(0)
	v_cmp_lt_u32_e32 vcc, s2, v177
	s_and_saveexec_b64 s[84:85], vcc
	s_cbranch_execz .LBB0_528
	s_nop 0
	global_load_lds_dwordx4 v72, s[100:101]
	s_add_u32 m0, m0, 0x400
	s_add_u32 s100, s100, 0x1a000
	s_addc_u32 s101, s101, 0
	s_nop 0
	global_load_lds_dwordx4 v73, s[100:101]
	s_add_u32 m0, m0, 0x400
	s_add_u32 s100, s100, 0x1a000
	s_addc_u32 s101, s101, 0
	s_nop 0
	global_load_lds_dwordx4 v72, s[100:101]
	s_add_u32 m0, m0, 0x400
	s_add_u32 s100, s100, 0x1a000
	s_addc_u32 s101, s101, 0
	s_nop 0
	global_load_lds_dwordx4 v73, s[100:101]
	s_add_u32 m0, m0, 0x400
	s_add_u32 s100, s100, 0x1a000
	s_addc_u32 s101, s101, 0
.LBB0_528:
	s_or_b64 exec, exec, s[84:85]
	v_mfma_f32_32x32x16_bf16 v[18:33], v[38:41], v[58:61], 0
	v_mfma_f32_32x32x16_bf16 v[18:33], v[46:49], v[54:57], v[18:33]
	v_mfma_f32_32x32x16_bf16 v[18:33], v[34:37], v[50:53], v[18:33]
	v_mfma_f32_32x32x16_bf16 v[18:33], v[42:45], v[62:65], v[18:33]
	s_waitcnt vmcnt(12)
	ds_read_b128 v[58:61], v74 offset:4096
	ds_read_b128 v[54:57], v75 offset:4096
	ds_read_b128 v[50:53], v76 offset:4096
	ds_read_b128 v[62:65], v77 offset:4096
	s_nop 8
	v_max_f32_e32 v18, v18, v18
	v_max_f32_e32 v19, v19, v19
	v_max_f32_e32 v18, 0, v18
	v_max_f32_e32 v20, v20, v20
	v_max_f32_e32 v19, 0, v19
	v_fma_f32 v18, v174, v18, 0
	v_max_f32_e32 v21, v21, v21
	v_max_f32_e32 v20, 0, v20
	v_fmac_f32_e32 v18, v173, v19
	v_max_f32_e32 v22, v22, v22
	v_max_f32_e32 v21, 0, v21
	v_fmac_f32_e32 v18, v172, v20
	v_max_f32_e32 v23, v23, v23
	v_max_f32_e32 v22, 0, v22
	v_fmac_f32_e32 v18, v171, v21
	v_max_f32_e32 v24, v24, v24
	v_max_f32_e32 v23, 0, v23
	v_fmac_f32_e32 v18, v170, v22
	v_max_f32_e32 v25, v25, v25
	v_max_f32_e32 v24, 0, v24
	v_fmac_f32_e32 v18, v169, v23
	v_max_f32_e32 v26, v26, v26
	v_max_f32_e32 v25, 0, v25
	v_fmac_f32_e32 v18, v168, v24
	v_max_f32_e32 v27, v27, v27
	v_max_f32_e32 v26, 0, v26
	v_fmac_f32_e32 v18, v167, v25
	v_max_f32_e32 v28, v28, v28
	v_max_f32_e32 v27, 0, v27
	v_fmac_f32_e32 v18, v166, v26
	v_max_f32_e32 v29, v29, v29
	v_max_f32_e32 v28, 0, v28
	v_fmac_f32_e32 v18, v165, v27
	v_max_f32_e32 v30, v30, v30
	v_max_f32_e32 v29, 0, v29
	v_fmac_f32_e32 v18, v164, v28
	v_max_f32_e32 v31, v31, v31
	v_max_f32_e32 v30, 0, v30
	v_fmac_f32_e32 v18, v163, v29
	v_fmac_f32_e32 v18, v162, v30
	v_max_f32_e32 v19, 0, v31
	v_fmac_f32_e32 v18, v161, v19
	v_max_f32_e32 v19, v32, v32
	v_max_f32_e32 v19, 0, v19
	v_fmac_f32_e32 v18, v160, v19
	v_max_f32_e32 v19, v33, v33
	v_max_f32_e32 v19, 0, v19
	v_fmac_f32_e32 v18, v89, v19
	v_not_b32_e32 v19, v18
	v_or_b32_e32 v20, 0x80000000, v18
	v_cmp_gt_i32_e32 vcc, 0, v18
	s_nop 1
	v_cndmask_b32_e32 v18, v20, v19, vcc
	v_cmp_le_u32_e32 vcc, v127, v87
	s_nop 1
	v_cndmask_b32_e32 v226, 0, v18, vcc
.LBB0_529:
	s_or_b64 exec, exec, s[82:83]
	s_movk_i32 s2, 0x41f
	v_cmp_lt_u32_e32 vcc, s2, v177
	v_mov_b32_e32 v227, 0
	s_and_saveexec_b64 s[82:83], vcc
	s_cbranch_execz .LBB0_533
	s_movk_i32 s2, 0x43f
	s_waitcnt lgkmcnt(0)
	v_cmp_lt_u32_e32 vcc, s2, v177
	s_and_saveexec_b64 s[84:85], vcc
	s_cbranch_execz .LBB0_532
	s_nop 0
	global_load_lds_dwordx4 v72, s[100:101]
	s_add_u32 m0, m0, 0x400
	s_add_u32 s100, s100, 0x1a000
	s_addc_u32 s101, s101, 0
	s_nop 0
	global_load_lds_dwordx4 v73, s[100:101]
	s_add_u32 m0, m0, 0x400
	s_add_u32 s100, s100, 0x1a000
	s_addc_u32 s101, s101, 0
	s_nop 0
	global_load_lds_dwordx4 v72, s[100:101]
	s_add_u32 m0, m0, 0x400
	s_add_u32 s100, s100, 0x1a000
	s_addc_u32 s101, s101, 0
	s_nop 0
	global_load_lds_dwordx4 v73, s[100:101]
	s_add_u32 m0, m0, 0x400
	s_add_u32 s100, s100, 0x1a000
	s_addc_u32 s101, s101, 0
.LBB0_532:
	s_or_b64 exec, exec, s[84:85]
	v_mfma_f32_32x32x16_bf16 v[18:33], v[38:41], v[58:61], 0
	v_mfma_f32_32x32x16_bf16 v[18:33], v[46:49], v[54:57], v[18:33]
	v_mfma_f32_32x32x16_bf16 v[18:33], v[34:37], v[50:53], v[18:33]
	v_mfma_f32_32x32x16_bf16 v[18:33], v[42:45], v[62:65], v[18:33]
	s_waitcnt vmcnt(12)
	ds_read_b128 v[58:61], v74 offset:8192
	ds_read_b128 v[54:57], v75 offset:8192
	ds_read_b128 v[50:53], v76 offset:8192
	ds_read_b128 v[62:65], v77 offset:8192
	s_nop 8
	v_max_f32_e32 v18, v18, v18
	v_max_f32_e32 v19, v19, v19
	v_max_f32_e32 v18, 0, v18
	v_max_f32_e32 v20, v20, v20
	v_max_f32_e32 v19, 0, v19
	v_fma_f32 v18, v174, v18, 0
	v_max_f32_e32 v21, v21, v21
	v_max_f32_e32 v20, 0, v20
	v_fmac_f32_e32 v18, v173, v19
	v_max_f32_e32 v22, v22, v22
	v_max_f32_e32 v21, 0, v21
	v_fmac_f32_e32 v18, v172, v20
	v_max_f32_e32 v23, v23, v23
	v_max_f32_e32 v22, 0, v22
	v_fmac_f32_e32 v18, v171, v21
	v_max_f32_e32 v24, v24, v24
	v_max_f32_e32 v23, 0, v23
	v_fmac_f32_e32 v18, v170, v22
	v_max_f32_e32 v25, v25, v25
	v_max_f32_e32 v24, 0, v24
	v_fmac_f32_e32 v18, v169, v23
	v_max_f32_e32 v26, v26, v26
	v_max_f32_e32 v25, 0, v25
	v_fmac_f32_e32 v18, v168, v24
	v_max_f32_e32 v27, v27, v27
	v_max_f32_e32 v26, 0, v26
	v_fmac_f32_e32 v18, v167, v25
	v_max_f32_e32 v28, v28, v28
	v_max_f32_e32 v27, 0, v27
	v_fmac_f32_e32 v18, v166, v26
	v_max_f32_e32 v29, v29, v29
	v_max_f32_e32 v28, 0, v28
	v_fmac_f32_e32 v18, v165, v27
	v_max_f32_e32 v30, v30, v30
	v_max_f32_e32 v29, 0, v29
	v_fmac_f32_e32 v18, v164, v28
	v_max_f32_e32 v31, v31, v31
	v_max_f32_e32 v30, 0, v30
	v_fmac_f32_e32 v18, v163, v29
	v_fmac_f32_e32 v18, v162, v30
	v_max_f32_e32 v19, 0, v31
	v_fmac_f32_e32 v18, v161, v19
	v_max_f32_e32 v19, v32, v32
	v_max_f32_e32 v19, 0, v19
	v_fmac_f32_e32 v18, v160, v19
	v_max_f32_e32 v19, v33, v33
	v_max_f32_e32 v19, 0, v19
	v_fmac_f32_e32 v18, v89, v19
	v_not_b32_e32 v19, v18
	v_or_b32_e32 v20, 0x80000000, v18
	v_cmp_gt_i32_e32 vcc, 0, v18
	s_nop 1
	v_cndmask_b32_e32 v18, v20, v19, vcc
	v_cmp_le_u32_e32 vcc, v128, v87
	s_nop 1
	v_cndmask_b32_e32 v227, 0, v18, vcc
.LBB0_533:
	s_or_b64 exec, exec, s[82:83]
	s_movk_i32 s2, 0x43f
	v_cmp_lt_u32_e32 vcc, s2, v177
	v_mov_b32_e32 v228, 0
	s_and_saveexec_b64 s[82:83], vcc
	s_cbranch_execz .LBB0_537
	s_movk_i32 s2, 0x45f
	s_waitcnt lgkmcnt(0)
	v_cmp_lt_u32_e32 vcc, s2, v177
	s_and_saveexec_b64 s[84:85], vcc
	s_cbranch_execz .LBB0_536
	s_nop 0
	global_load_lds_dwordx4 v72, s[100:101]
	s_add_u32 m0, m0, 0x400
	s_add_u32 s100, s100, 0x1a000
	s_addc_u32 s101, s101, 0
	s_nop 0
	global_load_lds_dwordx4 v73, s[100:101]
	s_add_u32 m0, m0, 0x400
	s_add_u32 s100, s100, 0x1a000
	s_addc_u32 s101, s101, 0
	s_nop 0
	global_load_lds_dwordx4 v72, s[100:101]
	s_add_u32 m0, m0, 0x400
	s_add_u32 s100, s100, 0x1a000
	s_addc_u32 s101, s101, 0
	s_nop 0
	global_load_lds_dwordx4 v73, s[100:101]
	s_add_u32 m0, m0, 0x400
	s_add_u32 s100, s100, 0x1a000
	s_addc_u32 s101, s101, 0
.LBB0_536:
	s_or_b64 exec, exec, s[84:85]
	v_mfma_f32_32x32x16_bf16 v[18:33], v[38:41], v[58:61], 0
	v_mfma_f32_32x32x16_bf16 v[18:33], v[46:49], v[54:57], v[18:33]
	v_mfma_f32_32x32x16_bf16 v[18:33], v[34:37], v[50:53], v[18:33]
	v_mfma_f32_32x32x16_bf16 v[18:33], v[42:45], v[62:65], v[18:33]
	s_waitcnt vmcnt(12)
	ds_read_b128 v[58:61], v74 offset:12288
	ds_read_b128 v[54:57], v75 offset:12288
	ds_read_b128 v[50:53], v76 offset:12288
	ds_read_b128 v[62:65], v77 offset:12288
	s_nop 8
	v_max_f32_e32 v18, v18, v18
	v_max_f32_e32 v19, v19, v19
	v_max_f32_e32 v18, 0, v18
	v_max_f32_e32 v20, v20, v20
	v_max_f32_e32 v19, 0, v19
	v_fma_f32 v18, v174, v18, 0
	v_max_f32_e32 v21, v21, v21
	v_max_f32_e32 v20, 0, v20
	v_fmac_f32_e32 v18, v173, v19
	v_max_f32_e32 v22, v22, v22
	v_max_f32_e32 v21, 0, v21
	v_fmac_f32_e32 v18, v172, v20
	v_max_f32_e32 v23, v23, v23
	v_max_f32_e32 v22, 0, v22
	v_fmac_f32_e32 v18, v171, v21
	v_max_f32_e32 v24, v24, v24
	v_max_f32_e32 v23, 0, v23
	v_fmac_f32_e32 v18, v170, v22
	v_max_f32_e32 v25, v25, v25
	v_max_f32_e32 v24, 0, v24
	v_fmac_f32_e32 v18, v169, v23
	v_max_f32_e32 v26, v26, v26
	v_max_f32_e32 v25, 0, v25
	v_fmac_f32_e32 v18, v168, v24
	v_max_f32_e32 v27, v27, v27
	v_max_f32_e32 v26, 0, v26
	v_fmac_f32_e32 v18, v167, v25
	v_max_f32_e32 v28, v28, v28
	v_max_f32_e32 v27, 0, v27
	v_fmac_f32_e32 v18, v166, v26
	v_max_f32_e32 v29, v29, v29
	v_max_f32_e32 v28, 0, v28
	v_fmac_f32_e32 v18, v165, v27
	v_max_f32_e32 v30, v30, v30
	v_max_f32_e32 v29, 0, v29
	v_fmac_f32_e32 v18, v164, v28
	v_max_f32_e32 v31, v31, v31
	v_max_f32_e32 v30, 0, v30
	v_fmac_f32_e32 v18, v163, v29
	v_fmac_f32_e32 v18, v162, v30
	v_max_f32_e32 v19, 0, v31
	v_fmac_f32_e32 v18, v161, v19
	v_max_f32_e32 v19, v32, v32
	v_max_f32_e32 v19, 0, v19
	v_fmac_f32_e32 v18, v160, v19
	v_max_f32_e32 v19, v33, v33
	v_max_f32_e32 v19, 0, v19
	v_fmac_f32_e32 v18, v89, v19
	v_not_b32_e32 v19, v18
	v_or_b32_e32 v20, 0x80000000, v18
	v_cmp_gt_i32_e32 vcc, 0, v18
	s_nop 1
	v_cndmask_b32_e32 v18, v20, v19, vcc
	v_cmp_le_u32_e32 vcc, v129, v87
	s_nop 1
	v_cndmask_b32_e32 v228, 0, v18, vcc
.LBB0_537:
	s_or_b64 exec, exec, s[82:83]
	s_movk_i32 s2, 0x45f
	v_cmp_lt_u32_e32 vcc, s2, v177
	v_mov_b32_e32 v229, 0
	s_and_saveexec_b64 s[82:83], vcc
	s_cbranch_execz .LBB0_541
	s_movk_i32 s2, 0x47f
	s_waitcnt lgkmcnt(0)
	v_cmp_lt_u32_e32 vcc, s2, v177
	s_and_saveexec_b64 s[84:85], vcc
	s_cbranch_execz .LBB0_540
	s_nop 0
	global_load_lds_dwordx4 v72, s[100:101]
	s_add_u32 m0, m0, 0x400
	s_add_u32 s100, s100, 0x1a000
	s_addc_u32 s101, s101, 0
	s_nop 0
	global_load_lds_dwordx4 v73, s[100:101]
	s_add_u32 m0, m0, 0x400
	s_add_u32 s100, s100, 0x1a000
	s_addc_u32 s101, s101, 0
	s_nop 0
	global_load_lds_dwordx4 v72, s[100:101]
	s_add_u32 m0, m0, 0x400
	s_add_u32 s100, s100, 0x1a000
	s_addc_u32 s101, s101, 0
	s_nop 0
	global_load_lds_dwordx4 v73, s[100:101]
	s_sub_u32 m0, m0, 0x3c00
	s_add_u32 s100, s100, 0x1a000
	s_addc_u32 s101, s101, 0
.LBB0_540:
	s_or_b64 exec, exec, s[84:85]
	v_mfma_f32_32x32x16_bf16 v[18:33], v[38:41], v[58:61], 0
	v_mfma_f32_32x32x16_bf16 v[18:33], v[46:49], v[54:57], v[18:33]
	v_mfma_f32_32x32x16_bf16 v[18:33], v[34:37], v[50:53], v[18:33]
	v_mfma_f32_32x32x16_bf16 v[18:33], v[42:45], v[62:65], v[18:33]
	s_waitcnt vmcnt(12)
	ds_read_b128 v[58:61], v74 offset:0
	ds_read_b128 v[54:57], v75 offset:0
	ds_read_b128 v[50:53], v76 offset:0
	ds_read_b128 v[62:65], v77 offset:0
	s_nop 8
	v_max_f32_e32 v18, v18, v18
	v_max_f32_e32 v19, v19, v19
	v_max_f32_e32 v18, 0, v18
	v_max_f32_e32 v20, v20, v20
	v_max_f32_e32 v19, 0, v19
	v_fma_f32 v18, v174, v18, 0
	v_max_f32_e32 v21, v21, v21
	v_max_f32_e32 v20, 0, v20
	v_fmac_f32_e32 v18, v173, v19
	v_max_f32_e32 v22, v22, v22
	v_max_f32_e32 v21, 0, v21
	v_fmac_f32_e32 v18, v172, v20
	v_max_f32_e32 v23, v23, v23
	v_max_f32_e32 v22, 0, v22
	v_fmac_f32_e32 v18, v171, v21
	v_max_f32_e32 v24, v24, v24
	v_max_f32_e32 v23, 0, v23
	v_fmac_f32_e32 v18, v170, v22
	v_max_f32_e32 v25, v25, v25
	v_max_f32_e32 v24, 0, v24
	v_fmac_f32_e32 v18, v169, v23
	v_max_f32_e32 v26, v26, v26
	v_max_f32_e32 v25, 0, v25
	v_fmac_f32_e32 v18, v168, v24
	v_max_f32_e32 v27, v27, v27
	v_max_f32_e32 v26, 0, v26
	v_fmac_f32_e32 v18, v167, v25
	v_max_f32_e32 v28, v28, v28
	v_max_f32_e32 v27, 0, v27
	v_fmac_f32_e32 v18, v166, v26
	v_max_f32_e32 v29, v29, v29
	v_max_f32_e32 v28, 0, v28
	v_fmac_f32_e32 v18, v165, v27
	v_max_f32_e32 v30, v30, v30
	v_max_f32_e32 v29, 0, v29
	v_fmac_f32_e32 v18, v164, v28
	v_max_f32_e32 v31, v31, v31
	v_max_f32_e32 v30, 0, v30
	v_fmac_f32_e32 v18, v163, v29
	v_fmac_f32_e32 v18, v162, v30
	v_max_f32_e32 v19, 0, v31
	v_fmac_f32_e32 v18, v161, v19
	v_max_f32_e32 v19, v32, v32
	v_max_f32_e32 v19, 0, v19
	v_fmac_f32_e32 v18, v160, v19
	v_max_f32_e32 v19, v33, v33
	v_max_f32_e32 v19, 0, v19
	v_fmac_f32_e32 v18, v89, v19
	v_not_b32_e32 v19, v18
	v_or_b32_e32 v20, 0x80000000, v18
	v_cmp_gt_i32_e32 vcc, 0, v18
	s_nop 1
	v_cndmask_b32_e32 v18, v20, v19, vcc
	v_cmp_le_u32_e32 vcc, v130, v87
	s_nop 1
	v_cndmask_b32_e32 v229, 0, v18, vcc
.LBB0_541:
	s_or_b64 exec, exec, s[82:83]
	s_movk_i32 s2, 0x47f
	v_cmp_lt_u32_e32 vcc, s2, v177
	v_mov_b32_e32 v230, 0
	s_and_saveexec_b64 s[82:83], vcc
	s_cbranch_execz .LBB0_545
	s_movk_i32 s2, 0x49f
	s_waitcnt lgkmcnt(0)
	v_cmp_lt_u32_e32 vcc, s2, v177
	s_and_saveexec_b64 s[84:85], vcc
	s_cbranch_execz .LBB0_544
	s_nop 0
	global_load_lds_dwordx4 v72, s[100:101]
	s_add_u32 m0, m0, 0x400
	s_add_u32 s100, s100, 0x1a000
	s_addc_u32 s101, s101, 0
	s_nop 0
	global_load_lds_dwordx4 v73, s[100:101]
	s_add_u32 m0, m0, 0x400
	s_add_u32 s100, s100, 0x1a000
	s_addc_u32 s101, s101, 0
	s_nop 0
	global_load_lds_dwordx4 v72, s[100:101]
	s_add_u32 m0, m0, 0x400
	s_add_u32 s100, s100, 0x1a000
	s_addc_u32 s101, s101, 0
	s_nop 0
	global_load_lds_dwordx4 v73, s[100:101]
	s_add_u32 m0, m0, 0x400
	s_add_u32 s100, s100, 0x1a000
	s_addc_u32 s101, s101, 0
.LBB0_544:
	s_or_b64 exec, exec, s[84:85]
	v_mfma_f32_32x32x16_bf16 v[18:33], v[38:41], v[58:61], 0
	v_mfma_f32_32x32x16_bf16 v[18:33], v[46:49], v[54:57], v[18:33]
	v_mfma_f32_32x32x16_bf16 v[18:33], v[34:37], v[50:53], v[18:33]
	v_mfma_f32_32x32x16_bf16 v[18:33], v[42:45], v[62:65], v[18:33]
	s_waitcnt vmcnt(12)
	ds_read_b128 v[58:61], v74 offset:4096
	ds_read_b128 v[54:57], v75 offset:4096
	ds_read_b128 v[50:53], v76 offset:4096
	ds_read_b128 v[62:65], v77 offset:4096
	s_nop 8
	v_max_f32_e32 v18, v18, v18
	v_max_f32_e32 v19, v19, v19
	v_max_f32_e32 v18, 0, v18
	v_max_f32_e32 v20, v20, v20
	v_max_f32_e32 v19, 0, v19
	v_fma_f32 v18, v174, v18, 0
	v_max_f32_e32 v21, v21, v21
	v_max_f32_e32 v20, 0, v20
	v_fmac_f32_e32 v18, v173, v19
	v_max_f32_e32 v22, v22, v22
	v_max_f32_e32 v21, 0, v21
	v_fmac_f32_e32 v18, v172, v20
	v_max_f32_e32 v23, v23, v23
	v_max_f32_e32 v22, 0, v22
	v_fmac_f32_e32 v18, v171, v21
	v_max_f32_e32 v24, v24, v24
	v_max_f32_e32 v23, 0, v23
	v_fmac_f32_e32 v18, v170, v22
	v_max_f32_e32 v25, v25, v25
	v_max_f32_e32 v24, 0, v24
	v_fmac_f32_e32 v18, v169, v23
	v_max_f32_e32 v26, v26, v26
	v_max_f32_e32 v25, 0, v25
	v_fmac_f32_e32 v18, v168, v24
	v_max_f32_e32 v27, v27, v27
	v_max_f32_e32 v26, 0, v26
	v_fmac_f32_e32 v18, v167, v25
	v_max_f32_e32 v28, v28, v28
	v_max_f32_e32 v27, 0, v27
	v_fmac_f32_e32 v18, v166, v26
	v_max_f32_e32 v29, v29, v29
	v_max_f32_e32 v28, 0, v28
	v_fmac_f32_e32 v18, v165, v27
	v_max_f32_e32 v30, v30, v30
	v_max_f32_e32 v29, 0, v29
	v_fmac_f32_e32 v18, v164, v28
	v_max_f32_e32 v31, v31, v31
	v_max_f32_e32 v30, 0, v30
	v_fmac_f32_e32 v18, v163, v29
	v_fmac_f32_e32 v18, v162, v30
	v_max_f32_e32 v19, 0, v31
	v_fmac_f32_e32 v18, v161, v19
	v_max_f32_e32 v19, v32, v32
	v_max_f32_e32 v19, 0, v19
	v_fmac_f32_e32 v18, v160, v19
	v_max_f32_e32 v19, v33, v33
	v_max_f32_e32 v19, 0, v19
	v_fmac_f32_e32 v18, v89, v19
	v_not_b32_e32 v19, v18
	v_or_b32_e32 v20, 0x80000000, v18
	v_cmp_gt_i32_e32 vcc, 0, v18
	s_nop 1
	v_cndmask_b32_e32 v18, v20, v19, vcc
	v_cmp_le_u32_e32 vcc, v131, v87
	s_nop 1
	v_cndmask_b32_e32 v230, 0, v18, vcc
.LBB0_545:
	s_or_b64 exec, exec, s[82:83]
	s_movk_i32 s2, 0x49f
	v_cmp_lt_u32_e32 vcc, s2, v177
	v_mov_b32_e32 v231, 0
	s_and_saveexec_b64 s[82:83], vcc
	s_cbranch_execz .LBB0_549
	s_movk_i32 s2, 0x4bf
	s_waitcnt lgkmcnt(0)
	v_cmp_lt_u32_e32 vcc, s2, v177
	s_and_saveexec_b64 s[84:85], vcc
	s_cbranch_execz .LBB0_548
	s_nop 0
	global_load_lds_dwordx4 v72, s[100:101]
	s_add_u32 m0, m0, 0x400
	s_add_u32 s100, s100, 0x1a000
	s_addc_u32 s101, s101, 0
	s_nop 0
	global_load_lds_dwordx4 v73, s[100:101]
	s_add_u32 m0, m0, 0x400
	s_add_u32 s100, s100, 0x1a000
	s_addc_u32 s101, s101, 0
	s_nop 0
	global_load_lds_dwordx4 v72, s[100:101]
	s_add_u32 m0, m0, 0x400
	s_add_u32 s100, s100, 0x1a000
	s_addc_u32 s101, s101, 0
	s_nop 0
	global_load_lds_dwordx4 v73, s[100:101]
	s_add_u32 m0, m0, 0x400
	s_add_u32 s100, s100, 0x1a000
	s_addc_u32 s101, s101, 0
.LBB0_548:
	s_or_b64 exec, exec, s[84:85]
	v_mfma_f32_32x32x16_bf16 v[18:33], v[38:41], v[58:61], 0
	v_mfma_f32_32x32x16_bf16 v[18:33], v[46:49], v[54:57], v[18:33]
	v_mfma_f32_32x32x16_bf16 v[18:33], v[34:37], v[50:53], v[18:33]
	v_mfma_f32_32x32x16_bf16 v[18:33], v[42:45], v[62:65], v[18:33]
	s_waitcnt vmcnt(12)
	ds_read_b128 v[58:61], v74 offset:8192
	ds_read_b128 v[54:57], v75 offset:8192
	ds_read_b128 v[50:53], v76 offset:8192
	ds_read_b128 v[62:65], v77 offset:8192
	s_nop 8
	v_max_f32_e32 v18, v18, v18
	v_max_f32_e32 v19, v19, v19
	v_max_f32_e32 v18, 0, v18
	v_max_f32_e32 v20, v20, v20
	v_max_f32_e32 v19, 0, v19
	v_fma_f32 v18, v174, v18, 0
	v_max_f32_e32 v21, v21, v21
	v_max_f32_e32 v20, 0, v20
	v_fmac_f32_e32 v18, v173, v19
	v_max_f32_e32 v22, v22, v22
	v_max_f32_e32 v21, 0, v21
	v_fmac_f32_e32 v18, v172, v20
	v_max_f32_e32 v23, v23, v23
	v_max_f32_e32 v22, 0, v22
	v_fmac_f32_e32 v18, v171, v21
	v_max_f32_e32 v24, v24, v24
	v_max_f32_e32 v23, 0, v23
	v_fmac_f32_e32 v18, v170, v22
	v_max_f32_e32 v25, v25, v25
	v_max_f32_e32 v24, 0, v24
	v_fmac_f32_e32 v18, v169, v23
	v_max_f32_e32 v26, v26, v26
	v_max_f32_e32 v25, 0, v25
	v_fmac_f32_e32 v18, v168, v24
	v_max_f32_e32 v27, v27, v27
	v_max_f32_e32 v26, 0, v26
	v_fmac_f32_e32 v18, v167, v25
	v_max_f32_e32 v28, v28, v28
	v_max_f32_e32 v27, 0, v27
	v_fmac_f32_e32 v18, v166, v26
	v_max_f32_e32 v29, v29, v29
	v_max_f32_e32 v28, 0, v28
	v_fmac_f32_e32 v18, v165, v27
	v_max_f32_e32 v30, v30, v30
	v_max_f32_e32 v29, 0, v29
	v_fmac_f32_e32 v18, v164, v28
	v_max_f32_e32 v31, v31, v31
	v_max_f32_e32 v30, 0, v30
	v_fmac_f32_e32 v18, v163, v29
	v_fmac_f32_e32 v18, v162, v30
	v_max_f32_e32 v19, 0, v31
	v_fmac_f32_e32 v18, v161, v19
	v_max_f32_e32 v19, v32, v32
	v_max_f32_e32 v19, 0, v19
	v_fmac_f32_e32 v18, v160, v19
	v_max_f32_e32 v19, v33, v33
	v_max_f32_e32 v19, 0, v19
	v_fmac_f32_e32 v18, v89, v19
	v_not_b32_e32 v19, v18
	v_or_b32_e32 v20, 0x80000000, v18
	v_cmp_gt_i32_e32 vcc, 0, v18
	s_nop 1
	v_cndmask_b32_e32 v18, v20, v19, vcc
	v_cmp_le_u32_e32 vcc, v132, v87
	s_nop 1
	v_cndmask_b32_e32 v231, 0, v18, vcc
.LBB0_549:
	s_or_b64 exec, exec, s[82:83]
	s_movk_i32 s2, 0x4bf
	v_cmp_lt_u32_e32 vcc, s2, v177
	v_mov_b32_e32 v232, 0
	s_and_saveexec_b64 s[82:83], vcc
	s_cbranch_execz .LBB0_553
	s_movk_i32 s2, 0x4df
	s_waitcnt lgkmcnt(0)
	v_cmp_lt_u32_e32 vcc, s2, v177
	s_and_saveexec_b64 s[84:85], vcc
	s_cbranch_execz .LBB0_552
	s_nop 0
	global_load_lds_dwordx4 v72, s[100:101]
	s_add_u32 m0, m0, 0x400
	s_add_u32 s100, s100, 0x1a000
	s_addc_u32 s101, s101, 0
	s_nop 0
	global_load_lds_dwordx4 v73, s[100:101]
	s_add_u32 m0, m0, 0x400
	s_add_u32 s100, s100, 0x1a000
	s_addc_u32 s101, s101, 0
	s_nop 0
	global_load_lds_dwordx4 v72, s[100:101]
	s_add_u32 m0, m0, 0x400
	s_add_u32 s100, s100, 0x1a000
	s_addc_u32 s101, s101, 0
	s_nop 0
	global_load_lds_dwordx4 v73, s[100:101]
	s_add_u32 m0, m0, 0x400
	s_add_u32 s100, s100, 0x1a000
	s_addc_u32 s101, s101, 0
.LBB0_552:
	s_or_b64 exec, exec, s[84:85]
	v_mfma_f32_32x32x16_bf16 v[18:33], v[38:41], v[58:61], 0
	v_mfma_f32_32x32x16_bf16 v[18:33], v[46:49], v[54:57], v[18:33]
	v_mfma_f32_32x32x16_bf16 v[18:33], v[34:37], v[50:53], v[18:33]
	v_mfma_f32_32x32x16_bf16 v[18:33], v[42:45], v[62:65], v[18:33]
	s_waitcnt vmcnt(12)
	ds_read_b128 v[58:61], v74 offset:12288
	ds_read_b128 v[54:57], v75 offset:12288
	ds_read_b128 v[50:53], v76 offset:12288
	ds_read_b128 v[62:65], v77 offset:12288
	s_nop 8
	v_max_f32_e32 v18, v18, v18
	v_max_f32_e32 v19, v19, v19
	v_max_f32_e32 v18, 0, v18
	v_max_f32_e32 v20, v20, v20
	v_max_f32_e32 v19, 0, v19
	v_fma_f32 v18, v174, v18, 0
	v_max_f32_e32 v21, v21, v21
	v_max_f32_e32 v20, 0, v20
	v_fmac_f32_e32 v18, v173, v19
	v_max_f32_e32 v22, v22, v22
	v_max_f32_e32 v21, 0, v21
	v_fmac_f32_e32 v18, v172, v20
	v_max_f32_e32 v23, v23, v23
	v_max_f32_e32 v22, 0, v22
	v_fmac_f32_e32 v18, v171, v21
	v_max_f32_e32 v24, v24, v24
	v_max_f32_e32 v23, 0, v23
	v_fmac_f32_e32 v18, v170, v22
	v_max_f32_e32 v25, v25, v25
	v_max_f32_e32 v24, 0, v24
	v_fmac_f32_e32 v18, v169, v23
	v_max_f32_e32 v26, v26, v26
	v_max_f32_e32 v25, 0, v25
	v_fmac_f32_e32 v18, v168, v24
	v_max_f32_e32 v27, v27, v27
	v_max_f32_e32 v26, 0, v26
	v_fmac_f32_e32 v18, v167, v25
	v_max_f32_e32 v28, v28, v28
	v_max_f32_e32 v27, 0, v27
	v_fmac_f32_e32 v18, v166, v26
	v_max_f32_e32 v29, v29, v29
	v_max_f32_e32 v28, 0, v28
	v_fmac_f32_e32 v18, v165, v27
	v_max_f32_e32 v30, v30, v30
	v_max_f32_e32 v29, 0, v29
	v_fmac_f32_e32 v18, v164, v28
	v_max_f32_e32 v31, v31, v31
	v_max_f32_e32 v30, 0, v30
	v_fmac_f32_e32 v18, v163, v29
	v_fmac_f32_e32 v18, v162, v30
	v_max_f32_e32 v19, 0, v31
	v_fmac_f32_e32 v18, v161, v19
	v_max_f32_e32 v19, v32, v32
	v_max_f32_e32 v19, 0, v19
	v_fmac_f32_e32 v18, v160, v19
	v_max_f32_e32 v19, v33, v33
	v_max_f32_e32 v19, 0, v19
	v_fmac_f32_e32 v18, v89, v19
	v_not_b32_e32 v19, v18
	v_or_b32_e32 v20, 0x80000000, v18
	v_cmp_gt_i32_e32 vcc, 0, v18
	s_nop 1
	v_cndmask_b32_e32 v18, v20, v19, vcc
	v_cmp_le_u32_e32 vcc, v133, v87
	s_nop 1
	v_cndmask_b32_e32 v232, 0, v18, vcc
.LBB0_553:
	s_or_b64 exec, exec, s[82:83]
	s_movk_i32 s2, 0x4df
	v_cmp_lt_u32_e32 vcc, s2, v177
	v_mov_b32_e32 v233, 0
	s_and_saveexec_b64 s[82:83], vcc
	s_cbranch_execz .LBB0_557
	s_movk_i32 s2, 0x4ff
	s_waitcnt lgkmcnt(0)
	v_cmp_lt_u32_e32 vcc, s2, v177
	s_and_saveexec_b64 s[84:85], vcc
	s_cbranch_execz .LBB0_556
	s_nop 0
	global_load_lds_dwordx4 v72, s[100:101]
	s_add_u32 m0, m0, 0x400
	s_add_u32 s100, s100, 0x1a000
	s_addc_u32 s101, s101, 0
	s_nop 0
	global_load_lds_dwordx4 v73, s[100:101]
	s_add_u32 m0, m0, 0x400
	s_add_u32 s100, s100, 0x1a000
	s_addc_u32 s101, s101, 0
	s_nop 0
	global_load_lds_dwordx4 v72, s[100:101]
	s_add_u32 m0, m0, 0x400
	s_add_u32 s100, s100, 0x1a000
	s_addc_u32 s101, s101, 0
	s_nop 0
	global_load_lds_dwordx4 v73, s[100:101]
	s_sub_u32 m0, m0, 0x3c00
	s_add_u32 s100, s100, 0x1a000
	s_addc_u32 s101, s101, 0
.LBB0_556:
	s_or_b64 exec, exec, s[84:85]
	v_mfma_f32_32x32x16_bf16 v[18:33], v[38:41], v[58:61], 0
	v_mfma_f32_32x32x16_bf16 v[18:33], v[46:49], v[54:57], v[18:33]
	v_mfma_f32_32x32x16_bf16 v[18:33], v[34:37], v[50:53], v[18:33]
	v_mfma_f32_32x32x16_bf16 v[18:33], v[42:45], v[62:65], v[18:33]
	s_waitcnt vmcnt(12)
	ds_read_b128 v[58:61], v74 offset:0
	ds_read_b128 v[54:57], v75 offset:0
	ds_read_b128 v[50:53], v76 offset:0
	ds_read_b128 v[62:65], v77 offset:0
	s_nop 8
	v_max_f32_e32 v18, v18, v18
	v_max_f32_e32 v19, v19, v19
	v_max_f32_e32 v18, 0, v18
	v_max_f32_e32 v20, v20, v20
	v_max_f32_e32 v19, 0, v19
	v_fma_f32 v18, v174, v18, 0
	v_max_f32_e32 v21, v21, v21
	v_max_f32_e32 v20, 0, v20
	v_fmac_f32_e32 v18, v173, v19
	v_max_f32_e32 v22, v22, v22
	v_max_f32_e32 v21, 0, v21
	v_fmac_f32_e32 v18, v172, v20
	v_max_f32_e32 v23, v23, v23
	v_max_f32_e32 v22, 0, v22
	v_fmac_f32_e32 v18, v171, v21
	v_max_f32_e32 v24, v24, v24
	v_max_f32_e32 v23, 0, v23
	v_fmac_f32_e32 v18, v170, v22
	v_max_f32_e32 v25, v25, v25
	v_max_f32_e32 v24, 0, v24
	v_fmac_f32_e32 v18, v169, v23
	v_max_f32_e32 v26, v26, v26
	v_max_f32_e32 v25, 0, v25
	v_fmac_f32_e32 v18, v168, v24
	v_max_f32_e32 v27, v27, v27
	v_max_f32_e32 v26, 0, v26
	v_fmac_f32_e32 v18, v167, v25
	v_max_f32_e32 v28, v28, v28
	v_max_f32_e32 v27, 0, v27
	v_fmac_f32_e32 v18, v166, v26
	v_max_f32_e32 v29, v29, v29
	v_max_f32_e32 v28, 0, v28
	v_fmac_f32_e32 v18, v165, v27
	v_max_f32_e32 v30, v30, v30
	v_max_f32_e32 v29, 0, v29
	v_fmac_f32_e32 v18, v164, v28
	v_max_f32_e32 v31, v31, v31
	v_max_f32_e32 v30, 0, v30
	v_fmac_f32_e32 v18, v163, v29
	v_fmac_f32_e32 v18, v162, v30
	v_max_f32_e32 v19, 0, v31
	v_fmac_f32_e32 v18, v161, v19
	v_max_f32_e32 v19, v32, v32
	v_max_f32_e32 v19, 0, v19
	v_fmac_f32_e32 v18, v160, v19
	v_max_f32_e32 v19, v33, v33
	v_max_f32_e32 v19, 0, v19
	v_fmac_f32_e32 v18, v89, v19
	v_not_b32_e32 v19, v18
	v_or_b32_e32 v20, 0x80000000, v18
	v_cmp_gt_i32_e32 vcc, 0, v18
	s_nop 1
	v_cndmask_b32_e32 v18, v20, v19, vcc
	v_cmp_le_u32_e32 vcc, v134, v87
	s_nop 1
	v_cndmask_b32_e32 v233, 0, v18, vcc
.LBB0_557:
	s_or_b64 exec, exec, s[82:83]
	s_movk_i32 s2, 0x4ff
	v_cmp_lt_u32_e32 vcc, s2, v177
	v_mov_b32_e32 v234, 0
	s_and_saveexec_b64 s[82:83], vcc
	s_cbranch_execz .LBB0_561
	s_movk_i32 s2, 0x51f
	s_waitcnt lgkmcnt(0)
	v_cmp_lt_u32_e32 vcc, s2, v177
	s_and_saveexec_b64 s[84:85], vcc
	s_cbranch_execz .LBB0_560
	s_nop 0
	global_load_lds_dwordx4 v72, s[100:101]
	s_add_u32 m0, m0, 0x400
	s_add_u32 s100, s100, 0x1a000
	s_addc_u32 s101, s101, 0
	s_nop 0
	global_load_lds_dwordx4 v73, s[100:101]
	s_add_u32 m0, m0, 0x400
	s_add_u32 s100, s100, 0x1a000
	s_addc_u32 s101, s101, 0
	s_nop 0
	global_load_lds_dwordx4 v72, s[100:101]
	s_add_u32 m0, m0, 0x400
	s_add_u32 s100, s100, 0x1a000
	s_addc_u32 s101, s101, 0
	s_nop 0
	global_load_lds_dwordx4 v73, s[100:101]
	s_add_u32 m0, m0, 0x400
	s_add_u32 s100, s100, 0x1a000
	s_addc_u32 s101, s101, 0
.LBB0_560:
	s_or_b64 exec, exec, s[84:85]
	v_mfma_f32_32x32x16_bf16 v[18:33], v[38:41], v[58:61], 0
	v_mfma_f32_32x32x16_bf16 v[18:33], v[46:49], v[54:57], v[18:33]
	v_mfma_f32_32x32x16_bf16 v[18:33], v[34:37], v[50:53], v[18:33]
	v_mfma_f32_32x32x16_bf16 v[18:33], v[42:45], v[62:65], v[18:33]
	s_waitcnt vmcnt(12)
	ds_read_b128 v[58:61], v74 offset:4096
	ds_read_b128 v[54:57], v75 offset:4096
	ds_read_b128 v[50:53], v76 offset:4096
	ds_read_b128 v[62:65], v77 offset:4096
	s_nop 8
	v_max_f32_e32 v18, v18, v18
	v_max_f32_e32 v19, v19, v19
	v_max_f32_e32 v18, 0, v18
	v_max_f32_e32 v20, v20, v20
	v_max_f32_e32 v19, 0, v19
	v_fma_f32 v18, v174, v18, 0
	v_max_f32_e32 v21, v21, v21
	v_max_f32_e32 v20, 0, v20
	v_fmac_f32_e32 v18, v173, v19
	v_max_f32_e32 v22, v22, v22
	v_max_f32_e32 v21, 0, v21
	v_fmac_f32_e32 v18, v172, v20
	v_max_f32_e32 v23, v23, v23
	v_max_f32_e32 v22, 0, v22
	v_fmac_f32_e32 v18, v171, v21
	v_max_f32_e32 v24, v24, v24
	v_max_f32_e32 v23, 0, v23
	v_fmac_f32_e32 v18, v170, v22
	v_max_f32_e32 v25, v25, v25
	v_max_f32_e32 v24, 0, v24
	v_fmac_f32_e32 v18, v169, v23
	v_max_f32_e32 v26, v26, v26
	v_max_f32_e32 v25, 0, v25
	v_fmac_f32_e32 v18, v168, v24
	v_max_f32_e32 v27, v27, v27
	v_max_f32_e32 v26, 0, v26
	v_fmac_f32_e32 v18, v167, v25
	v_max_f32_e32 v28, v28, v28
	v_max_f32_e32 v27, 0, v27
	v_fmac_f32_e32 v18, v166, v26
	v_max_f32_e32 v29, v29, v29
	v_max_f32_e32 v28, 0, v28
	v_fmac_f32_e32 v18, v165, v27
	v_max_f32_e32 v30, v30, v30
	v_max_f32_e32 v29, 0, v29
	v_fmac_f32_e32 v18, v164, v28
	v_max_f32_e32 v31, v31, v31
	v_max_f32_e32 v30, 0, v30
	v_fmac_f32_e32 v18, v163, v29
	v_fmac_f32_e32 v18, v162, v30
	v_max_f32_e32 v19, 0, v31
	v_fmac_f32_e32 v18, v161, v19
	v_max_f32_e32 v19, v32, v32
	v_max_f32_e32 v19, 0, v19
	v_fmac_f32_e32 v18, v160, v19
	v_max_f32_e32 v19, v33, v33
	v_max_f32_e32 v19, 0, v19
	v_fmac_f32_e32 v18, v89, v19
	v_not_b32_e32 v19, v18
	v_or_b32_e32 v20, 0x80000000, v18
	v_cmp_gt_i32_e32 vcc, 0, v18
	s_nop 1
	v_cndmask_b32_e32 v18, v20, v19, vcc
	v_cmp_le_u32_e32 vcc, v135, v87
	s_nop 1
	v_cndmask_b32_e32 v234, 0, v18, vcc
.LBB0_561:
	s_or_b64 exec, exec, s[82:83]
	s_movk_i32 s2, 0x51f
	v_cmp_lt_u32_e32 vcc, s2, v177
	v_mov_b32_e32 v235, 0
	s_and_saveexec_b64 s[82:83], vcc
	s_cbranch_execz .LBB0_565
	s_movk_i32 s2, 0x53f
	s_waitcnt lgkmcnt(0)
	v_cmp_lt_u32_e32 vcc, s2, v177
	s_and_saveexec_b64 s[84:85], vcc
	s_cbranch_execz .LBB0_564
	s_nop 0
	global_load_lds_dwordx4 v72, s[100:101]
	s_add_u32 m0, m0, 0x400
	s_add_u32 s100, s100, 0x1a000
	s_addc_u32 s101, s101, 0
	s_nop 0
	global_load_lds_dwordx4 v73, s[100:101]
	s_add_u32 m0, m0, 0x400
	s_add_u32 s100, s100, 0x1a000
	s_addc_u32 s101, s101, 0
	s_nop 0
	global_load_lds_dwordx4 v72, s[100:101]
	s_add_u32 m0, m0, 0x400
	s_add_u32 s100, s100, 0x1a000
	s_addc_u32 s101, s101, 0
	s_nop 0
	global_load_lds_dwordx4 v73, s[100:101]
	s_add_u32 m0, m0, 0x400
	s_add_u32 s100, s100, 0x1a000
	s_addc_u32 s101, s101, 0
.LBB0_564:
	s_or_b64 exec, exec, s[84:85]
	v_mfma_f32_32x32x16_bf16 v[18:33], v[38:41], v[58:61], 0
	v_mfma_f32_32x32x16_bf16 v[18:33], v[46:49], v[54:57], v[18:33]
	v_mfma_f32_32x32x16_bf16 v[18:33], v[34:37], v[50:53], v[18:33]
	v_mfma_f32_32x32x16_bf16 v[18:33], v[42:45], v[62:65], v[18:33]
	s_waitcnt vmcnt(12)
	ds_read_b128 v[58:61], v74 offset:8192
	ds_read_b128 v[54:57], v75 offset:8192
	ds_read_b128 v[50:53], v76 offset:8192
	ds_read_b128 v[62:65], v77 offset:8192
	s_nop 8
	v_max_f32_e32 v18, v18, v18
	v_max_f32_e32 v19, v19, v19
	v_max_f32_e32 v18, 0, v18
	v_max_f32_e32 v20, v20, v20
	v_max_f32_e32 v19, 0, v19
	v_fma_f32 v18, v174, v18, 0
	v_max_f32_e32 v21, v21, v21
	v_max_f32_e32 v20, 0, v20
	v_fmac_f32_e32 v18, v173, v19
	v_max_f32_e32 v22, v22, v22
	v_max_f32_e32 v21, 0, v21
	v_fmac_f32_e32 v18, v172, v20
	v_max_f32_e32 v23, v23, v23
	v_max_f32_e32 v22, 0, v22
	v_fmac_f32_e32 v18, v171, v21
	v_max_f32_e32 v24, v24, v24
	v_max_f32_e32 v23, 0, v23
	v_fmac_f32_e32 v18, v170, v22
	v_max_f32_e32 v25, v25, v25
	v_max_f32_e32 v24, 0, v24
	v_fmac_f32_e32 v18, v169, v23
	v_max_f32_e32 v26, v26, v26
	v_max_f32_e32 v25, 0, v25
	v_fmac_f32_e32 v18, v168, v24
	v_max_f32_e32 v27, v27, v27
	v_max_f32_e32 v26, 0, v26
	v_fmac_f32_e32 v18, v167, v25
	v_max_f32_e32 v28, v28, v28
	v_max_f32_e32 v27, 0, v27
	v_fmac_f32_e32 v18, v166, v26
	v_max_f32_e32 v29, v29, v29
	v_max_f32_e32 v28, 0, v28
	v_fmac_f32_e32 v18, v165, v27
	v_max_f32_e32 v30, v30, v30
	v_max_f32_e32 v29, 0, v29
	v_fmac_f32_e32 v18, v164, v28
	v_max_f32_e32 v31, v31, v31
	v_max_f32_e32 v30, 0, v30
	v_fmac_f32_e32 v18, v163, v29
	v_fmac_f32_e32 v18, v162, v30
	v_max_f32_e32 v19, 0, v31
	v_fmac_f32_e32 v18, v161, v19
	v_max_f32_e32 v19, v32, v32
	v_max_f32_e32 v19, 0, v19
	v_fmac_f32_e32 v18, v160, v19
	v_max_f32_e32 v19, v33, v33
	v_max_f32_e32 v19, 0, v19
	v_fmac_f32_e32 v18, v89, v19
	v_not_b32_e32 v19, v18
	v_or_b32_e32 v20, 0x80000000, v18
	v_cmp_gt_i32_e32 vcc, 0, v18
	s_nop 1
	v_cndmask_b32_e32 v18, v20, v19, vcc
	v_cmp_le_u32_e32 vcc, v136, v87
	s_nop 1
	v_cndmask_b32_e32 v235, 0, v18, vcc
.LBB0_565:
	s_or_b64 exec, exec, s[82:83]
	s_movk_i32 s2, 0x53f
	v_cmp_lt_u32_e32 vcc, s2, v177
	v_mov_b32_e32 v236, 0
	s_and_saveexec_b64 s[82:83], vcc
	s_cbranch_execz .LBB0_569
	s_movk_i32 s2, 0x55f
	s_waitcnt lgkmcnt(0)
	v_cmp_lt_u32_e32 vcc, s2, v177
	s_and_saveexec_b64 s[84:85], vcc
	s_cbranch_execz .LBB0_568
	s_nop 0
	global_load_lds_dwordx4 v72, s[100:101]
	s_add_u32 m0, m0, 0x400
	s_add_u32 s100, s100, 0x1a000
	s_addc_u32 s101, s101, 0
	s_nop 0
	global_load_lds_dwordx4 v73, s[100:101]
	s_add_u32 m0, m0, 0x400
	s_add_u32 s100, s100, 0x1a000
	s_addc_u32 s101, s101, 0
	s_nop 0
	global_load_lds_dwordx4 v72, s[100:101]
	s_add_u32 m0, m0, 0x400
	s_add_u32 s100, s100, 0x1a000
	s_addc_u32 s101, s101, 0
	s_nop 0
	global_load_lds_dwordx4 v73, s[100:101]
	s_add_u32 m0, m0, 0x400
	s_add_u32 s100, s100, 0x1a000
	s_addc_u32 s101, s101, 0
.LBB0_568:
	s_or_b64 exec, exec, s[84:85]
	v_mfma_f32_32x32x16_bf16 v[18:33], v[38:41], v[58:61], 0
	v_mfma_f32_32x32x16_bf16 v[18:33], v[46:49], v[54:57], v[18:33]
	v_mfma_f32_32x32x16_bf16 v[18:33], v[34:37], v[50:53], v[18:33]
	v_mfma_f32_32x32x16_bf16 v[18:33], v[42:45], v[62:65], v[18:33]
	s_waitcnt vmcnt(12)
	ds_read_b128 v[58:61], v74 offset:12288
	ds_read_b128 v[54:57], v75 offset:12288
	ds_read_b128 v[50:53], v76 offset:12288
	ds_read_b128 v[62:65], v77 offset:12288
	s_nop 8
	v_max_f32_e32 v18, v18, v18
	v_max_f32_e32 v19, v19, v19
	v_max_f32_e32 v18, 0, v18
	v_max_f32_e32 v20, v20, v20
	v_max_f32_e32 v19, 0, v19
	v_fma_f32 v18, v174, v18, 0
	v_max_f32_e32 v21, v21, v21
	v_max_f32_e32 v20, 0, v20
	v_fmac_f32_e32 v18, v173, v19
	v_max_f32_e32 v22, v22, v22
	v_max_f32_e32 v21, 0, v21
	v_fmac_f32_e32 v18, v172, v20
	v_max_f32_e32 v23, v23, v23
	v_max_f32_e32 v22, 0, v22
	v_fmac_f32_e32 v18, v171, v21
	v_max_f32_e32 v24, v24, v24
	v_max_f32_e32 v23, 0, v23
	v_fmac_f32_e32 v18, v170, v22
	v_max_f32_e32 v25, v25, v25
	v_max_f32_e32 v24, 0, v24
	v_fmac_f32_e32 v18, v169, v23
	v_max_f32_e32 v26, v26, v26
	v_max_f32_e32 v25, 0, v25
	v_fmac_f32_e32 v18, v168, v24
	v_max_f32_e32 v27, v27, v27
	v_max_f32_e32 v26, 0, v26
	v_fmac_f32_e32 v18, v167, v25
	v_max_f32_e32 v28, v28, v28
	v_max_f32_e32 v27, 0, v27
	v_fmac_f32_e32 v18, v166, v26
	v_max_f32_e32 v29, v29, v29
	v_max_f32_e32 v28, 0, v28
	v_fmac_f32_e32 v18, v165, v27
	v_max_f32_e32 v30, v30, v30
	v_max_f32_e32 v29, 0, v29
	v_fmac_f32_e32 v18, v164, v28
	v_max_f32_e32 v31, v31, v31
	v_max_f32_e32 v30, 0, v30
	v_fmac_f32_e32 v18, v163, v29
	v_fmac_f32_e32 v18, v162, v30
	v_max_f32_e32 v19, 0, v31
	v_fmac_f32_e32 v18, v161, v19
	v_max_f32_e32 v19, v32, v32
	v_max_f32_e32 v19, 0, v19
	v_fmac_f32_e32 v18, v160, v19
	v_max_f32_e32 v19, v33, v33
	v_max_f32_e32 v19, 0, v19
	v_fmac_f32_e32 v18, v89, v19
	v_not_b32_e32 v19, v18
	v_or_b32_e32 v20, 0x80000000, v18
	v_cmp_gt_i32_e32 vcc, 0, v18
	s_nop 1
	v_cndmask_b32_e32 v18, v20, v19, vcc
	v_cmp_le_u32_e32 vcc, v137, v87
	s_nop 1
	v_cndmask_b32_e32 v236, 0, v18, vcc
.LBB0_569:
	s_or_b64 exec, exec, s[82:83]
	s_movk_i32 s2, 0x55f
	v_cmp_lt_u32_e32 vcc, s2, v177
	v_mov_b32_e32 v237, 0
	s_and_saveexec_b64 s[82:83], vcc
	s_cbranch_execz .LBB0_573
	s_movk_i32 s2, 0x57f
	s_waitcnt lgkmcnt(0)
	v_cmp_lt_u32_e32 vcc, s2, v177
	s_and_saveexec_b64 s[84:85], vcc
	s_cbranch_execz .LBB0_572
	s_nop 0
	global_load_lds_dwordx4 v72, s[100:101]
	s_add_u32 m0, m0, 0x400
	s_add_u32 s100, s100, 0x1a000
	s_addc_u32 s101, s101, 0
	s_nop 0
	global_load_lds_dwordx4 v73, s[100:101]
	s_add_u32 m0, m0, 0x400
	s_add_u32 s100, s100, 0x1a000
	s_addc_u32 s101, s101, 0
	s_nop 0
	global_load_lds_dwordx4 v72, s[100:101]
	s_add_u32 m0, m0, 0x400
	s_add_u32 s100, s100, 0x1a000
	s_addc_u32 s101, s101, 0
	s_nop 0
	global_load_lds_dwordx4 v73, s[100:101]
	s_sub_u32 m0, m0, 0x3c00
	s_add_u32 s100, s100, 0x1a000
	s_addc_u32 s101, s101, 0
.LBB0_572:
	s_or_b64 exec, exec, s[84:85]
	v_mfma_f32_32x32x16_bf16 v[18:33], v[38:41], v[58:61], 0
	v_mfma_f32_32x32x16_bf16 v[18:33], v[46:49], v[54:57], v[18:33]
	v_mfma_f32_32x32x16_bf16 v[18:33], v[34:37], v[50:53], v[18:33]
	v_mfma_f32_32x32x16_bf16 v[18:33], v[42:45], v[62:65], v[18:33]
	s_waitcnt vmcnt(12)
	ds_read_b128 v[58:61], v74 offset:0
	ds_read_b128 v[54:57], v75 offset:0
	ds_read_b128 v[50:53], v76 offset:0
	ds_read_b128 v[62:65], v77 offset:0
	s_nop 8
	v_max_f32_e32 v18, v18, v18
	v_max_f32_e32 v19, v19, v19
	v_max_f32_e32 v18, 0, v18
	v_max_f32_e32 v20, v20, v20
	v_max_f32_e32 v19, 0, v19
	v_fma_f32 v18, v174, v18, 0
	v_max_f32_e32 v21, v21, v21
	v_max_f32_e32 v20, 0, v20
	v_fmac_f32_e32 v18, v173, v19
	v_max_f32_e32 v22, v22, v22
	v_max_f32_e32 v21, 0, v21
	v_fmac_f32_e32 v18, v172, v20
	v_max_f32_e32 v23, v23, v23
	v_max_f32_e32 v22, 0, v22
	v_fmac_f32_e32 v18, v171, v21
	v_max_f32_e32 v24, v24, v24
	v_max_f32_e32 v23, 0, v23
	v_fmac_f32_e32 v18, v170, v22
	v_max_f32_e32 v25, v25, v25
	v_max_f32_e32 v24, 0, v24
	v_fmac_f32_e32 v18, v169, v23
	v_max_f32_e32 v26, v26, v26
	v_max_f32_e32 v25, 0, v25
	v_fmac_f32_e32 v18, v168, v24
	v_max_f32_e32 v27, v27, v27
	v_max_f32_e32 v26, 0, v26
	v_fmac_f32_e32 v18, v167, v25
	v_max_f32_e32 v28, v28, v28
	v_max_f32_e32 v27, 0, v27
	v_fmac_f32_e32 v18, v166, v26
	v_max_f32_e32 v29, v29, v29
	v_max_f32_e32 v28, 0, v28
	v_fmac_f32_e32 v18, v165, v27
	v_max_f32_e32 v30, v30, v30
	v_max_f32_e32 v29, 0, v29
	v_fmac_f32_e32 v18, v164, v28
	v_max_f32_e32 v31, v31, v31
	v_max_f32_e32 v30, 0, v30
	v_fmac_f32_e32 v18, v163, v29
	v_fmac_f32_e32 v18, v162, v30
	v_max_f32_e32 v19, 0, v31
	v_fmac_f32_e32 v18, v161, v19
	v_max_f32_e32 v19, v32, v32
	v_max_f32_e32 v19, 0, v19
	v_fmac_f32_e32 v18, v160, v19
	v_max_f32_e32 v19, v33, v33
	v_max_f32_e32 v19, 0, v19
	v_fmac_f32_e32 v18, v89, v19
	v_not_b32_e32 v19, v18
	v_or_b32_e32 v20, 0x80000000, v18
	v_cmp_gt_i32_e32 vcc, 0, v18
	s_nop 1
	v_cndmask_b32_e32 v18, v20, v19, vcc
	v_cmp_le_u32_e32 vcc, v138, v87
	s_nop 1
	v_cndmask_b32_e32 v237, 0, v18, vcc
.LBB0_573:
	s_or_b64 exec, exec, s[82:83]
	s_movk_i32 s2, 0x57f
	v_cmp_lt_u32_e32 vcc, s2, v177
	v_mov_b32_e32 v238, 0
	s_and_saveexec_b64 s[82:83], vcc
	s_cbranch_execz .LBB0_577
	s_movk_i32 s2, 0x59f
	s_waitcnt lgkmcnt(0)
	v_cmp_lt_u32_e32 vcc, s2, v177
	s_and_saveexec_b64 s[84:85], vcc
	s_cbranch_execz .LBB0_576
	s_nop 0
	global_load_lds_dwordx4 v72, s[100:101]
	s_add_u32 m0, m0, 0x400
	s_add_u32 s100, s100, 0x1a000
	s_addc_u32 s101, s101, 0
	s_nop 0
	global_load_lds_dwordx4 v73, s[100:101]
	s_add_u32 m0, m0, 0x400
	s_add_u32 s100, s100, 0x1a000
	s_addc_u32 s101, s101, 0
	s_nop 0
	global_load_lds_dwordx4 v72, s[100:101]
	s_add_u32 m0, m0, 0x400
	s_add_u32 s100, s100, 0x1a000
	s_addc_u32 s101, s101, 0
	s_nop 0
	global_load_lds_dwordx4 v73, s[100:101]
	s_add_u32 m0, m0, 0x400
	s_add_u32 s100, s100, 0x1a000
	s_addc_u32 s101, s101, 0
.LBB0_576:
	s_or_b64 exec, exec, s[84:85]
	v_mfma_f32_32x32x16_bf16 v[18:33], v[38:41], v[58:61], 0
	v_mfma_f32_32x32x16_bf16 v[18:33], v[46:49], v[54:57], v[18:33]
	v_mfma_f32_32x32x16_bf16 v[18:33], v[34:37], v[50:53], v[18:33]
	v_mfma_f32_32x32x16_bf16 v[18:33], v[42:45], v[62:65], v[18:33]
	s_waitcnt vmcnt(12)
	ds_read_b128 v[58:61], v74 offset:4096
	ds_read_b128 v[54:57], v75 offset:4096
	ds_read_b128 v[50:53], v76 offset:4096
	ds_read_b128 v[62:65], v77 offset:4096
	s_nop 8
	v_max_f32_e32 v18, v18, v18
	v_max_f32_e32 v19, v19, v19
	v_max_f32_e32 v18, 0, v18
	v_max_f32_e32 v20, v20, v20
	v_max_f32_e32 v19, 0, v19
	v_fma_f32 v18, v174, v18, 0
	v_max_f32_e32 v21, v21, v21
	v_max_f32_e32 v20, 0, v20
	v_fmac_f32_e32 v18, v173, v19
	v_max_f32_e32 v22, v22, v22
	v_max_f32_e32 v21, 0, v21
	v_fmac_f32_e32 v18, v172, v20
	v_max_f32_e32 v23, v23, v23
	v_max_f32_e32 v22, 0, v22
	v_fmac_f32_e32 v18, v171, v21
	v_max_f32_e32 v24, v24, v24
	v_max_f32_e32 v23, 0, v23
	v_fmac_f32_e32 v18, v170, v22
	v_max_f32_e32 v25, v25, v25
	v_max_f32_e32 v24, 0, v24
	v_fmac_f32_e32 v18, v169, v23
	v_max_f32_e32 v26, v26, v26
	v_max_f32_e32 v25, 0, v25
	v_fmac_f32_e32 v18, v168, v24
	v_max_f32_e32 v27, v27, v27
	v_max_f32_e32 v26, 0, v26
	v_fmac_f32_e32 v18, v167, v25
	v_max_f32_e32 v28, v28, v28
	v_max_f32_e32 v27, 0, v27
	v_fmac_f32_e32 v18, v166, v26
	v_max_f32_e32 v29, v29, v29
	v_max_f32_e32 v28, 0, v28
	v_fmac_f32_e32 v18, v165, v27
	v_max_f32_e32 v30, v30, v30
	v_max_f32_e32 v29, 0, v29
	v_fmac_f32_e32 v18, v164, v28
	v_max_f32_e32 v31, v31, v31
	v_max_f32_e32 v30, 0, v30
	v_fmac_f32_e32 v18, v163, v29
	v_fmac_f32_e32 v18, v162, v30
	v_max_f32_e32 v19, 0, v31
	v_fmac_f32_e32 v18, v161, v19
	v_max_f32_e32 v19, v32, v32
	v_max_f32_e32 v19, 0, v19
	v_fmac_f32_e32 v18, v160, v19
	v_max_f32_e32 v19, v33, v33
	v_max_f32_e32 v19, 0, v19
	v_fmac_f32_e32 v18, v89, v19
	v_not_b32_e32 v19, v18
	v_or_b32_e32 v20, 0x80000000, v18
	v_cmp_gt_i32_e32 vcc, 0, v18
	s_nop 1
	v_cndmask_b32_e32 v18, v20, v19, vcc
	v_cmp_le_u32_e32 vcc, v139, v87
	s_nop 1
	v_cndmask_b32_e32 v238, 0, v18, vcc
.LBB0_577:
	s_or_b64 exec, exec, s[82:83]
	s_movk_i32 s2, 0x59f
	v_cmp_lt_u32_e32 vcc, s2, v177
	v_mov_b32_e32 v239, 0
	s_and_saveexec_b64 s[82:83], vcc
	s_cbranch_execz .LBB0_581
	s_movk_i32 s2, 0x5bf
	s_waitcnt lgkmcnt(0)
	v_cmp_lt_u32_e32 vcc, s2, v177
	s_and_saveexec_b64 s[84:85], vcc
	s_cbranch_execz .LBB0_580
	s_nop 0
	global_load_lds_dwordx4 v72, s[100:101]
	s_add_u32 m0, m0, 0x400
	s_add_u32 s100, s100, 0x1a000
	s_addc_u32 s101, s101, 0
	s_nop 0
	global_load_lds_dwordx4 v73, s[100:101]
	s_add_u32 m0, m0, 0x400
	s_add_u32 s100, s100, 0x1a000
	s_addc_u32 s101, s101, 0
	s_nop 0
	global_load_lds_dwordx4 v72, s[100:101]
	s_add_u32 m0, m0, 0x400
	s_add_u32 s100, s100, 0x1a000
	s_addc_u32 s101, s101, 0
	s_nop 0
	global_load_lds_dwordx4 v73, s[100:101]
	s_add_u32 m0, m0, 0x400
	s_add_u32 s100, s100, 0x1a000
	s_addc_u32 s101, s101, 0
.LBB0_580:
	s_or_b64 exec, exec, s[84:85]
	v_mfma_f32_32x32x16_bf16 v[18:33], v[38:41], v[58:61], 0
	v_mfma_f32_32x32x16_bf16 v[18:33], v[46:49], v[54:57], v[18:33]
	v_mfma_f32_32x32x16_bf16 v[18:33], v[34:37], v[50:53], v[18:33]
	v_mfma_f32_32x32x16_bf16 v[18:33], v[42:45], v[62:65], v[18:33]
	s_waitcnt vmcnt(12)
	ds_read_b128 v[58:61], v74 offset:8192
	ds_read_b128 v[54:57], v75 offset:8192
	ds_read_b128 v[50:53], v76 offset:8192
	ds_read_b128 v[62:65], v77 offset:8192
	s_nop 8
	v_max_f32_e32 v18, v18, v18
	v_max_f32_e32 v19, v19, v19
	v_max_f32_e32 v18, 0, v18
	v_max_f32_e32 v20, v20, v20
	v_max_f32_e32 v19, 0, v19
	v_fma_f32 v18, v174, v18, 0
	v_max_f32_e32 v21, v21, v21
	v_max_f32_e32 v20, 0, v20
	v_fmac_f32_e32 v18, v173, v19
	v_max_f32_e32 v22, v22, v22
	v_max_f32_e32 v21, 0, v21
	v_fmac_f32_e32 v18, v172, v20
	v_max_f32_e32 v23, v23, v23
	v_max_f32_e32 v22, 0, v22
	v_fmac_f32_e32 v18, v171, v21
	v_max_f32_e32 v24, v24, v24
	v_max_f32_e32 v23, 0, v23
	v_fmac_f32_e32 v18, v170, v22
	v_max_f32_e32 v25, v25, v25
	v_max_f32_e32 v24, 0, v24
	v_fmac_f32_e32 v18, v169, v23
	v_max_f32_e32 v26, v26, v26
	v_max_f32_e32 v25, 0, v25
	v_fmac_f32_e32 v18, v168, v24
	v_max_f32_e32 v27, v27, v27
	v_max_f32_e32 v26, 0, v26
	v_fmac_f32_e32 v18, v167, v25
	v_max_f32_e32 v28, v28, v28
	v_max_f32_e32 v27, 0, v27
	v_fmac_f32_e32 v18, v166, v26
	v_max_f32_e32 v29, v29, v29
	v_max_f32_e32 v28, 0, v28
	v_fmac_f32_e32 v18, v165, v27
	v_max_f32_e32 v30, v30, v30
	v_max_f32_e32 v29, 0, v29
	v_fmac_f32_e32 v18, v164, v28
	v_max_f32_e32 v31, v31, v31
	v_max_f32_e32 v30, 0, v30
	v_fmac_f32_e32 v18, v163, v29
	v_fmac_f32_e32 v18, v162, v30
	v_max_f32_e32 v19, 0, v31
	v_fmac_f32_e32 v18, v161, v19
	v_max_f32_e32 v19, v32, v32
	v_max_f32_e32 v19, 0, v19
	v_fmac_f32_e32 v18, v160, v19
	v_max_f32_e32 v19, v33, v33
	v_max_f32_e32 v19, 0, v19
	v_fmac_f32_e32 v18, v89, v19
	v_not_b32_e32 v19, v18
	v_or_b32_e32 v20, 0x80000000, v18
	v_cmp_gt_i32_e32 vcc, 0, v18
	s_nop 1
	v_cndmask_b32_e32 v18, v20, v19, vcc
	v_cmp_le_u32_e32 vcc, v140, v87
	s_nop 1
	v_cndmask_b32_e32 v239, 0, v18, vcc
.LBB0_581:
	s_or_b64 exec, exec, s[82:83]
	s_movk_i32 s2, 0x5bf
	v_cmp_lt_u32_e32 vcc, s2, v177
	v_mov_b32_e32 v240, 0
	s_and_saveexec_b64 s[82:83], vcc
	s_cbranch_execz .LBB0_585
	s_movk_i32 s2, 0x5df
	s_waitcnt lgkmcnt(0)
	v_cmp_lt_u32_e32 vcc, s2, v177
	s_and_saveexec_b64 s[84:85], vcc
	s_cbranch_execz .LBB0_584
	s_nop 0
	global_load_lds_dwordx4 v72, s[100:101]
	s_add_u32 m0, m0, 0x400
	s_add_u32 s100, s100, 0x1a000
	s_addc_u32 s101, s101, 0
	s_nop 0
	global_load_lds_dwordx4 v73, s[100:101]
	s_add_u32 m0, m0, 0x400
	s_add_u32 s100, s100, 0x1a000
	s_addc_u32 s101, s101, 0
	s_nop 0
	global_load_lds_dwordx4 v72, s[100:101]
	s_add_u32 m0, m0, 0x400
	s_add_u32 s100, s100, 0x1a000
	s_addc_u32 s101, s101, 0
	s_nop 0
	global_load_lds_dwordx4 v73, s[100:101]
	s_add_u32 m0, m0, 0x400
	s_add_u32 s100, s100, 0x1a000
	s_addc_u32 s101, s101, 0
.LBB0_584:
	s_or_b64 exec, exec, s[84:85]
	v_mfma_f32_32x32x16_bf16 v[18:33], v[38:41], v[58:61], 0
	v_mfma_f32_32x32x16_bf16 v[18:33], v[46:49], v[54:57], v[18:33]
	v_mfma_f32_32x32x16_bf16 v[18:33], v[34:37], v[50:53], v[18:33]
	v_mfma_f32_32x32x16_bf16 v[18:33], v[42:45], v[62:65], v[18:33]
	s_waitcnt vmcnt(12)
	ds_read_b128 v[58:61], v74 offset:12288
	ds_read_b128 v[54:57], v75 offset:12288
	ds_read_b128 v[50:53], v76 offset:12288
	ds_read_b128 v[62:65], v77 offset:12288
	s_nop 8
	v_max_f32_e32 v18, v18, v18
	v_max_f32_e32 v19, v19, v19
	v_max_f32_e32 v18, 0, v18
	v_max_f32_e32 v20, v20, v20
	v_max_f32_e32 v19, 0, v19
	v_fma_f32 v18, v174, v18, 0
	v_max_f32_e32 v21, v21, v21
	v_max_f32_e32 v20, 0, v20
	v_fmac_f32_e32 v18, v173, v19
	v_max_f32_e32 v22, v22, v22
	v_max_f32_e32 v21, 0, v21
	v_fmac_f32_e32 v18, v172, v20
	v_max_f32_e32 v23, v23, v23
	v_max_f32_e32 v22, 0, v22
	v_fmac_f32_e32 v18, v171, v21
	v_max_f32_e32 v24, v24, v24
	v_max_f32_e32 v23, 0, v23
	v_fmac_f32_e32 v18, v170, v22
	v_max_f32_e32 v25, v25, v25
	v_max_f32_e32 v24, 0, v24
	v_fmac_f32_e32 v18, v169, v23
	v_max_f32_e32 v26, v26, v26
	v_max_f32_e32 v25, 0, v25
	v_fmac_f32_e32 v18, v168, v24
	v_max_f32_e32 v27, v27, v27
	v_max_f32_e32 v26, 0, v26
	v_fmac_f32_e32 v18, v167, v25
	v_max_f32_e32 v28, v28, v28
	v_max_f32_e32 v27, 0, v27
	v_fmac_f32_e32 v18, v166, v26
	v_max_f32_e32 v29, v29, v29
	v_max_f32_e32 v28, 0, v28
	v_fmac_f32_e32 v18, v165, v27
	v_max_f32_e32 v30, v30, v30
	v_max_f32_e32 v29, 0, v29
	v_fmac_f32_e32 v18, v164, v28
	v_max_f32_e32 v31, v31, v31
	v_max_f32_e32 v30, 0, v30
	v_fmac_f32_e32 v18, v163, v29
	v_fmac_f32_e32 v18, v162, v30
	v_max_f32_e32 v19, 0, v31
	v_fmac_f32_e32 v18, v161, v19
	v_max_f32_e32 v19, v32, v32
	v_max_f32_e32 v19, 0, v19
	v_fmac_f32_e32 v18, v160, v19
	v_max_f32_e32 v19, v33, v33
	v_max_f32_e32 v19, 0, v19
	v_fmac_f32_e32 v18, v89, v19
	v_not_b32_e32 v19, v18
	v_or_b32_e32 v20, 0x80000000, v18
	v_cmp_gt_i32_e32 vcc, 0, v18
	s_nop 1
	v_cndmask_b32_e32 v18, v20, v19, vcc
	v_cmp_le_u32_e32 vcc, v141, v87
	s_nop 1
	v_cndmask_b32_e32 v240, 0, v18, vcc
.LBB0_585:
	s_or_b64 exec, exec, s[82:83]
	s_movk_i32 s2, 0x5df
	v_cmp_lt_u32_e32 vcc, s2, v177
	v_mov_b32_e32 v241, 0
	s_and_saveexec_b64 s[82:83], vcc
	s_cbranch_execz .LBB0_589
	s_movk_i32 s2, 0x5ff
	s_waitcnt lgkmcnt(0)
	v_cmp_lt_u32_e32 vcc, s2, v177
	s_and_saveexec_b64 s[84:85], vcc
	s_cbranch_execz .LBB0_588
	s_nop 0
	global_load_lds_dwordx4 v72, s[100:101]
	s_add_u32 m0, m0, 0x400
	s_add_u32 s100, s100, 0x1a000
	s_addc_u32 s101, s101, 0
	s_nop 0
	global_load_lds_dwordx4 v73, s[100:101]
	s_add_u32 m0, m0, 0x400
	s_add_u32 s100, s100, 0x1a000
	s_addc_u32 s101, s101, 0
	s_nop 0
	global_load_lds_dwordx4 v72, s[100:101]
	s_add_u32 m0, m0, 0x400
	s_add_u32 s100, s100, 0x1a000
	s_addc_u32 s101, s101, 0
	s_nop 0
	global_load_lds_dwordx4 v73, s[100:101]
	s_sub_u32 m0, m0, 0x3c00
	s_add_u32 s100, s100, 0x1a000
	s_addc_u32 s101, s101, 0
.LBB0_588:
	s_or_b64 exec, exec, s[84:85]
	v_mfma_f32_32x32x16_bf16 v[18:33], v[38:41], v[58:61], 0
	v_mfma_f32_32x32x16_bf16 v[18:33], v[46:49], v[54:57], v[18:33]
	v_mfma_f32_32x32x16_bf16 v[18:33], v[34:37], v[50:53], v[18:33]
	v_mfma_f32_32x32x16_bf16 v[18:33], v[42:45], v[62:65], v[18:33]
	s_waitcnt vmcnt(12)
	ds_read_b128 v[58:61], v74 offset:0
	ds_read_b128 v[54:57], v75 offset:0
	ds_read_b128 v[50:53], v76 offset:0
	ds_read_b128 v[62:65], v77 offset:0
	s_nop 8
	v_max_f32_e32 v18, v18, v18
	v_max_f32_e32 v19, v19, v19
	v_max_f32_e32 v18, 0, v18
	v_max_f32_e32 v20, v20, v20
	v_max_f32_e32 v19, 0, v19
	v_fma_f32 v18, v174, v18, 0
	v_max_f32_e32 v21, v21, v21
	v_max_f32_e32 v20, 0, v20
	v_fmac_f32_e32 v18, v173, v19
	v_max_f32_e32 v22, v22, v22
	v_max_f32_e32 v21, 0, v21
	v_fmac_f32_e32 v18, v172, v20
	v_max_f32_e32 v23, v23, v23
	v_max_f32_e32 v22, 0, v22
	v_fmac_f32_e32 v18, v171, v21
	v_max_f32_e32 v24, v24, v24
	v_max_f32_e32 v23, 0, v23
	v_fmac_f32_e32 v18, v170, v22
	v_max_f32_e32 v25, v25, v25
	v_max_f32_e32 v24, 0, v24
	v_fmac_f32_e32 v18, v169, v23
	v_max_f32_e32 v26, v26, v26
	v_max_f32_e32 v25, 0, v25
	v_fmac_f32_e32 v18, v168, v24
	v_max_f32_e32 v27, v27, v27
	v_max_f32_e32 v26, 0, v26
	v_fmac_f32_e32 v18, v167, v25
	v_max_f32_e32 v28, v28, v28
	v_max_f32_e32 v27, 0, v27
	v_fmac_f32_e32 v18, v166, v26
	v_max_f32_e32 v29, v29, v29
	v_max_f32_e32 v28, 0, v28
	v_fmac_f32_e32 v18, v165, v27
	v_max_f32_e32 v30, v30, v30
	v_max_f32_e32 v29, 0, v29
	v_fmac_f32_e32 v18, v164, v28
	v_max_f32_e32 v31, v31, v31
	v_max_f32_e32 v30, 0, v30
	v_fmac_f32_e32 v18, v163, v29
	v_fmac_f32_e32 v18, v162, v30
	v_max_f32_e32 v19, 0, v31
	v_fmac_f32_e32 v18, v161, v19
	v_max_f32_e32 v19, v32, v32
	v_max_f32_e32 v19, 0, v19
	v_fmac_f32_e32 v18, v160, v19
	v_max_f32_e32 v19, v33, v33
	v_max_f32_e32 v19, 0, v19
	v_fmac_f32_e32 v18, v89, v19
	v_not_b32_e32 v19, v18
	v_or_b32_e32 v20, 0x80000000, v18
	v_cmp_gt_i32_e32 vcc, 0, v18
	s_nop 1
	v_cndmask_b32_e32 v18, v20, v19, vcc
	v_cmp_le_u32_e32 vcc, v142, v87
	s_nop 1
	v_cndmask_b32_e32 v241, 0, v18, vcc
.LBB0_589:
	s_or_b64 exec, exec, s[82:83]
	s_movk_i32 s2, 0x5ff
	v_cmp_lt_u32_e32 vcc, s2, v177
	v_mov_b32_e32 v242, 0
	s_and_saveexec_b64 s[82:83], vcc
	s_cbranch_execz .LBB0_593
	s_movk_i32 s2, 0x61f
	s_waitcnt lgkmcnt(0)
	v_cmp_lt_u32_e32 vcc, s2, v177
	s_and_saveexec_b64 s[84:85], vcc
	s_cbranch_execz .LBB0_592
	s_nop 0
	global_load_lds_dwordx4 v72, s[100:101]
	s_add_u32 m0, m0, 0x400
	s_add_u32 s100, s100, 0x1a000
	s_addc_u32 s101, s101, 0
	s_nop 0
	global_load_lds_dwordx4 v73, s[100:101]
	s_add_u32 m0, m0, 0x400
	s_add_u32 s100, s100, 0x1a000
	s_addc_u32 s101, s101, 0
	s_nop 0
	global_load_lds_dwordx4 v72, s[100:101]
	s_add_u32 m0, m0, 0x400
	s_add_u32 s100, s100, 0x1a000
	s_addc_u32 s101, s101, 0
	s_nop 0
	global_load_lds_dwordx4 v73, s[100:101]
	s_add_u32 m0, m0, 0x400
	s_add_u32 s100, s100, 0x1a000
	s_addc_u32 s101, s101, 0
.LBB0_592:
	s_or_b64 exec, exec, s[84:85]
	v_mfma_f32_32x32x16_bf16 v[18:33], v[38:41], v[58:61], 0
	v_mfma_f32_32x32x16_bf16 v[18:33], v[46:49], v[54:57], v[18:33]
	v_mfma_f32_32x32x16_bf16 v[18:33], v[34:37], v[50:53], v[18:33]
	v_mfma_f32_32x32x16_bf16 v[18:33], v[42:45], v[62:65], v[18:33]
	s_waitcnt vmcnt(12)
	ds_read_b128 v[58:61], v74 offset:4096
	ds_read_b128 v[54:57], v75 offset:4096
	ds_read_b128 v[50:53], v76 offset:4096
	ds_read_b128 v[62:65], v77 offset:4096
	s_nop 8
	v_max_f32_e32 v18, v18, v18
	v_max_f32_e32 v19, v19, v19
	v_max_f32_e32 v18, 0, v18
	v_max_f32_e32 v20, v20, v20
	v_max_f32_e32 v19, 0, v19
	v_fma_f32 v18, v174, v18, 0
	v_max_f32_e32 v21, v21, v21
	v_max_f32_e32 v20, 0, v20
	v_fmac_f32_e32 v18, v173, v19
	v_max_f32_e32 v22, v22, v22
	v_max_f32_e32 v21, 0, v21
	v_fmac_f32_e32 v18, v172, v20
	v_max_f32_e32 v23, v23, v23
	v_max_f32_e32 v22, 0, v22
	v_fmac_f32_e32 v18, v171, v21
	v_max_f32_e32 v24, v24, v24
	v_max_f32_e32 v23, 0, v23
	v_fmac_f32_e32 v18, v170, v22
	v_max_f32_e32 v25, v25, v25
	v_max_f32_e32 v24, 0, v24
	v_fmac_f32_e32 v18, v169, v23
	v_max_f32_e32 v26, v26, v26
	v_max_f32_e32 v25, 0, v25
	v_fmac_f32_e32 v18, v168, v24
	v_max_f32_e32 v27, v27, v27
	v_max_f32_e32 v26, 0, v26
	v_fmac_f32_e32 v18, v167, v25
	v_max_f32_e32 v28, v28, v28
	v_max_f32_e32 v27, 0, v27
	v_fmac_f32_e32 v18, v166, v26
	v_max_f32_e32 v29, v29, v29
	v_max_f32_e32 v28, 0, v28
	v_fmac_f32_e32 v18, v165, v27
	v_max_f32_e32 v30, v30, v30
	v_max_f32_e32 v29, 0, v29
	v_fmac_f32_e32 v18, v164, v28
	v_max_f32_e32 v31, v31, v31
	v_max_f32_e32 v30, 0, v30
	v_fmac_f32_e32 v18, v163, v29
	v_fmac_f32_e32 v18, v162, v30
	v_max_f32_e32 v19, 0, v31
	v_fmac_f32_e32 v18, v161, v19
	v_max_f32_e32 v19, v32, v32
	v_max_f32_e32 v19, 0, v19
	v_fmac_f32_e32 v18, v160, v19
	v_max_f32_e32 v19, v33, v33
	v_max_f32_e32 v19, 0, v19
	v_fmac_f32_e32 v18, v89, v19
	v_not_b32_e32 v19, v18
	v_or_b32_e32 v20, 0x80000000, v18
	v_cmp_gt_i32_e32 vcc, 0, v18
	s_nop 1
	v_cndmask_b32_e32 v18, v20, v19, vcc
	v_cmp_le_u32_e32 vcc, v143, v87
	s_nop 1
	v_cndmask_b32_e32 v242, 0, v18, vcc
.LBB0_593:
	s_or_b64 exec, exec, s[82:83]
	s_movk_i32 s2, 0x61f
	v_cmp_lt_u32_e32 vcc, s2, v177
	v_mov_b32_e32 v243, 0
	s_and_saveexec_b64 s[82:83], vcc
	s_cbranch_execz .LBB0_597
	s_movk_i32 s2, 0x63f
	s_waitcnt lgkmcnt(0)
	v_cmp_lt_u32_e32 vcc, s2, v177
	s_and_saveexec_b64 s[84:85], vcc
	s_cbranch_execz .LBB0_596
	s_nop 0
	global_load_lds_dwordx4 v72, s[100:101]
	s_add_u32 m0, m0, 0x400
	s_add_u32 s100, s100, 0x1a000
	s_addc_u32 s101, s101, 0
	s_nop 0
	global_load_lds_dwordx4 v73, s[100:101]
	s_add_u32 m0, m0, 0x400
	s_add_u32 s100, s100, 0x1a000
	s_addc_u32 s101, s101, 0
	s_nop 0
	global_load_lds_dwordx4 v72, s[100:101]
	s_add_u32 m0, m0, 0x400
	s_add_u32 s100, s100, 0x1a000
	s_addc_u32 s101, s101, 0
	s_nop 0
	global_load_lds_dwordx4 v73, s[100:101]
	s_add_u32 m0, m0, 0x400
	s_add_u32 s100, s100, 0x1a000
	s_addc_u32 s101, s101, 0
.LBB0_596:
	s_or_b64 exec, exec, s[84:85]
	v_mfma_f32_32x32x16_bf16 v[18:33], v[38:41], v[58:61], 0
	v_mfma_f32_32x32x16_bf16 v[18:33], v[46:49], v[54:57], v[18:33]
	v_mfma_f32_32x32x16_bf16 v[18:33], v[34:37], v[50:53], v[18:33]
	v_mfma_f32_32x32x16_bf16 v[18:33], v[42:45], v[62:65], v[18:33]
	s_waitcnt vmcnt(12)
	ds_read_b128 v[58:61], v74 offset:8192
	ds_read_b128 v[54:57], v75 offset:8192
	ds_read_b128 v[50:53], v76 offset:8192
	ds_read_b128 v[62:65], v77 offset:8192
	s_nop 8
	v_max_f32_e32 v18, v18, v18
	v_max_f32_e32 v19, v19, v19
	v_max_f32_e32 v18, 0, v18
	v_max_f32_e32 v20, v20, v20
	v_max_f32_e32 v19, 0, v19
	v_fma_f32 v18, v174, v18, 0
	v_max_f32_e32 v21, v21, v21
	v_max_f32_e32 v20, 0, v20
	v_fmac_f32_e32 v18, v173, v19
	v_max_f32_e32 v22, v22, v22
	v_max_f32_e32 v21, 0, v21
	v_fmac_f32_e32 v18, v172, v20
	v_max_f32_e32 v23, v23, v23
	v_max_f32_e32 v22, 0, v22
	v_fmac_f32_e32 v18, v171, v21
	v_max_f32_e32 v24, v24, v24
	v_max_f32_e32 v23, 0, v23
	v_fmac_f32_e32 v18, v170, v22
	v_max_f32_e32 v25, v25, v25
	v_max_f32_e32 v24, 0, v24
	v_fmac_f32_e32 v18, v169, v23
	v_max_f32_e32 v26, v26, v26
	v_max_f32_e32 v25, 0, v25
	v_fmac_f32_e32 v18, v168, v24
	v_max_f32_e32 v27, v27, v27
	v_max_f32_e32 v26, 0, v26
	v_fmac_f32_e32 v18, v167, v25
	v_max_f32_e32 v28, v28, v28
	v_max_f32_e32 v27, 0, v27
	v_fmac_f32_e32 v18, v166, v26
	v_max_f32_e32 v29, v29, v29
	v_max_f32_e32 v28, 0, v28
	v_fmac_f32_e32 v18, v165, v27
	v_max_f32_e32 v30, v30, v30
	v_max_f32_e32 v29, 0, v29
	v_fmac_f32_e32 v18, v164, v28
	v_max_f32_e32 v31, v31, v31
	v_max_f32_e32 v30, 0, v30
	v_fmac_f32_e32 v18, v163, v29
	v_fmac_f32_e32 v18, v162, v30
	v_max_f32_e32 v19, 0, v31
	v_fmac_f32_e32 v18, v161, v19
	v_max_f32_e32 v19, v32, v32
	v_max_f32_e32 v19, 0, v19
	v_fmac_f32_e32 v18, v160, v19
	v_max_f32_e32 v19, v33, v33
	v_max_f32_e32 v19, 0, v19
	v_fmac_f32_e32 v18, v89, v19
	v_not_b32_e32 v19, v18
	v_or_b32_e32 v20, 0x80000000, v18
	v_cmp_gt_i32_e32 vcc, 0, v18
	s_nop 1
	v_cndmask_b32_e32 v18, v20, v19, vcc
	v_cmp_le_u32_e32 vcc, v144, v87
	s_nop 1
	v_cndmask_b32_e32 v243, 0, v18, vcc
.LBB0_597:
	s_or_b64 exec, exec, s[82:83]
	s_movk_i32 s2, 0x63f
	v_cmp_lt_u32_e32 vcc, s2, v177
	v_mov_b32_e32 v244, 0
	s_and_saveexec_b64 s[82:83], vcc
	s_cbranch_execz .LBB0_601
	s_movk_i32 s2, 0x65f
	s_waitcnt lgkmcnt(0)
	v_cmp_lt_u32_e32 vcc, s2, v177
	s_and_saveexec_b64 s[84:85], vcc
	s_cbranch_execz .LBB0_600
	s_nop 0
	global_load_lds_dwordx4 v72, s[100:101]
	s_add_u32 m0, m0, 0x400
	s_add_u32 s100, s100, 0x1a000
	s_addc_u32 s101, s101, 0
	s_nop 0
	global_load_lds_dwordx4 v73, s[100:101]
	s_add_u32 m0, m0, 0x400
	s_add_u32 s100, s100, 0x1a000
	s_addc_u32 s101, s101, 0
	s_nop 0
	global_load_lds_dwordx4 v72, s[100:101]
	s_add_u32 m0, m0, 0x400
	s_add_u32 s100, s100, 0x1a000
	s_addc_u32 s101, s101, 0
	s_nop 0
	global_load_lds_dwordx4 v73, s[100:101]
	s_add_u32 m0, m0, 0x400
	s_add_u32 s100, s100, 0x1a000
	s_addc_u32 s101, s101, 0
.LBB0_600:
	s_or_b64 exec, exec, s[84:85]
	v_mfma_f32_32x32x16_bf16 v[18:33], v[38:41], v[58:61], 0
	v_mfma_f32_32x32x16_bf16 v[18:33], v[46:49], v[54:57], v[18:33]
	v_mfma_f32_32x32x16_bf16 v[18:33], v[34:37], v[50:53], v[18:33]
	v_mfma_f32_32x32x16_bf16 v[18:33], v[42:45], v[62:65], v[18:33]
	s_waitcnt vmcnt(12)
	ds_read_b128 v[58:61], v74 offset:12288
	ds_read_b128 v[54:57], v75 offset:12288
	ds_read_b128 v[50:53], v76 offset:12288
	ds_read_b128 v[62:65], v77 offset:12288
	s_nop 8
	v_max_f32_e32 v18, v18, v18
	v_max_f32_e32 v19, v19, v19
	v_max_f32_e32 v18, 0, v18
	v_max_f32_e32 v20, v20, v20
	v_max_f32_e32 v19, 0, v19
	v_fma_f32 v18, v174, v18, 0
	v_max_f32_e32 v21, v21, v21
	v_max_f32_e32 v20, 0, v20
	v_fmac_f32_e32 v18, v173, v19
	v_max_f32_e32 v22, v22, v22
	v_max_f32_e32 v21, 0, v21
	v_fmac_f32_e32 v18, v172, v20
	v_max_f32_e32 v23, v23, v23
	v_max_f32_e32 v22, 0, v22
	v_fmac_f32_e32 v18, v171, v21
	v_max_f32_e32 v24, v24, v24
	v_max_f32_e32 v23, 0, v23
	v_fmac_f32_e32 v18, v170, v22
	v_max_f32_e32 v25, v25, v25
	v_max_f32_e32 v24, 0, v24
	v_fmac_f32_e32 v18, v169, v23
	v_max_f32_e32 v26, v26, v26
	v_max_f32_e32 v25, 0, v25
	v_fmac_f32_e32 v18, v168, v24
	v_max_f32_e32 v27, v27, v27
	v_max_f32_e32 v26, 0, v26
	v_fmac_f32_e32 v18, v167, v25
	v_max_f32_e32 v28, v28, v28
	v_max_f32_e32 v27, 0, v27
	v_fmac_f32_e32 v18, v166, v26
	v_max_f32_e32 v29, v29, v29
	v_max_f32_e32 v28, 0, v28
	v_fmac_f32_e32 v18, v165, v27
	v_max_f32_e32 v30, v30, v30
	v_max_f32_e32 v29, 0, v29
	v_fmac_f32_e32 v18, v164, v28
	v_max_f32_e32 v31, v31, v31
	v_max_f32_e32 v30, 0, v30
	v_fmac_f32_e32 v18, v163, v29
	v_fmac_f32_e32 v18, v162, v30
	v_max_f32_e32 v19, 0, v31
	v_fmac_f32_e32 v18, v161, v19
	v_max_f32_e32 v19, v32, v32
	v_max_f32_e32 v19, 0, v19
	v_fmac_f32_e32 v18, v160, v19
	v_max_f32_e32 v19, v33, v33
	v_max_f32_e32 v19, 0, v19
	v_fmac_f32_e32 v18, v89, v19
	v_not_b32_e32 v19, v18
	v_or_b32_e32 v20, 0x80000000, v18
	v_cmp_gt_i32_e32 vcc, 0, v18
	s_nop 1
	v_cndmask_b32_e32 v18, v20, v19, vcc
	v_cmp_le_u32_e32 vcc, v145, v87
	s_nop 1
	v_cndmask_b32_e32 v244, 0, v18, vcc
.LBB0_601:
	s_or_b64 exec, exec, s[82:83]
	s_movk_i32 s2, 0x65f
	v_cmp_lt_u32_e32 vcc, s2, v177
	v_mov_b32_e32 v245, 0
	s_and_saveexec_b64 s[82:83], vcc
	s_cbranch_execz .LBB0_605
	s_movk_i32 s2, 0x67f
	s_waitcnt lgkmcnt(0)
	v_cmp_lt_u32_e32 vcc, s2, v177
	s_and_saveexec_b64 s[84:85], vcc
	s_cbranch_execz .LBB0_604
	s_nop 0
	global_load_lds_dwordx4 v72, s[100:101]
	s_add_u32 m0, m0, 0x400
	s_add_u32 s100, s100, 0x1a000
	s_addc_u32 s101, s101, 0
	s_nop 0
	global_load_lds_dwordx4 v73, s[100:101]
	s_add_u32 m0, m0, 0x400
	s_add_u32 s100, s100, 0x1a000
	s_addc_u32 s101, s101, 0
	s_nop 0
	global_load_lds_dwordx4 v72, s[100:101]
	s_add_u32 m0, m0, 0x400
	s_add_u32 s100, s100, 0x1a000
	s_addc_u32 s101, s101, 0
	s_nop 0
	global_load_lds_dwordx4 v73, s[100:101]
	s_sub_u32 m0, m0, 0x3c00
	s_add_u32 s100, s100, 0x1a000
	s_addc_u32 s101, s101, 0
.LBB0_604:
	s_or_b64 exec, exec, s[84:85]
	v_mfma_f32_32x32x16_bf16 v[18:33], v[38:41], v[58:61], 0
	v_mfma_f32_32x32x16_bf16 v[18:33], v[46:49], v[54:57], v[18:33]
	v_mfma_f32_32x32x16_bf16 v[18:33], v[34:37], v[50:53], v[18:33]
	v_mfma_f32_32x32x16_bf16 v[18:33], v[42:45], v[62:65], v[18:33]
	s_waitcnt vmcnt(12)
	ds_read_b128 v[58:61], v74 offset:0
	ds_read_b128 v[54:57], v75 offset:0
	ds_read_b128 v[50:53], v76 offset:0
	ds_read_b128 v[62:65], v77 offset:0
	s_nop 8
	v_max_f32_e32 v18, v18, v18
	v_max_f32_e32 v19, v19, v19
	v_max_f32_e32 v18, 0, v18
	v_max_f32_e32 v20, v20, v20
	v_max_f32_e32 v19, 0, v19
	v_fma_f32 v18, v174, v18, 0
	v_max_f32_e32 v21, v21, v21
	v_max_f32_e32 v20, 0, v20
	v_fmac_f32_e32 v18, v173, v19
	v_max_f32_e32 v22, v22, v22
	v_max_f32_e32 v21, 0, v21
	v_fmac_f32_e32 v18, v172, v20
	v_max_f32_e32 v23, v23, v23
	v_max_f32_e32 v22, 0, v22
	v_fmac_f32_e32 v18, v171, v21
	v_max_f32_e32 v24, v24, v24
	v_max_f32_e32 v23, 0, v23
	v_fmac_f32_e32 v18, v170, v22
	v_max_f32_e32 v25, v25, v25
	v_max_f32_e32 v24, 0, v24
	v_fmac_f32_e32 v18, v169, v23
	v_max_f32_e32 v26, v26, v26
	v_max_f32_e32 v25, 0, v25
	v_fmac_f32_e32 v18, v168, v24
	v_max_f32_e32 v27, v27, v27
	v_max_f32_e32 v26, 0, v26
	v_fmac_f32_e32 v18, v167, v25
	v_max_f32_e32 v28, v28, v28
	v_max_f32_e32 v27, 0, v27
	v_fmac_f32_e32 v18, v166, v26
	v_max_f32_e32 v29, v29, v29
	v_max_f32_e32 v28, 0, v28
	v_fmac_f32_e32 v18, v165, v27
	v_max_f32_e32 v30, v30, v30
	v_max_f32_e32 v29, 0, v29
	v_fmac_f32_e32 v18, v164, v28
	v_max_f32_e32 v31, v31, v31
	v_max_f32_e32 v30, 0, v30
	v_fmac_f32_e32 v18, v163, v29
	v_fmac_f32_e32 v18, v162, v30
	v_max_f32_e32 v19, 0, v31
	v_fmac_f32_e32 v18, v161, v19
	v_max_f32_e32 v19, v32, v32
	v_max_f32_e32 v19, 0, v19
	v_fmac_f32_e32 v18, v160, v19
	v_max_f32_e32 v19, v33, v33
	v_max_f32_e32 v19, 0, v19
	v_fmac_f32_e32 v18, v89, v19
	v_not_b32_e32 v19, v18
	v_or_b32_e32 v20, 0x80000000, v18
	v_cmp_gt_i32_e32 vcc, 0, v18
	s_nop 1
	v_cndmask_b32_e32 v18, v20, v19, vcc
	v_cmp_le_u32_e32 vcc, v146, v87
	s_nop 1
	v_cndmask_b32_e32 v245, 0, v18, vcc
.LBB0_605:
	s_or_b64 exec, exec, s[82:83]
	s_movk_i32 s2, 0x67f
	v_cmp_lt_u32_e32 vcc, s2, v177
	v_mov_b32_e32 v246, 0
	s_and_saveexec_b64 s[82:83], vcc
	s_cbranch_execz .LBB0_609
	s_movk_i32 s2, 0x69f
	s_waitcnt lgkmcnt(0)
	v_cmp_lt_u32_e32 vcc, s2, v177
	s_and_saveexec_b64 s[84:85], vcc
	s_cbranch_execz .LBB0_608
	s_nop 0
	global_load_lds_dwordx4 v72, s[100:101]
	s_add_u32 m0, m0, 0x400
	s_add_u32 s100, s100, 0x1a000
	s_addc_u32 s101, s101, 0
	s_nop 0
	global_load_lds_dwordx4 v73, s[100:101]
	s_add_u32 m0, m0, 0x400
	s_add_u32 s100, s100, 0x1a000
	s_addc_u32 s101, s101, 0
	s_nop 0
	global_load_lds_dwordx4 v72, s[100:101]
	s_add_u32 m0, m0, 0x400
	s_add_u32 s100, s100, 0x1a000
	s_addc_u32 s101, s101, 0
	s_nop 0
	global_load_lds_dwordx4 v73, s[100:101]
	s_add_u32 m0, m0, 0x400
	s_add_u32 s100, s100, 0x1a000
	s_addc_u32 s101, s101, 0
.LBB0_608:
	s_or_b64 exec, exec, s[84:85]
	v_mfma_f32_32x32x16_bf16 v[18:33], v[38:41], v[58:61], 0
	v_mfma_f32_32x32x16_bf16 v[18:33], v[46:49], v[54:57], v[18:33]
	v_mfma_f32_32x32x16_bf16 v[18:33], v[34:37], v[50:53], v[18:33]
	v_mfma_f32_32x32x16_bf16 v[18:33], v[42:45], v[62:65], v[18:33]
	s_waitcnt vmcnt(12)
	ds_read_b128 v[58:61], v74 offset:4096
	ds_read_b128 v[54:57], v75 offset:4096
	ds_read_b128 v[50:53], v76 offset:4096
	ds_read_b128 v[62:65], v77 offset:4096
	s_nop 8
	v_max_f32_e32 v18, v18, v18
	v_max_f32_e32 v19, v19, v19
	v_max_f32_e32 v18, 0, v18
	v_max_f32_e32 v20, v20, v20
	v_max_f32_e32 v19, 0, v19
	v_fma_f32 v18, v174, v18, 0
	v_max_f32_e32 v21, v21, v21
	v_max_f32_e32 v20, 0, v20
	v_fmac_f32_e32 v18, v173, v19
	v_max_f32_e32 v22, v22, v22
	v_max_f32_e32 v21, 0, v21
	v_fmac_f32_e32 v18, v172, v20
	v_max_f32_e32 v23, v23, v23
	v_max_f32_e32 v22, 0, v22
	v_fmac_f32_e32 v18, v171, v21
	v_max_f32_e32 v24, v24, v24
	v_max_f32_e32 v23, 0, v23
	v_fmac_f32_e32 v18, v170, v22
	v_max_f32_e32 v25, v25, v25
	v_max_f32_e32 v24, 0, v24
	v_fmac_f32_e32 v18, v169, v23
	v_max_f32_e32 v26, v26, v26
	v_max_f32_e32 v25, 0, v25
	v_fmac_f32_e32 v18, v168, v24
	v_max_f32_e32 v27, v27, v27
	v_max_f32_e32 v26, 0, v26
	v_fmac_f32_e32 v18, v167, v25
	v_max_f32_e32 v28, v28, v28
	v_max_f32_e32 v27, 0, v27
	v_fmac_f32_e32 v18, v166, v26
	v_max_f32_e32 v29, v29, v29
	v_max_f32_e32 v28, 0, v28
	v_fmac_f32_e32 v18, v165, v27
	v_max_f32_e32 v30, v30, v30
	v_max_f32_e32 v29, 0, v29
	v_fmac_f32_e32 v18, v164, v28
	v_max_f32_e32 v31, v31, v31
	v_max_f32_e32 v30, 0, v30
	v_fmac_f32_e32 v18, v163, v29
	v_fmac_f32_e32 v18, v162, v30
	v_max_f32_e32 v19, 0, v31
	v_fmac_f32_e32 v18, v161, v19
	v_max_f32_e32 v19, v32, v32
	v_max_f32_e32 v19, 0, v19
	v_fmac_f32_e32 v18, v160, v19
	v_max_f32_e32 v19, v33, v33
	v_max_f32_e32 v19, 0, v19
	v_fmac_f32_e32 v18, v89, v19
	v_not_b32_e32 v19, v18
	v_or_b32_e32 v20, 0x80000000, v18
	v_cmp_gt_i32_e32 vcc, 0, v18
	s_nop 1
	v_cndmask_b32_e32 v18, v20, v19, vcc
	v_cmp_le_u32_e32 vcc, v147, v87
	s_nop 1
	v_cndmask_b32_e32 v246, 0, v18, vcc
.LBB0_609:
	s_or_b64 exec, exec, s[82:83]
	s_movk_i32 s2, 0x69f
	v_cmp_lt_u32_e32 vcc, s2, v177
	v_mov_b32_e32 v247, 0
	s_and_saveexec_b64 s[82:83], vcc
	s_cbranch_execz .LBB0_613
	s_movk_i32 s2, 0x6bf
	s_waitcnt lgkmcnt(0)
	v_cmp_lt_u32_e32 vcc, s2, v177
	s_and_saveexec_b64 s[84:85], vcc
	s_cbranch_execz .LBB0_612
	s_nop 0
	global_load_lds_dwordx4 v72, s[100:101]
	s_add_u32 m0, m0, 0x400
	s_add_u32 s100, s100, 0x1a000
	s_addc_u32 s101, s101, 0
	s_nop 0
	global_load_lds_dwordx4 v73, s[100:101]
	s_add_u32 m0, m0, 0x400
	s_add_u32 s100, s100, 0x1a000
	s_addc_u32 s101, s101, 0
	s_nop 0
	global_load_lds_dwordx4 v72, s[100:101]
	s_add_u32 m0, m0, 0x400
	s_add_u32 s100, s100, 0x1a000
	s_addc_u32 s101, s101, 0
	s_nop 0
	global_load_lds_dwordx4 v73, s[100:101]
	s_add_u32 m0, m0, 0x400
	s_add_u32 s100, s100, 0x1a000
	s_addc_u32 s101, s101, 0
.LBB0_612:
	s_or_b64 exec, exec, s[84:85]
	v_mfma_f32_32x32x16_bf16 v[18:33], v[38:41], v[58:61], 0
	v_mfma_f32_32x32x16_bf16 v[18:33], v[46:49], v[54:57], v[18:33]
	v_mfma_f32_32x32x16_bf16 v[18:33], v[34:37], v[50:53], v[18:33]
	v_mfma_f32_32x32x16_bf16 v[18:33], v[42:45], v[62:65], v[18:33]
	s_waitcnt vmcnt(12)
	ds_read_b128 v[58:61], v74 offset:8192
	ds_read_b128 v[54:57], v75 offset:8192
	ds_read_b128 v[50:53], v76 offset:8192
	ds_read_b128 v[62:65], v77 offset:8192
	s_nop 8
	v_max_f32_e32 v18, v18, v18
	v_max_f32_e32 v19, v19, v19
	v_max_f32_e32 v18, 0, v18
	v_max_f32_e32 v20, v20, v20
	v_max_f32_e32 v19, 0, v19
	v_fma_f32 v18, v174, v18, 0
	v_max_f32_e32 v21, v21, v21
	v_max_f32_e32 v20, 0, v20
	v_fmac_f32_e32 v18, v173, v19
	v_max_f32_e32 v22, v22, v22
	v_max_f32_e32 v21, 0, v21
	v_fmac_f32_e32 v18, v172, v20
	v_max_f32_e32 v23, v23, v23
	v_max_f32_e32 v22, 0, v22
	v_fmac_f32_e32 v18, v171, v21
	v_max_f32_e32 v24, v24, v24
	v_max_f32_e32 v23, 0, v23
	v_fmac_f32_e32 v18, v170, v22
	v_max_f32_e32 v25, v25, v25
	v_max_f32_e32 v24, 0, v24
	v_fmac_f32_e32 v18, v169, v23
	v_max_f32_e32 v26, v26, v26
	v_max_f32_e32 v25, 0, v25
	v_fmac_f32_e32 v18, v168, v24
	v_max_f32_e32 v27, v27, v27
	v_max_f32_e32 v26, 0, v26
	v_fmac_f32_e32 v18, v167, v25
	v_max_f32_e32 v28, v28, v28
	v_max_f32_e32 v27, 0, v27
	v_fmac_f32_e32 v18, v166, v26
	v_max_f32_e32 v29, v29, v29
	v_max_f32_e32 v28, 0, v28
	v_fmac_f32_e32 v18, v165, v27
	v_max_f32_e32 v30, v30, v30
	v_max_f32_e32 v29, 0, v29
	v_fmac_f32_e32 v18, v164, v28
	v_max_f32_e32 v31, v31, v31
	v_max_f32_e32 v30, 0, v30
	v_fmac_f32_e32 v18, v163, v29
	v_fmac_f32_e32 v18, v162, v30
	v_max_f32_e32 v19, 0, v31
	v_fmac_f32_e32 v18, v161, v19
	v_max_f32_e32 v19, v32, v32
	v_max_f32_e32 v19, 0, v19
	v_fmac_f32_e32 v18, v160, v19
	v_max_f32_e32 v19, v33, v33
	v_max_f32_e32 v19, 0, v19
	v_fmac_f32_e32 v18, v89, v19
	v_not_b32_e32 v19, v18
	v_or_b32_e32 v20, 0x80000000, v18
	v_cmp_gt_i32_e32 vcc, 0, v18
	s_nop 1
	v_cndmask_b32_e32 v18, v20, v19, vcc
	v_cmp_le_u32_e32 vcc, v148, v87
	s_nop 1
	v_cndmask_b32_e32 v247, 0, v18, vcc
.LBB0_613:
	s_or_b64 exec, exec, s[82:83]
	s_movk_i32 s2, 0x6bf
	v_cmp_lt_u32_e32 vcc, s2, v177
	v_mov_b32_e32 v248, 0
	s_and_saveexec_b64 s[82:83], vcc
	s_cbranch_execz .LBB0_617
	s_movk_i32 s2, 0x6df
	s_waitcnt lgkmcnt(0)
	v_cmp_lt_u32_e32 vcc, s2, v177
	s_and_saveexec_b64 s[84:85], vcc
	s_cbranch_execz .LBB0_616
	s_nop 0
	global_load_lds_dwordx4 v72, s[100:101]
	s_add_u32 m0, m0, 0x400
	s_add_u32 s100, s100, 0x1a000
	s_addc_u32 s101, s101, 0
	s_nop 0
	global_load_lds_dwordx4 v73, s[100:101]
	s_add_u32 m0, m0, 0x400
	s_add_u32 s100, s100, 0x1a000
	s_addc_u32 s101, s101, 0
	s_nop 0
	global_load_lds_dwordx4 v72, s[100:101]
	s_add_u32 m0, m0, 0x400
	s_add_u32 s100, s100, 0x1a000
	s_addc_u32 s101, s101, 0
	s_nop 0
	global_load_lds_dwordx4 v73, s[100:101]
	s_add_u32 m0, m0, 0x400
	s_add_u32 s100, s100, 0x1a000
	s_addc_u32 s101, s101, 0
.LBB0_616:
	s_or_b64 exec, exec, s[84:85]
	v_mfma_f32_32x32x16_bf16 v[18:33], v[38:41], v[58:61], 0
	v_mfma_f32_32x32x16_bf16 v[18:33], v[46:49], v[54:57], v[18:33]
	v_mfma_f32_32x32x16_bf16 v[18:33], v[34:37], v[50:53], v[18:33]
	v_mfma_f32_32x32x16_bf16 v[18:33], v[42:45], v[62:65], v[18:33]
	s_waitcnt vmcnt(12)
	ds_read_b128 v[58:61], v74 offset:12288
	ds_read_b128 v[54:57], v75 offset:12288
	ds_read_b128 v[50:53], v76 offset:12288
	ds_read_b128 v[62:65], v77 offset:12288
	s_nop 8
	v_max_f32_e32 v18, v18, v18
	v_max_f32_e32 v19, v19, v19
	v_max_f32_e32 v18, 0, v18
	v_max_f32_e32 v20, v20, v20
	v_max_f32_e32 v19, 0, v19
	v_fma_f32 v18, v174, v18, 0
	v_max_f32_e32 v21, v21, v21
	v_max_f32_e32 v20, 0, v20
	v_fmac_f32_e32 v18, v173, v19
	v_max_f32_e32 v22, v22, v22
	v_max_f32_e32 v21, 0, v21
	v_fmac_f32_e32 v18, v172, v20
	v_max_f32_e32 v23, v23, v23
	v_max_f32_e32 v22, 0, v22
	v_fmac_f32_e32 v18, v171, v21
	v_max_f32_e32 v24, v24, v24
	v_max_f32_e32 v23, 0, v23
	v_fmac_f32_e32 v18, v170, v22
	v_max_f32_e32 v25, v25, v25
	v_max_f32_e32 v24, 0, v24
	v_fmac_f32_e32 v18, v169, v23
	v_max_f32_e32 v26, v26, v26
	v_max_f32_e32 v25, 0, v25
	v_fmac_f32_e32 v18, v168, v24
	v_max_f32_e32 v27, v27, v27
	v_max_f32_e32 v26, 0, v26
	v_fmac_f32_e32 v18, v167, v25
	v_max_f32_e32 v28, v28, v28
	v_max_f32_e32 v27, 0, v27
	v_fmac_f32_e32 v18, v166, v26
	v_max_f32_e32 v29, v29, v29
	v_max_f32_e32 v28, 0, v28
	v_fmac_f32_e32 v18, v165, v27
	v_max_f32_e32 v30, v30, v30
	v_max_f32_e32 v29, 0, v29
	v_fmac_f32_e32 v18, v164, v28
	v_max_f32_e32 v31, v31, v31
	v_max_f32_e32 v30, 0, v30
	v_fmac_f32_e32 v18, v163, v29
	v_fmac_f32_e32 v18, v162, v30
	v_max_f32_e32 v19, 0, v31
	v_fmac_f32_e32 v18, v161, v19
	v_max_f32_e32 v19, v32, v32
	v_max_f32_e32 v19, 0, v19
	v_fmac_f32_e32 v18, v160, v19
	v_max_f32_e32 v19, v33, v33
	v_max_f32_e32 v19, 0, v19
	v_fmac_f32_e32 v18, v89, v19
	v_not_b32_e32 v19, v18
	v_or_b32_e32 v20, 0x80000000, v18
	v_cmp_gt_i32_e32 vcc, 0, v18
	s_nop 1
	v_cndmask_b32_e32 v18, v20, v19, vcc
	v_cmp_le_u32_e32 vcc, v149, v87
	s_nop 1
	v_cndmask_b32_e32 v248, 0, v18, vcc
.LBB0_617:
	s_or_b64 exec, exec, s[82:83]
	s_movk_i32 s2, 0x6df
	v_cmp_lt_u32_e32 vcc, s2, v177
	v_mov_b32_e32 v249, 0
	s_and_saveexec_b64 s[82:83], vcc
	s_cbranch_execz .LBB0_621
	s_movk_i32 s2, 0x6ff
	s_waitcnt lgkmcnt(0)
	v_cmp_lt_u32_e32 vcc, s2, v177
	s_and_saveexec_b64 s[84:85], vcc
	s_cbranch_execz .LBB0_620
	s_nop 0
	global_load_lds_dwordx4 v72, s[100:101]
	s_add_u32 m0, m0, 0x400
	s_add_u32 s100, s100, 0x1a000
	s_addc_u32 s101, s101, 0
	s_nop 0
	global_load_lds_dwordx4 v73, s[100:101]
	s_add_u32 m0, m0, 0x400
	s_add_u32 s100, s100, 0x1a000
	s_addc_u32 s101, s101, 0
	s_nop 0
	global_load_lds_dwordx4 v72, s[100:101]
	s_add_u32 m0, m0, 0x400
	s_add_u32 s100, s100, 0x1a000
	s_addc_u32 s101, s101, 0
	s_nop 0
	global_load_lds_dwordx4 v73, s[100:101]
	s_sub_u32 m0, m0, 0x3c00
	s_add_u32 s100, s100, 0x1a000
	s_addc_u32 s101, s101, 0
.LBB0_620:
	s_or_b64 exec, exec, s[84:85]
	v_mfma_f32_32x32x16_bf16 v[18:33], v[38:41], v[58:61], 0
	v_mfma_f32_32x32x16_bf16 v[18:33], v[46:49], v[54:57], v[18:33]
	v_mfma_f32_32x32x16_bf16 v[18:33], v[34:37], v[50:53], v[18:33]
	v_mfma_f32_32x32x16_bf16 v[18:33], v[42:45], v[62:65], v[18:33]
	s_waitcnt vmcnt(12)
	ds_read_b128 v[58:61], v74 offset:0
	ds_read_b128 v[54:57], v75 offset:0
	ds_read_b128 v[50:53], v76 offset:0
	ds_read_b128 v[62:65], v77 offset:0
	s_nop 8
	v_max_f32_e32 v18, v18, v18
	v_max_f32_e32 v19, v19, v19
	v_max_f32_e32 v18, 0, v18
	v_max_f32_e32 v20, v20, v20
	v_max_f32_e32 v19, 0, v19
	v_fma_f32 v18, v174, v18, 0
	v_max_f32_e32 v21, v21, v21
	v_max_f32_e32 v20, 0, v20
	v_fmac_f32_e32 v18, v173, v19
	v_max_f32_e32 v22, v22, v22
	v_max_f32_e32 v21, 0, v21
	v_fmac_f32_e32 v18, v172, v20
	v_max_f32_e32 v23, v23, v23
	v_max_f32_e32 v22, 0, v22
	v_fmac_f32_e32 v18, v171, v21
	v_max_f32_e32 v24, v24, v24
	v_max_f32_e32 v23, 0, v23
	v_fmac_f32_e32 v18, v170, v22
	v_max_f32_e32 v25, v25, v25
	v_max_f32_e32 v24, 0, v24
	v_fmac_f32_e32 v18, v169, v23
	v_max_f32_e32 v26, v26, v26
	v_max_f32_e32 v25, 0, v25
	v_fmac_f32_e32 v18, v168, v24
	v_max_f32_e32 v27, v27, v27
	v_max_f32_e32 v26, 0, v26
	v_fmac_f32_e32 v18, v167, v25
	v_max_f32_e32 v28, v28, v28
	v_max_f32_e32 v27, 0, v27
	v_fmac_f32_e32 v18, v166, v26
	v_max_f32_e32 v29, v29, v29
	v_max_f32_e32 v28, 0, v28
	v_fmac_f32_e32 v18, v165, v27
	v_max_f32_e32 v30, v30, v30
	v_max_f32_e32 v29, 0, v29
	v_fmac_f32_e32 v18, v164, v28
	v_max_f32_e32 v31, v31, v31
	v_max_f32_e32 v30, 0, v30
	v_fmac_f32_e32 v18, v163, v29
	v_fmac_f32_e32 v18, v162, v30
	v_max_f32_e32 v19, 0, v31
	v_fmac_f32_e32 v18, v161, v19
	v_max_f32_e32 v19, v32, v32
	v_max_f32_e32 v19, 0, v19
	v_fmac_f32_e32 v18, v160, v19
	v_max_f32_e32 v19, v33, v33
	v_max_f32_e32 v19, 0, v19
	v_fmac_f32_e32 v18, v89, v19
	v_not_b32_e32 v19, v18
	v_or_b32_e32 v20, 0x80000000, v18
	v_cmp_gt_i32_e32 vcc, 0, v18
	s_nop 1
	v_cndmask_b32_e32 v18, v20, v19, vcc
	v_cmp_le_u32_e32 vcc, v150, v87
	s_nop 1
	v_cndmask_b32_e32 v249, 0, v18, vcc
.LBB0_621:
	s_or_b64 exec, exec, s[82:83]
	s_movk_i32 s2, 0x6ff
	v_cmp_lt_u32_e32 vcc, s2, v177
	v_mov_b32_e32 v250, 0
	s_and_saveexec_b64 s[82:83], vcc
	s_cbranch_execz .LBB0_625
	s_movk_i32 s2, 0x71f
	s_waitcnt lgkmcnt(0)
	v_cmp_lt_u32_e32 vcc, s2, v177
	s_and_saveexec_b64 s[84:85], vcc
	s_cbranch_execz .LBB0_624
	s_nop 0
	global_load_lds_dwordx4 v72, s[100:101]
	s_add_u32 m0, m0, 0x400
	s_add_u32 s100, s100, 0x1a000
	s_addc_u32 s101, s101, 0
	s_nop 0
	global_load_lds_dwordx4 v73, s[100:101]
	s_add_u32 m0, m0, 0x400
	s_add_u32 s100, s100, 0x1a000
	s_addc_u32 s101, s101, 0
	s_nop 0
	global_load_lds_dwordx4 v72, s[100:101]
	s_add_u32 m0, m0, 0x400
	s_add_u32 s100, s100, 0x1a000
	s_addc_u32 s101, s101, 0
	s_nop 0
	global_load_lds_dwordx4 v73, s[100:101]
	s_add_u32 m0, m0, 0x400
	s_add_u32 s100, s100, 0x1a000
	s_addc_u32 s101, s101, 0
.LBB0_624:
	s_or_b64 exec, exec, s[84:85]
	v_mfma_f32_32x32x16_bf16 v[18:33], v[38:41], v[58:61], 0
	v_mfma_f32_32x32x16_bf16 v[18:33], v[46:49], v[54:57], v[18:33]
	v_mfma_f32_32x32x16_bf16 v[18:33], v[34:37], v[50:53], v[18:33]
	v_mfma_f32_32x32x16_bf16 v[18:33], v[42:45], v[62:65], v[18:33]
	s_waitcnt vmcnt(12)
	ds_read_b128 v[58:61], v74 offset:4096
	ds_read_b128 v[54:57], v75 offset:4096
	ds_read_b128 v[50:53], v76 offset:4096
	ds_read_b128 v[62:65], v77 offset:4096
	s_nop 8
	v_max_f32_e32 v18, v18, v18
	v_max_f32_e32 v19, v19, v19
	v_max_f32_e32 v18, 0, v18
	v_max_f32_e32 v20, v20, v20
	v_max_f32_e32 v19, 0, v19
	v_fma_f32 v18, v174, v18, 0
	v_max_f32_e32 v21, v21, v21
	v_max_f32_e32 v20, 0, v20
	v_fmac_f32_e32 v18, v173, v19
	v_max_f32_e32 v22, v22, v22
	v_max_f32_e32 v21, 0, v21
	v_fmac_f32_e32 v18, v172, v20
	v_max_f32_e32 v23, v23, v23
	v_max_f32_e32 v22, 0, v22
	v_fmac_f32_e32 v18, v171, v21
	v_max_f32_e32 v24, v24, v24
	v_max_f32_e32 v23, 0, v23
	v_fmac_f32_e32 v18, v170, v22
	v_max_f32_e32 v25, v25, v25
	v_max_f32_e32 v24, 0, v24
	v_fmac_f32_e32 v18, v169, v23
	v_max_f32_e32 v26, v26, v26
	v_max_f32_e32 v25, 0, v25
	v_fmac_f32_e32 v18, v168, v24
	v_max_f32_e32 v27, v27, v27
	v_max_f32_e32 v26, 0, v26
	v_fmac_f32_e32 v18, v167, v25
	v_max_f32_e32 v28, v28, v28
	v_max_f32_e32 v27, 0, v27
	v_fmac_f32_e32 v18, v166, v26
	v_max_f32_e32 v29, v29, v29
	v_max_f32_e32 v28, 0, v28
	v_fmac_f32_e32 v18, v165, v27
	v_max_f32_e32 v30, v30, v30
	v_max_f32_e32 v29, 0, v29
	v_fmac_f32_e32 v18, v164, v28
	v_max_f32_e32 v31, v31, v31
	v_max_f32_e32 v30, 0, v30
	v_fmac_f32_e32 v18, v163, v29
	v_fmac_f32_e32 v18, v162, v30
	v_max_f32_e32 v19, 0, v31
	v_fmac_f32_e32 v18, v161, v19
	v_max_f32_e32 v19, v32, v32
	v_max_f32_e32 v19, 0, v19
	v_fmac_f32_e32 v18, v160, v19
	v_max_f32_e32 v19, v33, v33
	v_max_f32_e32 v19, 0, v19
	v_fmac_f32_e32 v18, v89, v19
	v_not_b32_e32 v19, v18
	v_or_b32_e32 v20, 0x80000000, v18
	v_cmp_gt_i32_e32 vcc, 0, v18
	s_nop 1
	v_cndmask_b32_e32 v18, v20, v19, vcc
	v_cmp_le_u32_e32 vcc, v151, v87
	s_nop 1
	v_cndmask_b32_e32 v250, 0, v18, vcc
.LBB0_625:
	s_or_b64 exec, exec, s[82:83]
	s_movk_i32 s2, 0x71f
	v_cmp_lt_u32_e32 vcc, s2, v177
	v_mov_b32_e32 v199, 0
	s_and_saveexec_b64 s[82:83], vcc
	s_cbranch_execz .LBB0_629
	s_movk_i32 s2, 0x73f
	s_waitcnt lgkmcnt(0)
	v_cmp_lt_u32_e32 vcc, s2, v177
	s_and_saveexec_b64 s[84:85], vcc
	s_cbranch_execz .LBB0_628
	s_nop 0
	global_load_lds_dwordx4 v72, s[100:101]
	s_add_u32 m0, m0, 0x400
	s_add_u32 s100, s100, 0x1a000
	s_addc_u32 s101, s101, 0
	s_nop 0
	global_load_lds_dwordx4 v73, s[100:101]
	s_add_u32 m0, m0, 0x400
	s_add_u32 s100, s100, 0x1a000
	s_addc_u32 s101, s101, 0
	s_nop 0
	global_load_lds_dwordx4 v72, s[100:101]
	s_add_u32 m0, m0, 0x400
	s_add_u32 s100, s100, 0x1a000
	s_addc_u32 s101, s101, 0
	s_nop 0
	global_load_lds_dwordx4 v73, s[100:101]
	s_add_u32 m0, m0, 0x400
	s_add_u32 s100, s100, 0x1a000
	s_addc_u32 s101, s101, 0
.LBB0_628:
	s_or_b64 exec, exec, s[84:85]
	v_mfma_f32_32x32x16_bf16 v[18:33], v[38:41], v[58:61], 0
	v_mfma_f32_32x32x16_bf16 v[18:33], v[46:49], v[54:57], v[18:33]
	v_mfma_f32_32x32x16_bf16 v[18:33], v[34:37], v[50:53], v[18:33]
	v_mfma_f32_32x32x16_bf16 v[18:33], v[42:45], v[62:65], v[18:33]
	s_waitcnt vmcnt(12)
	ds_read_b128 v[58:61], v74 offset:8192
	ds_read_b128 v[54:57], v75 offset:8192
	ds_read_b128 v[50:53], v76 offset:8192
	ds_read_b128 v[62:65], v77 offset:8192
	s_nop 8
	v_max_f32_e32 v18, v18, v18
	v_max_f32_e32 v19, v19, v19
	v_max_f32_e32 v18, 0, v18
	v_max_f32_e32 v20, v20, v20
	v_max_f32_e32 v19, 0, v19
	v_fma_f32 v18, v174, v18, 0
	v_max_f32_e32 v21, v21, v21
	v_max_f32_e32 v20, 0, v20
	v_fmac_f32_e32 v18, v173, v19
	v_max_f32_e32 v22, v22, v22
	v_max_f32_e32 v21, 0, v21
	v_fmac_f32_e32 v18, v172, v20
	v_max_f32_e32 v23, v23, v23
	v_max_f32_e32 v22, 0, v22
	v_fmac_f32_e32 v18, v171, v21
	v_max_f32_e32 v24, v24, v24
	v_max_f32_e32 v23, 0, v23
	v_fmac_f32_e32 v18, v170, v22
	v_max_f32_e32 v25, v25, v25
	v_max_f32_e32 v24, 0, v24
	v_fmac_f32_e32 v18, v169, v23
	v_max_f32_e32 v26, v26, v26
	v_max_f32_e32 v25, 0, v25
	v_fmac_f32_e32 v18, v168, v24
	v_max_f32_e32 v27, v27, v27
	v_max_f32_e32 v26, 0, v26
	v_fmac_f32_e32 v18, v167, v25
	v_max_f32_e32 v28, v28, v28
	v_max_f32_e32 v27, 0, v27
	v_fmac_f32_e32 v18, v166, v26
	v_max_f32_e32 v29, v29, v29
	v_max_f32_e32 v28, 0, v28
	v_fmac_f32_e32 v18, v165, v27
	v_max_f32_e32 v30, v30, v30
	v_max_f32_e32 v29, 0, v29
	v_fmac_f32_e32 v18, v164, v28
	v_max_f32_e32 v31, v31, v31
	v_max_f32_e32 v30, 0, v30
	v_fmac_f32_e32 v18, v163, v29
	v_fmac_f32_e32 v18, v162, v30
	v_max_f32_e32 v19, 0, v31
	v_fmac_f32_e32 v18, v161, v19
	v_max_f32_e32 v19, v32, v32
	v_max_f32_e32 v19, 0, v19
	v_fmac_f32_e32 v18, v160, v19
	v_max_f32_e32 v19, v33, v33
	v_max_f32_e32 v19, 0, v19
	v_fmac_f32_e32 v18, v89, v19
	v_not_b32_e32 v19, v18
	v_or_b32_e32 v20, 0x80000000, v18
	v_cmp_gt_i32_e32 vcc, 0, v18
	s_nop 1
	v_cndmask_b32_e32 v18, v20, v19, vcc
	v_cmp_le_u32_e32 vcc, v152, v87
	s_nop 1
	v_cndmask_b32_e32 v199, 0, v18, vcc
.LBB0_629:
	s_or_b64 exec, exec, s[82:83]
	s_movk_i32 s2, 0x73f
	v_cmp_lt_u32_e32 vcc, s2, v177
	v_mov_b32_e32 v200, 0
	s_and_saveexec_b64 s[82:83], vcc
	s_cbranch_execz .LBB0_633
	s_movk_i32 s2, 0x75f
	s_waitcnt lgkmcnt(0)
	v_cmp_lt_u32_e32 vcc, s2, v177
	s_and_saveexec_b64 s[84:85], vcc
	s_cbranch_execz .LBB0_632
	s_nop 0
	global_load_lds_dwordx4 v72, s[100:101]
	s_add_u32 m0, m0, 0x400
	s_add_u32 s100, s100, 0x1a000
	s_addc_u32 s101, s101, 0
	s_nop 0
	global_load_lds_dwordx4 v73, s[100:101]
	s_add_u32 m0, m0, 0x400
	s_add_u32 s100, s100, 0x1a000
	s_addc_u32 s101, s101, 0
	s_nop 0
	global_load_lds_dwordx4 v72, s[100:101]
	s_add_u32 m0, m0, 0x400
	s_add_u32 s100, s100, 0x1a000
	s_addc_u32 s101, s101, 0
	s_nop 0
	global_load_lds_dwordx4 v73, s[100:101]
	s_add_u32 m0, m0, 0x400
	s_add_u32 s100, s100, 0x1a000
	s_addc_u32 s101, s101, 0
.LBB0_632:
	s_or_b64 exec, exec, s[84:85]
	v_mfma_f32_32x32x16_bf16 v[18:33], v[38:41], v[58:61], 0
	v_mfma_f32_32x32x16_bf16 v[18:33], v[46:49], v[54:57], v[18:33]
	v_mfma_f32_32x32x16_bf16 v[18:33], v[34:37], v[50:53], v[18:33]
	v_mfma_f32_32x32x16_bf16 v[18:33], v[42:45], v[62:65], v[18:33]
	s_waitcnt vmcnt(12)
	ds_read_b128 v[58:61], v74 offset:12288
	ds_read_b128 v[54:57], v75 offset:12288
	ds_read_b128 v[50:53], v76 offset:12288
	ds_read_b128 v[62:65], v77 offset:12288
	s_nop 8
	v_max_f32_e32 v18, v18, v18
	v_max_f32_e32 v19, v19, v19
	v_max_f32_e32 v18, 0, v18
	v_max_f32_e32 v20, v20, v20
	v_max_f32_e32 v19, 0, v19
	v_fma_f32 v18, v174, v18, 0
	v_max_f32_e32 v21, v21, v21
	v_max_f32_e32 v20, 0, v20
	v_fmac_f32_e32 v18, v173, v19
	v_max_f32_e32 v22, v22, v22
	v_max_f32_e32 v21, 0, v21
	v_fmac_f32_e32 v18, v172, v20
	v_max_f32_e32 v23, v23, v23
	v_max_f32_e32 v22, 0, v22
	v_fmac_f32_e32 v18, v171, v21
	v_max_f32_e32 v24, v24, v24
	v_max_f32_e32 v23, 0, v23
	v_fmac_f32_e32 v18, v170, v22
	v_max_f32_e32 v25, v25, v25
	v_max_f32_e32 v24, 0, v24
	v_fmac_f32_e32 v18, v169, v23
	v_max_f32_e32 v26, v26, v26
	v_max_f32_e32 v25, 0, v25
	v_fmac_f32_e32 v18, v168, v24
	v_max_f32_e32 v27, v27, v27
	v_max_f32_e32 v26, 0, v26
	v_fmac_f32_e32 v18, v167, v25
	v_max_f32_e32 v28, v28, v28
	v_max_f32_e32 v27, 0, v27
	v_fmac_f32_e32 v18, v166, v26
	v_max_f32_e32 v29, v29, v29
	v_max_f32_e32 v28, 0, v28
	v_fmac_f32_e32 v18, v165, v27
	v_max_f32_e32 v30, v30, v30
	v_max_f32_e32 v29, 0, v29
	v_fmac_f32_e32 v18, v164, v28
	v_max_f32_e32 v31, v31, v31
	v_max_f32_e32 v30, 0, v30
	v_fmac_f32_e32 v18, v163, v29
	v_fmac_f32_e32 v18, v162, v30
	v_max_f32_e32 v19, 0, v31
	v_fmac_f32_e32 v18, v161, v19
	v_max_f32_e32 v19, v32, v32
	v_max_f32_e32 v19, 0, v19
	v_fmac_f32_e32 v18, v160, v19
	v_max_f32_e32 v19, v33, v33
	v_max_f32_e32 v19, 0, v19
	v_fmac_f32_e32 v18, v89, v19
	v_not_b32_e32 v19, v18
	v_or_b32_e32 v20, 0x80000000, v18
	v_cmp_gt_i32_e32 vcc, 0, v18
	s_nop 1
	v_cndmask_b32_e32 v18, v20, v19, vcc
	v_cmp_le_u32_e32 vcc, v153, v87
	s_nop 1
	v_cndmask_b32_e32 v200, 0, v18, vcc
.LBB0_633:
	s_or_b64 exec, exec, s[82:83]
	s_movk_i32 s2, 0x75f
	v_cmp_lt_u32_e32 vcc, s2, v177
	v_mov_b32_e32 v207, 0
	s_and_saveexec_b64 s[82:83], vcc
	s_cbranch_execz .LBB0_637
	s_movk_i32 s2, 0x77f
	s_waitcnt lgkmcnt(0)
	v_cmp_lt_u32_e32 vcc, s2, v177
	s_and_saveexec_b64 s[84:85], vcc
	s_cbranch_execz .LBB0_636
	s_nop 0
	global_load_lds_dwordx4 v72, s[100:101]
	s_add_u32 m0, m0, 0x400
	s_add_u32 s100, s100, 0x1a000
	s_addc_u32 s101, s101, 0
	s_nop 0
	global_load_lds_dwordx4 v73, s[100:101]
	s_add_u32 m0, m0, 0x400
	s_add_u32 s100, s100, 0x1a000
	s_addc_u32 s101, s101, 0
	s_nop 0
	global_load_lds_dwordx4 v72, s[100:101]
	s_add_u32 m0, m0, 0x400
	s_add_u32 s100, s100, 0x1a000
	s_addc_u32 s101, s101, 0
	s_nop 0
	global_load_lds_dwordx4 v73, s[100:101]
	s_sub_u32 m0, m0, 0x3c00
	s_add_u32 s100, s100, 0x1a000
	s_addc_u32 s101, s101, 0
.LBB0_636:
	s_or_b64 exec, exec, s[84:85]
	v_mfma_f32_32x32x16_bf16 v[18:33], v[38:41], v[58:61], 0
	v_mfma_f32_32x32x16_bf16 v[18:33], v[46:49], v[54:57], v[18:33]
	v_mfma_f32_32x32x16_bf16 v[18:33], v[34:37], v[50:53], v[18:33]
	v_mfma_f32_32x32x16_bf16 v[18:33], v[42:45], v[62:65], v[18:33]
	s_waitcnt vmcnt(12)
	ds_read_b128 v[58:61], v74 offset:0
	ds_read_b128 v[54:57], v75 offset:0
	ds_read_b128 v[50:53], v76 offset:0
	ds_read_b128 v[62:65], v77 offset:0
	s_nop 8
	v_max_f32_e32 v18, v18, v18
	v_max_f32_e32 v19, v19, v19
	v_max_f32_e32 v18, 0, v18
	v_max_f32_e32 v20, v20, v20
	v_max_f32_e32 v19, 0, v19
	v_fma_f32 v18, v174, v18, 0
	v_max_f32_e32 v21, v21, v21
	v_max_f32_e32 v20, 0, v20
	v_fmac_f32_e32 v18, v173, v19
	v_max_f32_e32 v22, v22, v22
	v_max_f32_e32 v21, 0, v21
	v_fmac_f32_e32 v18, v172, v20
	v_max_f32_e32 v23, v23, v23
	v_max_f32_e32 v22, 0, v22
	v_fmac_f32_e32 v18, v171, v21
	v_max_f32_e32 v24, v24, v24
	v_max_f32_e32 v23, 0, v23
	v_fmac_f32_e32 v18, v170, v22
	v_max_f32_e32 v25, v25, v25
	v_max_f32_e32 v24, 0, v24
	v_fmac_f32_e32 v18, v169, v23
	v_max_f32_e32 v26, v26, v26
	v_max_f32_e32 v25, 0, v25
	v_fmac_f32_e32 v18, v168, v24
	v_max_f32_e32 v27, v27, v27
	v_max_f32_e32 v26, 0, v26
	v_fmac_f32_e32 v18, v167, v25
	v_max_f32_e32 v28, v28, v28
	v_max_f32_e32 v27, 0, v27
	v_fmac_f32_e32 v18, v166, v26
	v_max_f32_e32 v29, v29, v29
	v_max_f32_e32 v28, 0, v28
	v_fmac_f32_e32 v18, v165, v27
	v_max_f32_e32 v30, v30, v30
	v_max_f32_e32 v29, 0, v29
	v_fmac_f32_e32 v18, v164, v28
	v_max_f32_e32 v31, v31, v31
	v_max_f32_e32 v30, 0, v30
	v_fmac_f32_e32 v18, v163, v29
	v_fmac_f32_e32 v18, v162, v30
	v_max_f32_e32 v19, 0, v31
	v_fmac_f32_e32 v18, v161, v19
	v_max_f32_e32 v19, v32, v32
	v_max_f32_e32 v19, 0, v19
	v_fmac_f32_e32 v18, v160, v19
	v_max_f32_e32 v19, v33, v33
	v_max_f32_e32 v19, 0, v19
	v_fmac_f32_e32 v18, v89, v19
	v_not_b32_e32 v19, v18
	v_or_b32_e32 v20, 0x80000000, v18
	v_cmp_gt_i32_e32 vcc, 0, v18
	s_nop 1
	v_cndmask_b32_e32 v18, v20, v19, vcc
	v_cmp_le_u32_e32 vcc, v154, v87
	s_nop 1
	v_cndmask_b32_e32 v207, 0, v18, vcc
.LBB0_637:
	s_or_b64 exec, exec, s[82:83]
	s_movk_i32 s2, 0x77f
	v_cmp_lt_u32_e32 vcc, s2, v177
	v_mov_b32_e32 v208, 0
	s_and_saveexec_b64 s[82:83], vcc
	s_cbranch_execz .LBB0_641
	s_movk_i32 s2, 0x79f
	s_waitcnt lgkmcnt(0)
	v_cmp_lt_u32_e32 vcc, s2, v177
	s_and_saveexec_b64 s[84:85], vcc
	s_cbranch_execz .LBB0_640
.LBB0_640:
	s_or_b64 exec, exec, s[84:85]
	v_mfma_f32_32x32x16_bf16 v[18:33], v[38:41], v[58:61], 0
	v_mfma_f32_32x32x16_bf16 v[18:33], v[46:49], v[54:57], v[18:33]
	v_mfma_f32_32x32x16_bf16 v[18:33], v[34:37], v[50:53], v[18:33]
	v_mfma_f32_32x32x16_bf16 v[18:33], v[42:45], v[62:65], v[18:33]
	s_waitcnt vmcnt(8)
	ds_read_b128 v[58:61], v74 offset:4096
	ds_read_b128 v[54:57], v75 offset:4096
	ds_read_b128 v[50:53], v76 offset:4096
	ds_read_b128 v[62:65], v77 offset:4096
	s_nop 8
	v_max_f32_e32 v18, v18, v18
	v_max_f32_e32 v19, v19, v19
	v_max_f32_e32 v18, 0, v18
	v_max_f32_e32 v20, v20, v20
	v_max_f32_e32 v19, 0, v19
	v_fma_f32 v18, v174, v18, 0
	v_max_f32_e32 v21, v21, v21
	v_max_f32_e32 v20, 0, v20
	v_fmac_f32_e32 v18, v173, v19
	v_max_f32_e32 v22, v22, v22
	v_max_f32_e32 v21, 0, v21
	v_fmac_f32_e32 v18, v172, v20
	v_max_f32_e32 v23, v23, v23
	v_max_f32_e32 v22, 0, v22
	v_fmac_f32_e32 v18, v171, v21
	v_max_f32_e32 v24, v24, v24
	v_max_f32_e32 v23, 0, v23
	v_fmac_f32_e32 v18, v170, v22
	v_max_f32_e32 v25, v25, v25
	v_max_f32_e32 v24, 0, v24
	v_fmac_f32_e32 v18, v169, v23
	v_max_f32_e32 v26, v26, v26
	v_max_f32_e32 v25, 0, v25
	v_fmac_f32_e32 v18, v168, v24
	v_max_f32_e32 v27, v27, v27
	v_max_f32_e32 v26, 0, v26
	v_fmac_f32_e32 v18, v167, v25
	v_max_f32_e32 v28, v28, v28
	v_max_f32_e32 v27, 0, v27
	v_fmac_f32_e32 v18, v166, v26
	v_max_f32_e32 v29, v29, v29
	v_max_f32_e32 v28, 0, v28
	v_fmac_f32_e32 v18, v165, v27
	v_max_f32_e32 v30, v30, v30
	v_max_f32_e32 v29, 0, v29
	v_fmac_f32_e32 v18, v164, v28
	v_max_f32_e32 v31, v31, v31
	v_max_f32_e32 v30, 0, v30
	v_fmac_f32_e32 v18, v163, v29
	v_fmac_f32_e32 v18, v162, v30
	v_max_f32_e32 v19, 0, v31
	v_fmac_f32_e32 v18, v161, v19
	v_max_f32_e32 v19, v32, v32
	v_max_f32_e32 v19, 0, v19
	v_fmac_f32_e32 v18, v160, v19
	v_max_f32_e32 v19, v33, v33
	v_max_f32_e32 v19, 0, v19
	v_fmac_f32_e32 v18, v89, v19
	v_not_b32_e32 v19, v18
	v_or_b32_e32 v20, 0x80000000, v18
	v_cmp_gt_i32_e32 vcc, 0, v18
	s_nop 1
	v_cndmask_b32_e32 v18, v20, v19, vcc
	v_cmp_le_u32_e32 vcc, v155, v87
	s_nop 1
	v_cndmask_b32_e32 v208, 0, v18, vcc
.LBB0_641:
	s_or_b64 exec, exec, s[82:83]
	s_movk_i32 s2, 0x79f
	v_cmp_lt_u32_e32 vcc, s2, v177
	v_mov_b32_e32 v210, 0
	s_and_saveexec_b64 s[82:83], vcc
	s_cbranch_execz .LBB0_645
	s_movk_i32 s2, 0x7bf
	s_waitcnt lgkmcnt(0)
	v_cmp_lt_u32_e32 vcc, s2, v177
	s_and_saveexec_b64 s[84:85], vcc
	s_cbranch_execz .LBB0_644
.LBB0_644:
	s_or_b64 exec, exec, s[84:85]
	v_mfma_f32_32x32x16_bf16 v[18:33], v[38:41], v[58:61], 0
	v_mfma_f32_32x32x16_bf16 v[18:33], v[46:49], v[54:57], v[18:33]
	v_mfma_f32_32x32x16_bf16 v[18:33], v[34:37], v[50:53], v[18:33]
	v_mfma_f32_32x32x16_bf16 v[18:33], v[42:45], v[62:65], v[18:33]
	s_waitcnt vmcnt(4)
	ds_read_b128 v[58:61], v74 offset:8192
	ds_read_b128 v[54:57], v75 offset:8192
	ds_read_b128 v[50:53], v76 offset:8192
	ds_read_b128 v[62:65], v77 offset:8192
	s_nop 8
	v_max_f32_e32 v18, v18, v18
	v_max_f32_e32 v19, v19, v19
	v_max_f32_e32 v18, 0, v18
	v_max_f32_e32 v20, v20, v20
	v_max_f32_e32 v19, 0, v19
	v_fma_f32 v18, v174, v18, 0
	v_max_f32_e32 v21, v21, v21
	v_max_f32_e32 v20, 0, v20
	v_fmac_f32_e32 v18, v173, v19
	v_max_f32_e32 v22, v22, v22
	v_max_f32_e32 v21, 0, v21
	v_fmac_f32_e32 v18, v172, v20
	v_max_f32_e32 v23, v23, v23
	v_max_f32_e32 v22, 0, v22
	v_fmac_f32_e32 v18, v171, v21
	v_max_f32_e32 v24, v24, v24
	v_max_f32_e32 v23, 0, v23
	v_fmac_f32_e32 v18, v170, v22
	v_max_f32_e32 v25, v25, v25
	v_max_f32_e32 v24, 0, v24
	v_fmac_f32_e32 v18, v169, v23
	v_max_f32_e32 v26, v26, v26
	v_max_f32_e32 v25, 0, v25
	v_fmac_f32_e32 v18, v168, v24
	v_max_f32_e32 v27, v27, v27
	v_max_f32_e32 v26, 0, v26
	v_fmac_f32_e32 v18, v167, v25
	v_max_f32_e32 v28, v28, v28
	v_max_f32_e32 v27, 0, v27
	v_fmac_f32_e32 v18, v166, v26
	v_max_f32_e32 v29, v29, v29
	v_max_f32_e32 v28, 0, v28
	v_fmac_f32_e32 v18, v165, v27
	v_max_f32_e32 v30, v30, v30
	v_max_f32_e32 v29, 0, v29
	v_fmac_f32_e32 v18, v164, v28
	v_max_f32_e32 v31, v31, v31
	v_max_f32_e32 v30, 0, v30
	v_fmac_f32_e32 v18, v163, v29
	v_fmac_f32_e32 v18, v162, v30
	v_max_f32_e32 v19, 0, v31
	v_fmac_f32_e32 v18, v161, v19
	v_max_f32_e32 v19, v32, v32
	v_max_f32_e32 v19, 0, v19
	v_fmac_f32_e32 v18, v160, v19
	v_max_f32_e32 v19, v33, v33
	v_max_f32_e32 v19, 0, v19
	v_fmac_f32_e32 v18, v89, v19
	v_not_b32_e32 v19, v18
	v_or_b32_e32 v20, 0x80000000, v18
	v_cmp_gt_i32_e32 vcc, 0, v18
	s_nop 1
	v_cndmask_b32_e32 v18, v20, v19, vcc
	v_cmp_le_u32_e32 vcc, v156, v87
	s_nop 1
	v_cndmask_b32_e32 v210, 0, v18, vcc
.LBB0_645:
	s_or_b64 exec, exec, s[82:83]
	s_movk_i32 s2, 0x7bf
	v_lshrrev_b32_e32 v201, 5, v177
	v_cmp_lt_u32_e32 vcc, s2, v177
	v_mov_b32_e32 v70, 0
	s_and_saveexec_b64 s[82:83], vcc
	s_cbranch_execz .LBB0_649
	s_waitcnt lgkmcnt(0)
	v_cmp_eq_u32_e32 vcc, 63, v201
	s_and_saveexec_b64 s[84:85], vcc
	s_cbranch_execz .LBB0_648
.LBB0_648:
	s_or_b64 exec, exec, s[84:85]
	v_mfma_f32_32x32x16_bf16 v[18:33], v[38:41], v[58:61], 0
	v_mfma_f32_32x32x16_bf16 v[18:33], v[46:49], v[54:57], v[18:33]
	v_mfma_f32_32x32x16_bf16 v[18:33], v[34:37], v[50:53], v[18:33]
	v_mfma_f32_32x32x16_bf16 v[18:33], v[42:45], v[62:65], v[18:33]
	s_waitcnt vmcnt(0)
	ds_read_b128 v[58:61], v74 offset:12288
	ds_read_b128 v[54:57], v75 offset:12288
	ds_read_b128 v[50:53], v76 offset:12288
	ds_read_b128 v[62:65], v77 offset:12288
	s_nop 8
	v_max_f32_e32 v18, v18, v18
	v_max_f32_e32 v19, v19, v19
	v_max_f32_e32 v18, 0, v18
	v_max_f32_e32 v20, v20, v20
	v_max_f32_e32 v19, 0, v19
	v_fma_f32 v18, v174, v18, 0
	v_max_f32_e32 v21, v21, v21
	v_max_f32_e32 v20, 0, v20
	v_fmac_f32_e32 v18, v173, v19
	v_max_f32_e32 v22, v22, v22
	v_max_f32_e32 v21, 0, v21
	v_fmac_f32_e32 v18, v172, v20
	v_max_f32_e32 v23, v23, v23
	v_max_f32_e32 v22, 0, v22
	v_fmac_f32_e32 v18, v171, v21
	v_max_f32_e32 v24, v24, v24
	v_max_f32_e32 v23, 0, v23
	v_fmac_f32_e32 v18, v170, v22
	v_max_f32_e32 v25, v25, v25
	v_max_f32_e32 v24, 0, v24
	v_fmac_f32_e32 v18, v169, v23
	v_max_f32_e32 v26, v26, v26
	v_max_f32_e32 v25, 0, v25
	v_fmac_f32_e32 v18, v168, v24
	v_max_f32_e32 v27, v27, v27
	v_max_f32_e32 v26, 0, v26
	v_fmac_f32_e32 v18, v167, v25
	v_max_f32_e32 v28, v28, v28
	v_max_f32_e32 v27, 0, v27
	v_fmac_f32_e32 v18, v166, v26
	v_max_f32_e32 v29, v29, v29
	v_max_f32_e32 v28, 0, v28
	v_fmac_f32_e32 v18, v165, v27
	v_max_f32_e32 v30, v30, v30
	v_max_f32_e32 v29, 0, v29
	v_fmac_f32_e32 v18, v164, v28
	v_max_f32_e32 v31, v31, v31
	v_max_f32_e32 v30, 0, v30
	v_fmac_f32_e32 v18, v163, v29
	v_fmac_f32_e32 v18, v162, v30
	v_max_f32_e32 v19, 0, v31
	v_fmac_f32_e32 v18, v161, v19
	v_max_f32_e32 v19, v32, v32
	v_max_f32_e32 v19, 0, v19
	v_fmac_f32_e32 v18, v160, v19
	v_max_f32_e32 v19, v33, v33
	v_max_f32_e32 v19, 0, v19
	v_fmac_f32_e32 v18, v89, v19
	v_not_b32_e32 v19, v18
	v_or_b32_e32 v20, 0x80000000, v18
	v_cmp_gt_i32_e32 vcc, 0, v18
	s_nop 1
	v_cndmask_b32_e32 v18, v20, v19, vcc
	v_cmp_le_u32_e32 vcc, v157, v87
	s_nop 1
	v_cndmask_b32_e32 v70, 0, v18, vcc
.LBB0_649:
	s_or_b64 exec, exec, s[82:83]
	v_cmp_eq_u32_e32 vcc, 63, v201
	v_mov_b32_e32 v66, 0
	v_mov_b32_e32 v18, 0
	s_and_saveexec_b64 s[82:83], vcc
	s_cbranch_execz .LBB0_651
	s_waitcnt lgkmcnt(0)
	v_mfma_f32_32x32x16_bf16 v[18:33], v[38:41], v[58:61], 0
	v_mfma_f32_32x32x16_bf16 v[18:33], v[46:49], v[54:57], v[18:33]
	v_mfma_f32_32x32x16_bf16 v[18:33], v[34:37], v[50:53], v[18:33]
	v_mfma_f32_32x32x16_bf16 v[18:33], v[42:45], v[62:65], v[18:33]
	s_nop 11
	v_max_f32_e32 v18, v18, v18
	v_max_f32_e32 v19, v19, v19
	v_max_f32_e32 v18, 0, v18
	v_max_f32_e32 v20, v20, v20
	v_max_f32_e32 v19, 0, v19
	v_fma_f32 v18, v174, v18, 0
	v_max_f32_e32 v21, v21, v21
	v_max_f32_e32 v20, 0, v20
	v_fmac_f32_e32 v18, v173, v19
	v_max_f32_e32 v22, v22, v22
	v_max_f32_e32 v21, 0, v21
	v_fmac_f32_e32 v18, v172, v20
	v_max_f32_e32 v23, v23, v23
	v_max_f32_e32 v22, 0, v22
	v_fmac_f32_e32 v18, v171, v21
	v_max_f32_e32 v24, v24, v24
	v_max_f32_e32 v23, 0, v23
	v_fmac_f32_e32 v18, v170, v22
	v_max_f32_e32 v25, v25, v25
	v_max_f32_e32 v24, 0, v24
	v_fmac_f32_e32 v18, v169, v23
	v_max_f32_e32 v26, v26, v26
	v_max_f32_e32 v25, 0, v25
	v_fmac_f32_e32 v18, v168, v24
	v_max_f32_e32 v27, v27, v27
	v_max_f32_e32 v26, 0, v26
	v_fmac_f32_e32 v18, v167, v25
	v_max_f32_e32 v28, v28, v28
	v_max_f32_e32 v27, 0, v27
	v_fmac_f32_e32 v18, v166, v26
	v_max_f32_e32 v29, v29, v29
	v_max_f32_e32 v28, 0, v28
	v_fmac_f32_e32 v18, v165, v27
	v_max_f32_e32 v30, v30, v30
	v_max_f32_e32 v29, 0, v29
	v_fmac_f32_e32 v18, v164, v28
	v_max_f32_e32 v31, v31, v31
	v_max_f32_e32 v30, 0, v30
	v_fmac_f32_e32 v18, v163, v29
	v_max_f32_e32 v32, v32, v32
	v_max_f32_e32 v31, 0, v31
	v_fmac_f32_e32 v18, v162, v30
	v_max_f32_e32 v32, 0, v32
	v_fmac_f32_e32 v18, v161, v31
	v_max_f32_e32 v19, v33, v33
	v_fmac_f32_e32 v18, v160, v32
	v_max_f32_e32 v19, 0, v19
	v_fmac_f32_e32 v18, v89, v19
	v_not_b32_e32 v19, v18
	v_or_b32_e32 v20, 0x80000000, v18
	v_cmp_gt_i32_e32 vcc, 0, v18
	s_nop 1
	v_cndmask_b32_e32 v18, v20, v19, vcc
	v_cmp_le_u32_e32 vcc, v158, v87
	s_nop 1
	v_cndmask_b32_e32 v18, 0, v18, vcc
